# own phase 0: adaLN GEMV with 32 loads in flight per wave (baseline had 1), wave-level streaming weight converter (pipelined, no block barriers) for both layers; MFMA tail priority
# speedup vs baseline: 1.0828x; 1.0175x over previous
.LBB0_21:
	v_readlane_b32 s6, v244, 1
	v_readlane_b32 s7, v244, 2
	s_cmp_lt_u32 s70, 11
	v_readlane_b32 s0, v244, 3
	s_mov_b32 s71, s6
	s_cselect_b64 s[6:7], -1, 0
	s_add_i32 s20, s70, -9
	v_readlane_b32 s1, v244, 4
	v_readlane_b32 s3, v244, 0
	s_cmp_gt_u32 s70, 10
	s_cselect_b64 s[22:23], -1, 0
	s_waitcnt lgkmcnt(0)
	s_load_dwordx2 s[24:25], s[0:1], 0xb8
	s_and_b64 s[18:19], s[22:23], exec
	s_cselect_b32 s18, s20, s70
	s_cmp_lt_u32 s70, 2
	s_cselect_b32 s19, s70, s18
	s_cmp_eq_u32 s19, 0
	s_cbranch_scc1 .Lp0_entry
	s_cmp_eq_u32 s19, 9
	s_cbranch_scc1 .Lgy_entry
	s_cmp_eq_u32 s19, 8
	s_cbranch_scc1 .Lup_entry
	s_cmp_eq_u32 s19, 2
	s_cbranch_scc1 .Lpj_entry
	s_cmp_lt_i32 s19, 5
	s_cbranch_scc1 .LBB0_46
	s_and_b64 s[20:21], s[22:23], exec
	s_cselect_b32 s18, 0x18000, 0
	s_waitcnt lgkmcnt(0)
	s_add_u32 s66, s24, s18
	s_addc_u32 s80, s25, 0
	s_cmp_gt_i32 s19, 7
	s_cbranch_scc0 .LBB0_47
	s_cmp_gt_i32 s19, 8
	s_cbranch_scc0 .LBB0_48
	s_cmp_gt_i32 s19, 9
	s_cbranch_scc0 .LBB0_64
	s_mov_b64 s[20:21], 0
	s_mov_b64 s[24:25], 0
	s_cmp_eq_u32 s19, 10
	v_writelane_b32 v244, s20, 56
	s_nop 1
	v_writelane_b32 v244, s21, 57
	s_cbranch_scc0 .LBB0_65
	s_load_dwordx2 s[30:31], s[0:1], 0x68
	s_and_b64 vcc, exec, s[6:7]
	s_cbranch_vccz .LBB0_334
	s_lshl_b32 s18, s71, 2
	s_abs_i32 s6, s18
	v_cvt_f32_u32_e32 v0, s6
	s_waitcnt vmcnt(0)
	v_mov_b32_e32 v34, v154
	v_mov_b32_e32 v2, v154
	s_sub_i32 s26, 0, s6
	v_rcp_iflag_f32_e32 v0, v0
	s_nop 0
	v_mul_f32_e32 v0, 0x4f7ffffe, v0
	v_cvt_u32_f32_e32 v0, v0
	v_readfirstlane_b32 s7, v2
	s_ashr_i32 s20, s7, 6
	s_add_i32 s7, s18, 0x3fff
	v_readfirstlane_b32 s27, v0
	s_mul_i32 s26, s26, s27
	s_mul_hi_u32 s26, s27, s26
	s_xor_b32 s21, s7, s18
	s_abs_i32 s7, s7
	s_add_i32 s27, s27, s26
	s_mul_hi_u32 s26, s7, s27
	s_mul_i32 s27, s26, s6
	s_sub_i32 s7, s7, s27
	s_ashr_i32 s21, s21, 31
	s_add_i32 s27, s26, 1
	s_sub_i32 s28, s7, s6
	s_cmp_ge_u32 s7, s6
	s_cselect_b32 s26, s27, s26
	s_cselect_b32 s7, s28, s7
	s_add_i32 s27, s26, 1
	s_cmp_ge_u32 s7, s6
	s_cselect_b32 s6, s27, s26
	s_xor_b32 s6, s6, s21
	s_lshl_b32 s52, s3, 2
	s_sub_i32 s7, s6, s21
	s_add_i32 s6, s20, s52
	s_mul_i32 s6, s6, s7
	s_cmpk_gt_i32 s6, 0x3fff
	s_cbranch_scc1 .LBB0_335
	s_load_dwordx2 s[26:27], s[0:1], 0x110
	s_ashr_i32 s20, s6, 12
	s_mulk_i32 s20, 0x1800
	v_lshlrev_b32_e32 v0, 2, v34
	v_and_b32_e32 v35, 0xfc, v0
	s_waitcnt lgkmcnt(0)
	s_cmp_lg_u64 s[26:27], 0
	s_cselect_b64 s[40:41], -1, 0
	s_ashr_i32 s21, s20, 31
	s_lshl_b64 s[34:35], s[20:21], 2
	s_add_u32 s20, s66, s34
	s_addc_u32 s21, s80, s35
	s_add_u32 s36, s20, 0x5000
	s_addc_u32 s37, s21, 0
	s_and_b64 vcc, exec, s[40:41]
	v_lshlrev_b32_e32 v0, 2, v35
	s_cbranch_vccz .LBB0_30
	v_lshl_add_u64 v[10:11], s[36:37], 0, v[0:1]
	v_add_co_u32_e32 v6, vcc, 0x30000, v10
	global_load_dwordx4 v[2:5], v0, s[36:37]
	s_nop 0
	v_addc_co_u32_e32 v7, vcc, 0, v11, vcc
	global_load_dwordx4 v[6:9], v[6:7], off
	s_waitcnt vmcnt(0)
	v_pk_add_f32 v[6:7], v[2:3], v[6:7]
	v_add_co_u32_e32 v2, vcc, 0x60000, v10
	v_pk_add_f32 v[8:9], v[4:5], v[8:9]
	s_nop 0
	v_addc_co_u32_e32 v3, vcc, 0, v11, vcc
	global_load_dwordx4 v[2:5], v[2:3], off
	s_waitcnt vmcnt(0)
	v_pk_add_f32 v[6:7], v[6:7], v[2:3]
	v_add_co_u32_e32 v2, vcc, 0x90000, v10
	v_pk_add_f32 v[8:9], v[8:9], v[4:5]
	s_nop 0
	v_addc_co_u32_e32 v3, vcc, 0, v11, vcc
	global_load_dwordx4 v[2:5], v[2:3], off
	s_waitcnt vmcnt(0)
	v_pk_add_f32 v[68:69], v[8:9], v[4:5]
	v_pk_add_f32 v[66:67], v[6:7], v[2:3]
	global_load_dwordx4 v[2:5], v0, s[30:31]

.LBB0_335:
	s_mov_b64 s[20:21], 0
	s_waitcnt vmcnt(0)
	v_mov_b32_e32 v20, v154
	s_mov_b64 s[6:7], 0
	s_cmpk_gt_u32 s3, 0xcff
	v_writelane_b32 v244, s20, 56
	s_nop 1
	v_writelane_b32 v244, s21, 57
	s_cbranch_scc1 .LBB0_520
	s_branch .Lcv_p10
	s_add_u32 s34, s0, 0x98
	s_addc_u32 s35, s1, 0
	s_cmpk_gt_u32 s3, 0x3bf
	s_cbranch_scc0 .LBB0_342
	s_add_u32 s34, s0, 0xa0
	s_addc_u32 s35, s1, 0
	s_cmpk_gt_u32 s3, 0x4bf
	s_cbranch_scc0 .LBB0_486
	s_add_u32 s34, s0, 0xa8
	s_addc_u32 s35, s1, 0
	s_cmpk_gt_u32 s3, 0xa3f
	s_cbranch_scc0 .LBB0_547
	s_add_i32 s26, s3, 0xf5c0
	s_and_b32 s27, s26, 0xffff
	s_load_dwordx2 s[20:21], s[0:1], 0x88
	s_mul_i32 s27, s27, 0xba2f
	s_lshr_b32 s27, s27, 21
	s_mul_i32 s28, s27, 44
	s_sub_i32 s26, s26, s28
	s_waitcnt lgkmcnt(0)
	s_add_u32 s36, s20, 0xb00000
	s_addc_u32 s37, s21, 0
	s_add_u32 s34, s0, 0xb0
	s_addc_u32 s35, s1, 0
	s_lshl_b32 s20, s26, 6
	s_lshl_b32 s27, s27, 6
	s_and_b32 s20, s20, 0xffc0
	s_or_b32 s28, s27, 32
	s_cbranch_execz .LBB0_548
	s_movk_i32 s26, 0x400
	s_movk_i32 s72, 0xb00
	s_mov_b32 s21, s27
	s_cbranch_execz .LBB0_487
	s_branch .LBB0_488

.Lp0_entry:
	s_waitcnt lgkmcnt(0)
	s_cmpk_lt_u32 s3, 0xc0
	s_cbranch_scc1 .Lmd_entry
	s_branch .Lcv_p0a
.Lmd_entry:
	s_load_dwordx2 s[38:39], s[0:1], 0x8
	s_load_dwordx2 s[40:41], s[0:1], 0x10
	s_load_dwordx2 s[54:55], s[0:1], 0x18
	s_load_dwordx2 s[56:57], s[0:1], 0xb8
	v_and_b32_e32 v130, 63, v154
	v_lshrrev_b32_e32 v168, 6, v154
	v_lshlrev_b32_e32 v131, 4, v130
	v_readfirstlane_b32 s51, v168
	s_cmpk_lt_u32 s3, 96
	s_cselect_b32 s26, 0, 1
	s_mul_i32 s37, s26, 96
	s_sub_i32 s37, s3, s37
	s_and_b32 s28, s37, 3
	s_lshr_b32 s27, s37, 2
	s_lshl_b32 s27, s27, 8
	s_lshl_b32 s37, s28, 8
	s_lshl_b32 s43, s51, 6
	s_add_i32 s37, s37, s43
	s_waitcnt lgkmcnt(0)
	v_lshl_add_u32 v168, v130, 2, 0
	s_lshl_b32 s43, s37, 2
	v_add_u32_e32 v168, s43, v168
	v_add_u32_e32 v136, 0x0, v168
	v_add_u32_e32 v137, 0x1000, v168
	v_add_u32_e32 v138, 0x2000, v168
	v_add_u32_e32 v139, 0x3000, v168
	global_load_dword v132, v136, s[38:39]
	global_load_dword v133, v137, s[38:39]
	global_load_dword v134, v138, s[38:39]
	global_load_dword v135, v139, s[38:39]
	s_lshl_b32 s43, s26, 10
	s_add_i32 s43, s43, s37
	s_mul_i32 s37, s43, 0x6000
	s_mul_hi_u32 s43, s43, 0x6000
	s_add_u32 s58, s40, s37
	s_addc_u32 s59, s41, s43
	s_lshl_b32 s37, s27, 2
	s_add_u32 s58, s58, s37
	s_addc_u32 s59, s59, 0
	v_mov_b32_e32 v136, 0
	v_mov_b32_e32 v137, 0
	v_mov_b32_e32 v138, 0
	v_mov_b32_e32 v139, 0
	v_mov_b32_e32 v140, 0
	v_mov_b32_e32 v141, 0
	v_mov_b32_e32 v142, 0
	v_mov_b32_e32 v143, 0
	v_mov_b32_e32 v144, 0
	v_mov_b32_e32 v145, 0
	v_mov_b32_e32 v146, 0
	v_mov_b32_e32 v147, 0
	v_mov_b32_e32 v148, 0
	v_mov_b32_e32 v149, 0
	v_mov_b32_e32 v150, 0
	v_mov_b32_e32 v151, 0
	global_load_dwordx4 v[2:5], v131, s[58:59] nt
	s_add_u32 s58, s58, 0x6000
	s_addc_u32 s59, s59, 0
	global_load_dwordx4 v[6:9], v131, s[58:59] nt
	s_add_u32 s58, s58, 0x6000
	s_addc_u32 s59, s59, 0
	global_load_dwordx4 v[10:13], v131, s[58:59] nt
	s_add_u32 s58, s58, 0x6000
	s_addc_u32 s59, s59, 0
	global_load_dwordx4 v[14:17], v131, s[58:59] nt
	s_add_u32 s58, s58, 0x6000
	s_addc_u32 s59, s59, 0
	global_load_dwordx4 v[18:21], v131, s[58:59] nt
	s_add_u32 s58, s58, 0x6000
	s_addc_u32 s59, s59, 0
	global_load_dwordx4 v[22:25], v131, s[58:59] nt
	s_add_u32 s58, s58, 0x6000
	s_addc_u32 s59, s59, 0
	global_load_dwordx4 v[26:29], v131, s[58:59] nt
	s_add_u32 s58, s58, 0x6000
	s_addc_u32 s59, s59, 0
	global_load_dwordx4 v[30:33], v131, s[58:59] nt
	s_add_u32 s58, s58, 0x6000
	s_addc_u32 s59, s59, 0
	global_load_dwordx4 v[34:37], v131, s[58:59] nt
	s_add_u32 s58, s58, 0x6000
	s_addc_u32 s59, s59, 0
	global_load_dwordx4 v[38:41], v131, s[58:59] nt
	s_add_u32 s58, s58, 0x6000
	s_addc_u32 s59, s59, 0
	global_load_dwordx4 v[42:45], v131, s[58:59] nt
	s_add_u32 s58, s58, 0x6000
	s_addc_u32 s59, s59, 0
	global_load_dwordx4 v[46:49], v131, s[58:59] nt
	s_add_u32 s58, s58, 0x6000
	s_addc_u32 s59, s59, 0
	global_load_dwordx4 v[50:53], v131, s[58:59] nt
	s_add_u32 s58, s58, 0x6000
	s_addc_u32 s59, s59, 0
	global_load_dwordx4 v[54:57], v131, s[58:59] nt
	s_add_u32 s58, s58, 0x6000
	s_addc_u32 s59, s59, 0
	global_load_dwordx4 v[58:61], v131, s[58:59] nt
	s_add_u32 s58, s58, 0x6000
	s_addc_u32 s59, s59, 0
	global_load_dwordx4 v[62:65], v131, s[58:59] nt
	s_add_u32 s58, s58, 0x6000
	s_addc_u32 s59, s59, 0
	global_load_dwordx4 v[66:69], v131, s[58:59] nt
	s_add_u32 s58, s58, 0x6000
	s_addc_u32 s59, s59, 0
	global_load_dwordx4 v[70:73], v131, s[58:59] nt
	s_add_u32 s58, s58, 0x6000
	s_addc_u32 s59, s59, 0
	global_load_dwordx4 v[74:77], v131, s[58:59] nt
	s_add_u32 s58, s58, 0x6000
	s_addc_u32 s59, s59, 0
	global_load_dwordx4 v[78:81], v131, s[58:59] nt
	s_add_u32 s58, s58, 0x6000
	s_addc_u32 s59, s59, 0
	global_load_dwordx4 v[82:85], v131, s[58:59] nt
	s_add_u32 s58, s58, 0x6000
	s_addc_u32 s59, s59, 0
	global_load_dwordx4 v[86:89], v131, s[58:59] nt
	s_add_u32 s58, s58, 0x6000
	s_addc_u32 s59, s59, 0
	global_load_dwordx4 v[90:93], v131, s[58:59] nt
	s_add_u32 s58, s58, 0x6000
	s_addc_u32 s59, s59, 0
	global_load_dwordx4 v[94:97], v131, s[58:59] nt
	s_add_u32 s58, s58, 0x6000
	s_addc_u32 s59, s59, 0
	global_load_dwordx4 v[98:101], v131, s[58:59] nt
	s_add_u32 s58, s58, 0x6000
	s_addc_u32 s59, s59, 0
	global_load_dwordx4 v[102:105], v131, s[58:59] nt
	s_add_u32 s58, s58, 0x6000
	s_addc_u32 s59, s59, 0
	global_load_dwordx4 v[106:109], v131, s[58:59] nt
	s_add_u32 s58, s58, 0x6000
	s_addc_u32 s59, s59, 0
	global_load_dwordx4 v[110:113], v131, s[58:59] nt
	s_add_u32 s58, s58, 0x6000
	s_addc_u32 s59, s59, 0
	global_load_dwordx4 v[114:117], v131, s[58:59] nt
	s_add_u32 s58, s58, 0x6000
	s_addc_u32 s59, s59, 0
	global_load_dwordx4 v[118:121], v131, s[58:59] nt
	s_add_u32 s58, s58, 0x6000
	s_addc_u32 s59, s59, 0
	global_load_dwordx4 v[122:125], v131, s[58:59] nt
	s_add_u32 s58, s58, 0x6000
	s_addc_u32 s59, s59, 0
	global_load_dwordx4 v[126:129], v131, s[58:59] nt
	s_add_u32 s58, s58, 0x6000
	s_addc_u32 s59, s59, 0
	s_waitcnt vmcnt(32)
	v_mul_f32_e32 v168, 0xbfb8aa3b, v132
	v_exp_f32_e32 v168, v168
	s_nop 0
	v_add_f32_e32 v168, 1.0, v168
	v_rcp_f32_e32 v168, v168
	s_nop 0
	v_mul_f32_e32 v132, v132, v168
	v_mul_f32_e32 v168, 0xbfb8aa3b, v133
	v_exp_f32_e32 v168, v168
	s_nop 0
	v_add_f32_e32 v168, 1.0, v168
	v_rcp_f32_e32 v168, v168
	s_nop 0
	v_mul_f32_e32 v133, v133, v168
	v_mul_f32_e32 v168, 0xbfb8aa3b, v134
	v_exp_f32_e32 v168, v168
	s_nop 0
	v_add_f32_e32 v168, 1.0, v168
	v_rcp_f32_e32 v168, v168
	s_nop 0
	v_mul_f32_e32 v134, v134, v168
	v_mul_f32_e32 v168, 0xbfb8aa3b, v135
	v_exp_f32_e32 v168, v168
	s_nop 0
	v_add_f32_e32 v168, 1.0, v168
	v_rcp_f32_e32 v168, v168
	s_nop 0
	v_mul_f32_e32 v135, v135, v168
	s_waitcnt vmcnt(31)
	v_readlane_b32 s30, v132, 0
	v_readlane_b32 s31, v133, 0
	v_readlane_b32 s34, v134, 0
	v_readlane_b32 s35, v135, 0
	s_nop 1
	v_fmac_f32_e32 v136, s30, v2
	v_fmac_f32_e32 v137, s30, v3
	v_fmac_f32_e32 v138, s30, v4
	v_fmac_f32_e32 v139, s30, v5
	v_fmac_f32_e32 v140, s31, v2
	v_fmac_f32_e32 v141, s31, v3
	v_fmac_f32_e32 v142, s31, v4
	v_fmac_f32_e32 v143, s31, v5
	v_fmac_f32_e32 v144, s34, v2
	v_fmac_f32_e32 v145, s34, v3
	v_fmac_f32_e32 v146, s34, v4
	v_fmac_f32_e32 v147, s34, v5
	v_fmac_f32_e32 v148, s35, v2
	v_fmac_f32_e32 v149, s35, v3
	v_fmac_f32_e32 v150, s35, v4
	v_fmac_f32_e32 v151, s35, v5
	s_waitcnt vmcnt(30)
	v_readlane_b32 s30, v132, 1
	v_readlane_b32 s31, v133, 1
	v_readlane_b32 s34, v134, 1
	v_readlane_b32 s35, v135, 1
	s_nop 1
	v_fmac_f32_e32 v136, s30, v6
	v_fmac_f32_e32 v137, s30, v7
	v_fmac_f32_e32 v138, s30, v8
	v_fmac_f32_e32 v139, s30, v9
	v_fmac_f32_e32 v140, s31, v6
	v_fmac_f32_e32 v141, s31, v7
	v_fmac_f32_e32 v142, s31, v8
	v_fmac_f32_e32 v143, s31, v9
	v_fmac_f32_e32 v144, s34, v6
	v_fmac_f32_e32 v145, s34, v7
	v_fmac_f32_e32 v146, s34, v8
	v_fmac_f32_e32 v147, s34, v9
	v_fmac_f32_e32 v148, s35, v6
	v_fmac_f32_e32 v149, s35, v7
	v_fmac_f32_e32 v150, s35, v8
	v_fmac_f32_e32 v151, s35, v9
	s_waitcnt vmcnt(29)
	v_readlane_b32 s30, v132, 2
	v_readlane_b32 s31, v133, 2
	v_readlane_b32 s34, v134, 2
	v_readlane_b32 s35, v135, 2
	s_nop 1
	v_fmac_f32_e32 v136, s30, v10
	v_fmac_f32_e32 v137, s30, v11
	v_fmac_f32_e32 v138, s30, v12
	v_fmac_f32_e32 v139, s30, v13
	v_fmac_f32_e32 v140, s31, v10
	v_fmac_f32_e32 v141, s31, v11
	v_fmac_f32_e32 v142, s31, v12
	v_fmac_f32_e32 v143, s31, v13
	v_fmac_f32_e32 v144, s34, v10
	v_fmac_f32_e32 v145, s34, v11
	v_fmac_f32_e32 v146, s34, v12
	v_fmac_f32_e32 v147, s34, v13
	v_fmac_f32_e32 v148, s35, v10
	v_fmac_f32_e32 v149, s35, v11
	v_fmac_f32_e32 v150, s35, v12
	v_fmac_f32_e32 v151, s35, v13
	s_waitcnt vmcnt(28)
	v_readlane_b32 s30, v132, 3
	v_readlane_b32 s31, v133, 3
	v_readlane_b32 s34, v134, 3
	v_readlane_b32 s35, v135, 3
	s_nop 1
	v_fmac_f32_e32 v136, s30, v14
	v_fmac_f32_e32 v137, s30, v15
	v_fmac_f32_e32 v138, s30, v16
	v_fmac_f32_e32 v139, s30, v17
	v_fmac_f32_e32 v140, s31, v14
	v_fmac_f32_e32 v141, s31, v15
	v_fmac_f32_e32 v142, s31, v16
	v_fmac_f32_e32 v143, s31, v17
	v_fmac_f32_e32 v144, s34, v14
	v_fmac_f32_e32 v145, s34, v15
	v_fmac_f32_e32 v146, s34, v16
	v_fmac_f32_e32 v147, s34, v17
	v_fmac_f32_e32 v148, s35, v14
	v_fmac_f32_e32 v149, s35, v15
	v_fmac_f32_e32 v150, s35, v16
	v_fmac_f32_e32 v151, s35, v17
	s_waitcnt vmcnt(27)
	v_readlane_b32 s30, v132, 4
	v_readlane_b32 s31, v133, 4
	v_readlane_b32 s34, v134, 4
	v_readlane_b32 s35, v135, 4
	s_nop 1
	v_fmac_f32_e32 v136, s30, v18
	v_fmac_f32_e32 v137, s30, v19
	v_fmac_f32_e32 v138, s30, v20
	v_fmac_f32_e32 v139, s30, v21
	v_fmac_f32_e32 v140, s31, v18
	v_fmac_f32_e32 v141, s31, v19
	v_fmac_f32_e32 v142, s31, v20
	v_fmac_f32_e32 v143, s31, v21
	v_fmac_f32_e32 v144, s34, v18
	v_fmac_f32_e32 v145, s34, v19
	v_fmac_f32_e32 v146, s34, v20
	v_fmac_f32_e32 v147, s34, v21
	v_fmac_f32_e32 v148, s35, v18
	v_fmac_f32_e32 v149, s35, v19
	v_fmac_f32_e32 v150, s35, v20
	v_fmac_f32_e32 v151, s35, v21
	s_waitcnt vmcnt(26)
	v_readlane_b32 s30, v132, 5
	v_readlane_b32 s31, v133, 5
	v_readlane_b32 s34, v134, 5
	v_readlane_b32 s35, v135, 5
	s_nop 1
	v_fmac_f32_e32 v136, s30, v22
	v_fmac_f32_e32 v137, s30, v23
	v_fmac_f32_e32 v138, s30, v24
	v_fmac_f32_e32 v139, s30, v25
	v_fmac_f32_e32 v140, s31, v22
	v_fmac_f32_e32 v141, s31, v23
	v_fmac_f32_e32 v142, s31, v24
	v_fmac_f32_e32 v143, s31, v25
	v_fmac_f32_e32 v144, s34, v22
	v_fmac_f32_e32 v145, s34, v23
	v_fmac_f32_e32 v146, s34, v24
	v_fmac_f32_e32 v147, s34, v25
	v_fmac_f32_e32 v148, s35, v22
	v_fmac_f32_e32 v149, s35, v23
	v_fmac_f32_e32 v150, s35, v24
	v_fmac_f32_e32 v151, s35, v25
	s_waitcnt vmcnt(25)
	v_readlane_b32 s30, v132, 6
	v_readlane_b32 s31, v133, 6
	v_readlane_b32 s34, v134, 6
	v_readlane_b32 s35, v135, 6
	s_nop 1
	v_fmac_f32_e32 v136, s30, v26
	v_fmac_f32_e32 v137, s30, v27
	v_fmac_f32_e32 v138, s30, v28
	v_fmac_f32_e32 v139, s30, v29
	v_fmac_f32_e32 v140, s31, v26
	v_fmac_f32_e32 v141, s31, v27
	v_fmac_f32_e32 v142, s31, v28
	v_fmac_f32_e32 v143, s31, v29
	v_fmac_f32_e32 v144, s34, v26
	v_fmac_f32_e32 v145, s34, v27
	v_fmac_f32_e32 v146, s34, v28
	v_fmac_f32_e32 v147, s34, v29
	v_fmac_f32_e32 v148, s35, v26
	v_fmac_f32_e32 v149, s35, v27
	v_fmac_f32_e32 v150, s35, v28
	v_fmac_f32_e32 v151, s35, v29
	s_waitcnt vmcnt(24)
	v_readlane_b32 s30, v132, 7
	v_readlane_b32 s31, v133, 7
	v_readlane_b32 s34, v134, 7
	v_readlane_b32 s35, v135, 7
	s_nop 1
	v_fmac_f32_e32 v136, s30, v30
	v_fmac_f32_e32 v137, s30, v31
	v_fmac_f32_e32 v138, s30, v32
	v_fmac_f32_e32 v139, s30, v33
	v_fmac_f32_e32 v140, s31, v30
	v_fmac_f32_e32 v141, s31, v31
	v_fmac_f32_e32 v142, s31, v32
	v_fmac_f32_e32 v143, s31, v33
	v_fmac_f32_e32 v144, s34, v30
	v_fmac_f32_e32 v145, s34, v31
	v_fmac_f32_e32 v146, s34, v32
	v_fmac_f32_e32 v147, s34, v33
	v_fmac_f32_e32 v148, s35, v30
	v_fmac_f32_e32 v149, s35, v31
	v_fmac_f32_e32 v150, s35, v32
	v_fmac_f32_e32 v151, s35, v33
	s_waitcnt vmcnt(23)
	v_readlane_b32 s30, v132, 8
	v_readlane_b32 s31, v133, 8
	v_readlane_b32 s34, v134, 8
	v_readlane_b32 s35, v135, 8
	s_nop 1
	v_fmac_f32_e32 v136, s30, v34
	v_fmac_f32_e32 v137, s30, v35
	v_fmac_f32_e32 v138, s30, v36
	v_fmac_f32_e32 v139, s30, v37
	v_fmac_f32_e32 v140, s31, v34
	v_fmac_f32_e32 v141, s31, v35
	v_fmac_f32_e32 v142, s31, v36
	v_fmac_f32_e32 v143, s31, v37
	v_fmac_f32_e32 v144, s34, v34
	v_fmac_f32_e32 v145, s34, v35
	v_fmac_f32_e32 v146, s34, v36
	v_fmac_f32_e32 v147, s34, v37
	v_fmac_f32_e32 v148, s35, v34
	v_fmac_f32_e32 v149, s35, v35
	v_fmac_f32_e32 v150, s35, v36
	v_fmac_f32_e32 v151, s35, v37
	s_waitcnt vmcnt(22)
	v_readlane_b32 s30, v132, 9
	v_readlane_b32 s31, v133, 9
	v_readlane_b32 s34, v134, 9
	v_readlane_b32 s35, v135, 9
	s_nop 1
	v_fmac_f32_e32 v136, s30, v38
	v_fmac_f32_e32 v137, s30, v39
	v_fmac_f32_e32 v138, s30, v40
	v_fmac_f32_e32 v139, s30, v41
	v_fmac_f32_e32 v140, s31, v38
	v_fmac_f32_e32 v141, s31, v39
	v_fmac_f32_e32 v142, s31, v40
	v_fmac_f32_e32 v143, s31, v41
	v_fmac_f32_e32 v144, s34, v38
	v_fmac_f32_e32 v145, s34, v39
	v_fmac_f32_e32 v146, s34, v40
	v_fmac_f32_e32 v147, s34, v41
	v_fmac_f32_e32 v148, s35, v38
	v_fmac_f32_e32 v149, s35, v39
	v_fmac_f32_e32 v150, s35, v40
	v_fmac_f32_e32 v151, s35, v41
	s_waitcnt vmcnt(21)
	v_readlane_b32 s30, v132, 10
	v_readlane_b32 s31, v133, 10
	v_readlane_b32 s34, v134, 10
	v_readlane_b32 s35, v135, 10
	s_nop 1
	v_fmac_f32_e32 v136, s30, v42
	v_fmac_f32_e32 v137, s30, v43
	v_fmac_f32_e32 v138, s30, v44
	v_fmac_f32_e32 v139, s30, v45
	v_fmac_f32_e32 v140, s31, v42
	v_fmac_f32_e32 v141, s31, v43
	v_fmac_f32_e32 v142, s31, v44
	v_fmac_f32_e32 v143, s31, v45
	v_fmac_f32_e32 v144, s34, v42
	v_fmac_f32_e32 v145, s34, v43
	v_fmac_f32_e32 v146, s34, v44
	v_fmac_f32_e32 v147, s34, v45
	v_fmac_f32_e32 v148, s35, v42
	v_fmac_f32_e32 v149, s35, v43
	v_fmac_f32_e32 v150, s35, v44
	v_fmac_f32_e32 v151, s35, v45
	s_waitcnt vmcnt(20)
	v_readlane_b32 s30, v132, 11
	v_readlane_b32 s31, v133, 11
	v_readlane_b32 s34, v134, 11
	v_readlane_b32 s35, v135, 11
	s_nop 1
	v_fmac_f32_e32 v136, s30, v46
	v_fmac_f32_e32 v137, s30, v47
	v_fmac_f32_e32 v138, s30, v48
	v_fmac_f32_e32 v139, s30, v49
	v_fmac_f32_e32 v140, s31, v46
	v_fmac_f32_e32 v141, s31, v47
	v_fmac_f32_e32 v142, s31, v48
	v_fmac_f32_e32 v143, s31, v49
	v_fmac_f32_e32 v144, s34, v46
	v_fmac_f32_e32 v145, s34, v47
	v_fmac_f32_e32 v146, s34, v48
	v_fmac_f32_e32 v147, s34, v49
	v_fmac_f32_e32 v148, s35, v46
	v_fmac_f32_e32 v149, s35, v47
	v_fmac_f32_e32 v150, s35, v48
	v_fmac_f32_e32 v151, s35, v49
	s_waitcnt vmcnt(19)
	v_readlane_b32 s30, v132, 12
	v_readlane_b32 s31, v133, 12
	v_readlane_b32 s34, v134, 12
	v_readlane_b32 s35, v135, 12
	s_nop 1
	v_fmac_f32_e32 v136, s30, v50
	v_fmac_f32_e32 v137, s30, v51
	v_fmac_f32_e32 v138, s30, v52
	v_fmac_f32_e32 v139, s30, v53
	v_fmac_f32_e32 v140, s31, v50
	v_fmac_f32_e32 v141, s31, v51
	v_fmac_f32_e32 v142, s31, v52
	v_fmac_f32_e32 v143, s31, v53
	v_fmac_f32_e32 v144, s34, v50
	v_fmac_f32_e32 v145, s34, v51
	v_fmac_f32_e32 v146, s34, v52
	v_fmac_f32_e32 v147, s34, v53
	v_fmac_f32_e32 v148, s35, v50
	v_fmac_f32_e32 v149, s35, v51
	v_fmac_f32_e32 v150, s35, v52
	v_fmac_f32_e32 v151, s35, v53
	s_waitcnt vmcnt(18)
	v_readlane_b32 s30, v132, 13
	v_readlane_b32 s31, v133, 13
	v_readlane_b32 s34, v134, 13
	v_readlane_b32 s35, v135, 13
	s_nop 1
	v_fmac_f32_e32 v136, s30, v54
	v_fmac_f32_e32 v137, s30, v55
	v_fmac_f32_e32 v138, s30, v56
	v_fmac_f32_e32 v139, s30, v57
	v_fmac_f32_e32 v140, s31, v54
	v_fmac_f32_e32 v141, s31, v55
	v_fmac_f32_e32 v142, s31, v56
	v_fmac_f32_e32 v143, s31, v57
	v_fmac_f32_e32 v144, s34, v54
	v_fmac_f32_e32 v145, s34, v55
	v_fmac_f32_e32 v146, s34, v56
	v_fmac_f32_e32 v147, s34, v57
	v_fmac_f32_e32 v148, s35, v54
	v_fmac_f32_e32 v149, s35, v55
	v_fmac_f32_e32 v150, s35, v56
	v_fmac_f32_e32 v151, s35, v57
	s_waitcnt vmcnt(17)
	v_readlane_b32 s30, v132, 14
	v_readlane_b32 s31, v133, 14
	v_readlane_b32 s34, v134, 14
	v_readlane_b32 s35, v135, 14
	s_nop 1
	v_fmac_f32_e32 v136, s30, v58
	v_fmac_f32_e32 v137, s30, v59
	v_fmac_f32_e32 v138, s30, v60
	v_fmac_f32_e32 v139, s30, v61
	v_fmac_f32_e32 v140, s31, v58
	v_fmac_f32_e32 v141, s31, v59
	v_fmac_f32_e32 v142, s31, v60
	v_fmac_f32_e32 v143, s31, v61
	v_fmac_f32_e32 v144, s34, v58
	v_fmac_f32_e32 v145, s34, v59
	v_fmac_f32_e32 v146, s34, v60
	v_fmac_f32_e32 v147, s34, v61
	v_fmac_f32_e32 v148, s35, v58
	v_fmac_f32_e32 v149, s35, v59
	v_fmac_f32_e32 v150, s35, v60
	v_fmac_f32_e32 v151, s35, v61
	s_waitcnt vmcnt(16)
	v_readlane_b32 s30, v132, 15
	v_readlane_b32 s31, v133, 15
	v_readlane_b32 s34, v134, 15
	v_readlane_b32 s35, v135, 15
	s_nop 1
	v_fmac_f32_e32 v136, s30, v62
	v_fmac_f32_e32 v137, s30, v63
	v_fmac_f32_e32 v138, s30, v64
	v_fmac_f32_e32 v139, s30, v65
	v_fmac_f32_e32 v140, s31, v62
	v_fmac_f32_e32 v141, s31, v63
	v_fmac_f32_e32 v142, s31, v64
	v_fmac_f32_e32 v143, s31, v65
	v_fmac_f32_e32 v144, s34, v62
	v_fmac_f32_e32 v145, s34, v63
	v_fmac_f32_e32 v146, s34, v64
	v_fmac_f32_e32 v147, s34, v65
	v_fmac_f32_e32 v148, s35, v62
	v_fmac_f32_e32 v149, s35, v63
	v_fmac_f32_e32 v150, s35, v64
	v_fmac_f32_e32 v151, s35, v65
	s_waitcnt vmcnt(15)
	v_readlane_b32 s30, v132, 16
	v_readlane_b32 s31, v133, 16
	v_readlane_b32 s34, v134, 16
	v_readlane_b32 s35, v135, 16
	s_nop 1
	v_fmac_f32_e32 v136, s30, v66
	v_fmac_f32_e32 v137, s30, v67
	v_fmac_f32_e32 v138, s30, v68
	v_fmac_f32_e32 v139, s30, v69
	v_fmac_f32_e32 v140, s31, v66
	v_fmac_f32_e32 v141, s31, v67
	v_fmac_f32_e32 v142, s31, v68
	v_fmac_f32_e32 v143, s31, v69
	v_fmac_f32_e32 v144, s34, v66
	v_fmac_f32_e32 v145, s34, v67
	v_fmac_f32_e32 v146, s34, v68
	v_fmac_f32_e32 v147, s34, v69
	v_fmac_f32_e32 v148, s35, v66
	v_fmac_f32_e32 v149, s35, v67
	v_fmac_f32_e32 v150, s35, v68
	v_fmac_f32_e32 v151, s35, v69
	s_waitcnt vmcnt(14)
	v_readlane_b32 s30, v132, 17
	v_readlane_b32 s31, v133, 17
	v_readlane_b32 s34, v134, 17
	v_readlane_b32 s35, v135, 17
	s_nop 1
	v_fmac_f32_e32 v136, s30, v70
	v_fmac_f32_e32 v137, s30, v71
	v_fmac_f32_e32 v138, s30, v72
	v_fmac_f32_e32 v139, s30, v73
	v_fmac_f32_e32 v140, s31, v70
	v_fmac_f32_e32 v141, s31, v71
	v_fmac_f32_e32 v142, s31, v72
	v_fmac_f32_e32 v143, s31, v73
	v_fmac_f32_e32 v144, s34, v70
	v_fmac_f32_e32 v145, s34, v71
	v_fmac_f32_e32 v146, s34, v72
	v_fmac_f32_e32 v147, s34, v73
	v_fmac_f32_e32 v148, s35, v70
	v_fmac_f32_e32 v149, s35, v71
	v_fmac_f32_e32 v150, s35, v72
	v_fmac_f32_e32 v151, s35, v73
	s_waitcnt vmcnt(13)
	v_readlane_b32 s30, v132, 18
	v_readlane_b32 s31, v133, 18
	v_readlane_b32 s34, v134, 18
	v_readlane_b32 s35, v135, 18
	s_nop 1
	v_fmac_f32_e32 v136, s30, v74
	v_fmac_f32_e32 v137, s30, v75
	v_fmac_f32_e32 v138, s30, v76
	v_fmac_f32_e32 v139, s30, v77
	v_fmac_f32_e32 v140, s31, v74
	v_fmac_f32_e32 v141, s31, v75
	v_fmac_f32_e32 v142, s31, v76
	v_fmac_f32_e32 v143, s31, v77
	v_fmac_f32_e32 v144, s34, v74
	v_fmac_f32_e32 v145, s34, v75
	v_fmac_f32_e32 v146, s34, v76
	v_fmac_f32_e32 v147, s34, v77
	v_fmac_f32_e32 v148, s35, v74
	v_fmac_f32_e32 v149, s35, v75
	v_fmac_f32_e32 v150, s35, v76
	v_fmac_f32_e32 v151, s35, v77
	s_waitcnt vmcnt(12)
	v_readlane_b32 s30, v132, 19
	v_readlane_b32 s31, v133, 19
	v_readlane_b32 s34, v134, 19
	v_readlane_b32 s35, v135, 19
	s_nop 1
	v_fmac_f32_e32 v136, s30, v78
	v_fmac_f32_e32 v137, s30, v79
	v_fmac_f32_e32 v138, s30, v80
	v_fmac_f32_e32 v139, s30, v81
	v_fmac_f32_e32 v140, s31, v78
	v_fmac_f32_e32 v141, s31, v79
	v_fmac_f32_e32 v142, s31, v80
	v_fmac_f32_e32 v143, s31, v81
	v_fmac_f32_e32 v144, s34, v78
	v_fmac_f32_e32 v145, s34, v79
	v_fmac_f32_e32 v146, s34, v80
	v_fmac_f32_e32 v147, s34, v81
	v_fmac_f32_e32 v148, s35, v78
	v_fmac_f32_e32 v149, s35, v79
	v_fmac_f32_e32 v150, s35, v80
	v_fmac_f32_e32 v151, s35, v81
	s_waitcnt vmcnt(11)
	v_readlane_b32 s30, v132, 20
	v_readlane_b32 s31, v133, 20
	v_readlane_b32 s34, v134, 20
	v_readlane_b32 s35, v135, 20
	s_nop 1
	v_fmac_f32_e32 v136, s30, v82
	v_fmac_f32_e32 v137, s30, v83
	v_fmac_f32_e32 v138, s30, v84
	v_fmac_f32_e32 v139, s30, v85
	v_fmac_f32_e32 v140, s31, v82
	v_fmac_f32_e32 v141, s31, v83
	v_fmac_f32_e32 v142, s31, v84
	v_fmac_f32_e32 v143, s31, v85
	v_fmac_f32_e32 v144, s34, v82
	v_fmac_f32_e32 v145, s34, v83
	v_fmac_f32_e32 v146, s34, v84
	v_fmac_f32_e32 v147, s34, v85
	v_fmac_f32_e32 v148, s35, v82
	v_fmac_f32_e32 v149, s35, v83
	v_fmac_f32_e32 v150, s35, v84
	v_fmac_f32_e32 v151, s35, v85
	s_waitcnt vmcnt(10)
	v_readlane_b32 s30, v132, 21
	v_readlane_b32 s31, v133, 21
	v_readlane_b32 s34, v134, 21
	v_readlane_b32 s35, v135, 21
	s_nop 1
	v_fmac_f32_e32 v136, s30, v86
	v_fmac_f32_e32 v137, s30, v87
	v_fmac_f32_e32 v138, s30, v88
	v_fmac_f32_e32 v139, s30, v89
	v_fmac_f32_e32 v140, s31, v86
	v_fmac_f32_e32 v141, s31, v87
	v_fmac_f32_e32 v142, s31, v88
	v_fmac_f32_e32 v143, s31, v89
	v_fmac_f32_e32 v144, s34, v86
	v_fmac_f32_e32 v145, s34, v87
	v_fmac_f32_e32 v146, s34, v88
	v_fmac_f32_e32 v147, s34, v89
	v_fmac_f32_e32 v148, s35, v86
	v_fmac_f32_e32 v149, s35, v87
	v_fmac_f32_e32 v150, s35, v88
	v_fmac_f32_e32 v151, s35, v89
	s_waitcnt vmcnt(9)
	v_readlane_b32 s30, v132, 22
	v_readlane_b32 s31, v133, 22
	v_readlane_b32 s34, v134, 22
	v_readlane_b32 s35, v135, 22
	s_nop 1
	v_fmac_f32_e32 v136, s30, v90
	v_fmac_f32_e32 v137, s30, v91
	v_fmac_f32_e32 v138, s30, v92
	v_fmac_f32_e32 v139, s30, v93
	v_fmac_f32_e32 v140, s31, v90
	v_fmac_f32_e32 v141, s31, v91
	v_fmac_f32_e32 v142, s31, v92
	v_fmac_f32_e32 v143, s31, v93
	v_fmac_f32_e32 v144, s34, v90
	v_fmac_f32_e32 v145, s34, v91
	v_fmac_f32_e32 v146, s34, v92
	v_fmac_f32_e32 v147, s34, v93
	v_fmac_f32_e32 v148, s35, v90
	v_fmac_f32_e32 v149, s35, v91
	v_fmac_f32_e32 v150, s35, v92
	v_fmac_f32_e32 v151, s35, v93
	s_waitcnt vmcnt(8)
	v_readlane_b32 s30, v132, 23
	v_readlane_b32 s31, v133, 23
	v_readlane_b32 s34, v134, 23
	v_readlane_b32 s35, v135, 23
	s_nop 1
	v_fmac_f32_e32 v136, s30, v94
	v_fmac_f32_e32 v137, s30, v95
	v_fmac_f32_e32 v138, s30, v96
	v_fmac_f32_e32 v139, s30, v97
	v_fmac_f32_e32 v140, s31, v94
	v_fmac_f32_e32 v141, s31, v95
	v_fmac_f32_e32 v142, s31, v96
	v_fmac_f32_e32 v143, s31, v97
	v_fmac_f32_e32 v144, s34, v94
	v_fmac_f32_e32 v145, s34, v95
	v_fmac_f32_e32 v146, s34, v96
	v_fmac_f32_e32 v147, s34, v97
	v_fmac_f32_e32 v148, s35, v94
	v_fmac_f32_e32 v149, s35, v95
	v_fmac_f32_e32 v150, s35, v96
	v_fmac_f32_e32 v151, s35, v97
	s_waitcnt vmcnt(7)
	v_readlane_b32 s30, v132, 24
	v_readlane_b32 s31, v133, 24
	v_readlane_b32 s34, v134, 24
	v_readlane_b32 s35, v135, 24
	s_nop 1
	v_fmac_f32_e32 v136, s30, v98
	v_fmac_f32_e32 v137, s30, v99
	v_fmac_f32_e32 v138, s30, v100
	v_fmac_f32_e32 v139, s30, v101
	v_fmac_f32_e32 v140, s31, v98
	v_fmac_f32_e32 v141, s31, v99
	v_fmac_f32_e32 v142, s31, v100
	v_fmac_f32_e32 v143, s31, v101
	v_fmac_f32_e32 v144, s34, v98
	v_fmac_f32_e32 v145, s34, v99
	v_fmac_f32_e32 v146, s34, v100
	v_fmac_f32_e32 v147, s34, v101
	v_fmac_f32_e32 v148, s35, v98
	v_fmac_f32_e32 v149, s35, v99
	v_fmac_f32_e32 v150, s35, v100
	v_fmac_f32_e32 v151, s35, v101
	s_waitcnt vmcnt(6)
	v_readlane_b32 s30, v132, 25
	v_readlane_b32 s31, v133, 25
	v_readlane_b32 s34, v134, 25
	v_readlane_b32 s35, v135, 25
	s_nop 1
	v_fmac_f32_e32 v136, s30, v102
	v_fmac_f32_e32 v137, s30, v103
	v_fmac_f32_e32 v138, s30, v104
	v_fmac_f32_e32 v139, s30, v105
	v_fmac_f32_e32 v140, s31, v102
	v_fmac_f32_e32 v141, s31, v103
	v_fmac_f32_e32 v142, s31, v104
	v_fmac_f32_e32 v143, s31, v105
	v_fmac_f32_e32 v144, s34, v102
	v_fmac_f32_e32 v145, s34, v103
	v_fmac_f32_e32 v146, s34, v104
	v_fmac_f32_e32 v147, s34, v105
	v_fmac_f32_e32 v148, s35, v102
	v_fmac_f32_e32 v149, s35, v103
	v_fmac_f32_e32 v150, s35, v104
	v_fmac_f32_e32 v151, s35, v105
	s_waitcnt vmcnt(5)
	v_readlane_b32 s30, v132, 26
	v_readlane_b32 s31, v133, 26
	v_readlane_b32 s34, v134, 26
	v_readlane_b32 s35, v135, 26
	s_nop 1
	v_fmac_f32_e32 v136, s30, v106
	v_fmac_f32_e32 v137, s30, v107
	v_fmac_f32_e32 v138, s30, v108
	v_fmac_f32_e32 v139, s30, v109
	v_fmac_f32_e32 v140, s31, v106
	v_fmac_f32_e32 v141, s31, v107
	v_fmac_f32_e32 v142, s31, v108
	v_fmac_f32_e32 v143, s31, v109
	v_fmac_f32_e32 v144, s34, v106
	v_fmac_f32_e32 v145, s34, v107
	v_fmac_f32_e32 v146, s34, v108
	v_fmac_f32_e32 v147, s34, v109
	v_fmac_f32_e32 v148, s35, v106
	v_fmac_f32_e32 v149, s35, v107
	v_fmac_f32_e32 v150, s35, v108
	v_fmac_f32_e32 v151, s35, v109
	s_waitcnt vmcnt(4)
	v_readlane_b32 s30, v132, 27
	v_readlane_b32 s31, v133, 27
	v_readlane_b32 s34, v134, 27
	v_readlane_b32 s35, v135, 27
	s_nop 1
	v_fmac_f32_e32 v136, s30, v110
	v_fmac_f32_e32 v137, s30, v111
	v_fmac_f32_e32 v138, s30, v112
	v_fmac_f32_e32 v139, s30, v113
	v_fmac_f32_e32 v140, s31, v110
	v_fmac_f32_e32 v141, s31, v111
	v_fmac_f32_e32 v142, s31, v112
	v_fmac_f32_e32 v143, s31, v113
	v_fmac_f32_e32 v144, s34, v110
	v_fmac_f32_e32 v145, s34, v111
	v_fmac_f32_e32 v146, s34, v112
	v_fmac_f32_e32 v147, s34, v113
	v_fmac_f32_e32 v148, s35, v110
	v_fmac_f32_e32 v149, s35, v111
	v_fmac_f32_e32 v150, s35, v112
	v_fmac_f32_e32 v151, s35, v113
	s_waitcnt vmcnt(3)
	v_readlane_b32 s30, v132, 28
	v_readlane_b32 s31, v133, 28
	v_readlane_b32 s34, v134, 28
	v_readlane_b32 s35, v135, 28
	s_nop 1
	v_fmac_f32_e32 v136, s30, v114
	v_fmac_f32_e32 v137, s30, v115
	v_fmac_f32_e32 v138, s30, v116
	v_fmac_f32_e32 v139, s30, v117
	v_fmac_f32_e32 v140, s31, v114
	v_fmac_f32_e32 v141, s31, v115
	v_fmac_f32_e32 v142, s31, v116
	v_fmac_f32_e32 v143, s31, v117
	v_fmac_f32_e32 v144, s34, v114
	v_fmac_f32_e32 v145, s34, v115
	v_fmac_f32_e32 v146, s34, v116
	v_fmac_f32_e32 v147, s34, v117
	v_fmac_f32_e32 v148, s35, v114
	v_fmac_f32_e32 v149, s35, v115
	v_fmac_f32_e32 v150, s35, v116
	v_fmac_f32_e32 v151, s35, v117
	s_waitcnt vmcnt(2)
	v_readlane_b32 s30, v132, 29
	v_readlane_b32 s31, v133, 29
	v_readlane_b32 s34, v134, 29
	v_readlane_b32 s35, v135, 29
	s_nop 1
	v_fmac_f32_e32 v136, s30, v118
	v_fmac_f32_e32 v137, s30, v119
	v_fmac_f32_e32 v138, s30, v120
	v_fmac_f32_e32 v139, s30, v121
	v_fmac_f32_e32 v140, s31, v118
	v_fmac_f32_e32 v141, s31, v119
	v_fmac_f32_e32 v142, s31, v120
	v_fmac_f32_e32 v143, s31, v121
	v_fmac_f32_e32 v144, s34, v118
	v_fmac_f32_e32 v145, s34, v119
	v_fmac_f32_e32 v146, s34, v120
	v_fmac_f32_e32 v147, s34, v121
	v_fmac_f32_e32 v148, s35, v118
	v_fmac_f32_e32 v149, s35, v119
	v_fmac_f32_e32 v150, s35, v120
	v_fmac_f32_e32 v151, s35, v121
	s_waitcnt vmcnt(1)
	v_readlane_b32 s30, v132, 30
	v_readlane_b32 s31, v133, 30
	v_readlane_b32 s34, v134, 30
	v_readlane_b32 s35, v135, 30
	s_nop 1
	v_fmac_f32_e32 v136, s30, v122
	v_fmac_f32_e32 v137, s30, v123
	v_fmac_f32_e32 v138, s30, v124
	v_fmac_f32_e32 v139, s30, v125
	v_fmac_f32_e32 v140, s31, v122
	v_fmac_f32_e32 v141, s31, v123
	v_fmac_f32_e32 v142, s31, v124
	v_fmac_f32_e32 v143, s31, v125
	v_fmac_f32_e32 v144, s34, v122
	v_fmac_f32_e32 v145, s34, v123
	v_fmac_f32_e32 v146, s34, v124
	v_fmac_f32_e32 v147, s34, v125
	v_fmac_f32_e32 v148, s35, v122
	v_fmac_f32_e32 v149, s35, v123
	v_fmac_f32_e32 v150, s35, v124
	v_fmac_f32_e32 v151, s35, v125
	s_waitcnt vmcnt(0)
	v_readlane_b32 s30, v132, 31
	v_readlane_b32 s31, v133, 31
	v_readlane_b32 s34, v134, 31
	v_readlane_b32 s35, v135, 31
	s_nop 1
	v_fmac_f32_e32 v136, s30, v126
	v_fmac_f32_e32 v137, s30, v127
	v_fmac_f32_e32 v138, s30, v128
	v_fmac_f32_e32 v139, s30, v129
	v_fmac_f32_e32 v140, s31, v126
	v_fmac_f32_e32 v141, s31, v127
	v_fmac_f32_e32 v142, s31, v128
	v_fmac_f32_e32 v143, s31, v129
	v_fmac_f32_e32 v144, s34, v126
	v_fmac_f32_e32 v145, s34, v127
	v_fmac_f32_e32 v146, s34, v128
	v_fmac_f32_e32 v147, s34, v129
	v_fmac_f32_e32 v148, s35, v126
	v_fmac_f32_e32 v149, s35, v127
	v_fmac_f32_e32 v150, s35, v128
	v_fmac_f32_e32 v151, s35, v129
	global_load_dwordx4 v[2:5], v131, s[58:59] nt
	s_add_u32 s58, s58, 0x6000
	s_addc_u32 s59, s59, 0
	global_load_dwordx4 v[6:9], v131, s[58:59] nt
	s_add_u32 s58, s58, 0x6000
	s_addc_u32 s59, s59, 0
	global_load_dwordx4 v[10:13], v131, s[58:59] nt
	s_add_u32 s58, s58, 0x6000
	s_addc_u32 s59, s59, 0
	global_load_dwordx4 v[14:17], v131, s[58:59] nt
	s_add_u32 s58, s58, 0x6000
	s_addc_u32 s59, s59, 0
	global_load_dwordx4 v[18:21], v131, s[58:59] nt
	s_add_u32 s58, s58, 0x6000
	s_addc_u32 s59, s59, 0
	global_load_dwordx4 v[22:25], v131, s[58:59] nt
	s_add_u32 s58, s58, 0x6000
	s_addc_u32 s59, s59, 0
	global_load_dwordx4 v[26:29], v131, s[58:59] nt
	s_add_u32 s58, s58, 0x6000
	s_addc_u32 s59, s59, 0
	global_load_dwordx4 v[30:33], v131, s[58:59] nt
	s_add_u32 s58, s58, 0x6000
	s_addc_u32 s59, s59, 0
	global_load_dwordx4 v[34:37], v131, s[58:59] nt
	s_add_u32 s58, s58, 0x6000
	s_addc_u32 s59, s59, 0
	global_load_dwordx4 v[38:41], v131, s[58:59] nt
	s_add_u32 s58, s58, 0x6000
	s_addc_u32 s59, s59, 0
	global_load_dwordx4 v[42:45], v131, s[58:59] nt
	s_add_u32 s58, s58, 0x6000
	s_addc_u32 s59, s59, 0
	global_load_dwordx4 v[46:49], v131, s[58:59] nt
	s_add_u32 s58, s58, 0x6000
	s_addc_u32 s59, s59, 0
	global_load_dwordx4 v[50:53], v131, s[58:59] nt
	s_add_u32 s58, s58, 0x6000
	s_addc_u32 s59, s59, 0
	global_load_dwordx4 v[54:57], v131, s[58:59] nt
	s_add_u32 s58, s58, 0x6000
	s_addc_u32 s59, s59, 0
	global_load_dwordx4 v[58:61], v131, s[58:59] nt
	s_add_u32 s58, s58, 0x6000
	s_addc_u32 s59, s59, 0
	global_load_dwordx4 v[62:65], v131, s[58:59] nt
	s_add_u32 s58, s58, 0x6000
	s_addc_u32 s59, s59, 0
	global_load_dwordx4 v[66:69], v131, s[58:59] nt
	s_add_u32 s58, s58, 0x6000
	s_addc_u32 s59, s59, 0
	global_load_dwordx4 v[70:73], v131, s[58:59] nt
	s_add_u32 s58, s58, 0x6000
	s_addc_u32 s59, s59, 0
	global_load_dwordx4 v[74:77], v131, s[58:59] nt
	s_add_u32 s58, s58, 0x6000
	s_addc_u32 s59, s59, 0
	global_load_dwordx4 v[78:81], v131, s[58:59] nt
	s_add_u32 s58, s58, 0x6000
	s_addc_u32 s59, s59, 0
	global_load_dwordx4 v[82:85], v131, s[58:59] nt
	s_add_u32 s58, s58, 0x6000
	s_addc_u32 s59, s59, 0
	global_load_dwordx4 v[86:89], v131, s[58:59] nt
	s_add_u32 s58, s58, 0x6000
	s_addc_u32 s59, s59, 0
	global_load_dwordx4 v[90:93], v131, s[58:59] nt
	s_add_u32 s58, s58, 0x6000
	s_addc_u32 s59, s59, 0
	global_load_dwordx4 v[94:97], v131, s[58:59] nt
	s_add_u32 s58, s58, 0x6000
	s_addc_u32 s59, s59, 0
	global_load_dwordx4 v[98:101], v131, s[58:59] nt
	s_add_u32 s58, s58, 0x6000
	s_addc_u32 s59, s59, 0
	global_load_dwordx4 v[102:105], v131, s[58:59] nt
	s_add_u32 s58, s58, 0x6000
	s_addc_u32 s59, s59, 0
	global_load_dwordx4 v[106:109], v131, s[58:59] nt
	s_add_u32 s58, s58, 0x6000
	s_addc_u32 s59, s59, 0
	global_load_dwordx4 v[110:113], v131, s[58:59] nt
	s_add_u32 s58, s58, 0x6000
	s_addc_u32 s59, s59, 0
	global_load_dwordx4 v[114:117], v131, s[58:59] nt
	s_add_u32 s58, s58, 0x6000
	s_addc_u32 s59, s59, 0
	global_load_dwordx4 v[118:121], v131, s[58:59] nt
	s_add_u32 s58, s58, 0x6000
	s_addc_u32 s59, s59, 0
	global_load_dwordx4 v[122:125], v131, s[58:59] nt
	s_add_u32 s58, s58, 0x6000
	s_addc_u32 s59, s59, 0
	global_load_dwordx4 v[126:129], v131, s[58:59] nt
	s_add_u32 s58, s58, 0x6000
	s_addc_u32 s59, s59, 0
	s_waitcnt vmcnt(31)
	v_readlane_b32 s30, v132, 32
	v_readlane_b32 s31, v133, 32
	v_readlane_b32 s34, v134, 32
	v_readlane_b32 s35, v135, 32
	s_nop 1
	v_fmac_f32_e32 v136, s30, v2
	v_fmac_f32_e32 v137, s30, v3
	v_fmac_f32_e32 v138, s30, v4
	v_fmac_f32_e32 v139, s30, v5
	v_fmac_f32_e32 v140, s31, v2
	v_fmac_f32_e32 v141, s31, v3
	v_fmac_f32_e32 v142, s31, v4
	v_fmac_f32_e32 v143, s31, v5
	v_fmac_f32_e32 v144, s34, v2
	v_fmac_f32_e32 v145, s34, v3
	v_fmac_f32_e32 v146, s34, v4
	v_fmac_f32_e32 v147, s34, v5
	v_fmac_f32_e32 v148, s35, v2
	v_fmac_f32_e32 v149, s35, v3
	v_fmac_f32_e32 v150, s35, v4
	v_fmac_f32_e32 v151, s35, v5
	s_waitcnt vmcnt(30)
	v_readlane_b32 s30, v132, 33
	v_readlane_b32 s31, v133, 33
	v_readlane_b32 s34, v134, 33
	v_readlane_b32 s35, v135, 33
	s_nop 1
	v_fmac_f32_e32 v136, s30, v6
	v_fmac_f32_e32 v137, s30, v7
	v_fmac_f32_e32 v138, s30, v8
	v_fmac_f32_e32 v139, s30, v9
	v_fmac_f32_e32 v140, s31, v6
	v_fmac_f32_e32 v141, s31, v7
	v_fmac_f32_e32 v142, s31, v8
	v_fmac_f32_e32 v143, s31, v9
	v_fmac_f32_e32 v144, s34, v6
	v_fmac_f32_e32 v145, s34, v7
	v_fmac_f32_e32 v146, s34, v8
	v_fmac_f32_e32 v147, s34, v9
	v_fmac_f32_e32 v148, s35, v6
	v_fmac_f32_e32 v149, s35, v7
	v_fmac_f32_e32 v150, s35, v8
	v_fmac_f32_e32 v151, s35, v9
	s_waitcnt vmcnt(29)
	v_readlane_b32 s30, v132, 34
	v_readlane_b32 s31, v133, 34
	v_readlane_b32 s34, v134, 34
	v_readlane_b32 s35, v135, 34
	s_nop 1
	v_fmac_f32_e32 v136, s30, v10
	v_fmac_f32_e32 v137, s30, v11
	v_fmac_f32_e32 v138, s30, v12
	v_fmac_f32_e32 v139, s30, v13
	v_fmac_f32_e32 v140, s31, v10
	v_fmac_f32_e32 v141, s31, v11
	v_fmac_f32_e32 v142, s31, v12
	v_fmac_f32_e32 v143, s31, v13
	v_fmac_f32_e32 v144, s34, v10
	v_fmac_f32_e32 v145, s34, v11
	v_fmac_f32_e32 v146, s34, v12
	v_fmac_f32_e32 v147, s34, v13
	v_fmac_f32_e32 v148, s35, v10
	v_fmac_f32_e32 v149, s35, v11
	v_fmac_f32_e32 v150, s35, v12
	v_fmac_f32_e32 v151, s35, v13
	s_waitcnt vmcnt(28)
	v_readlane_b32 s30, v132, 35
	v_readlane_b32 s31, v133, 35
	v_readlane_b32 s34, v134, 35
	v_readlane_b32 s35, v135, 35
	s_nop 1
	v_fmac_f32_e32 v136, s30, v14
	v_fmac_f32_e32 v137, s30, v15
	v_fmac_f32_e32 v138, s30, v16
	v_fmac_f32_e32 v139, s30, v17
	v_fmac_f32_e32 v140, s31, v14
	v_fmac_f32_e32 v141, s31, v15
	v_fmac_f32_e32 v142, s31, v16
	v_fmac_f32_e32 v143, s31, v17
	v_fmac_f32_e32 v144, s34, v14
	v_fmac_f32_e32 v145, s34, v15
	v_fmac_f32_e32 v146, s34, v16
	v_fmac_f32_e32 v147, s34, v17
	v_fmac_f32_e32 v148, s35, v14
	v_fmac_f32_e32 v149, s35, v15
	v_fmac_f32_e32 v150, s35, v16
	v_fmac_f32_e32 v151, s35, v17
	s_waitcnt vmcnt(27)
	v_readlane_b32 s30, v132, 36
	v_readlane_b32 s31, v133, 36
	v_readlane_b32 s34, v134, 36
	v_readlane_b32 s35, v135, 36
	s_nop 1
	v_fmac_f32_e32 v136, s30, v18
	v_fmac_f32_e32 v137, s30, v19
	v_fmac_f32_e32 v138, s30, v20
	v_fmac_f32_e32 v139, s30, v21
	v_fmac_f32_e32 v140, s31, v18
	v_fmac_f32_e32 v141, s31, v19
	v_fmac_f32_e32 v142, s31, v20
	v_fmac_f32_e32 v143, s31, v21
	v_fmac_f32_e32 v144, s34, v18
	v_fmac_f32_e32 v145, s34, v19
	v_fmac_f32_e32 v146, s34, v20
	v_fmac_f32_e32 v147, s34, v21
	v_fmac_f32_e32 v148, s35, v18
	v_fmac_f32_e32 v149, s35, v19
	v_fmac_f32_e32 v150, s35, v20
	v_fmac_f32_e32 v151, s35, v21
	s_waitcnt vmcnt(26)
	v_readlane_b32 s30, v132, 37
	v_readlane_b32 s31, v133, 37
	v_readlane_b32 s34, v134, 37
	v_readlane_b32 s35, v135, 37
	s_nop 1
	v_fmac_f32_e32 v136, s30, v22
	v_fmac_f32_e32 v137, s30, v23
	v_fmac_f32_e32 v138, s30, v24
	v_fmac_f32_e32 v139, s30, v25
	v_fmac_f32_e32 v140, s31, v22
	v_fmac_f32_e32 v141, s31, v23
	v_fmac_f32_e32 v142, s31, v24
	v_fmac_f32_e32 v143, s31, v25
	v_fmac_f32_e32 v144, s34, v22
	v_fmac_f32_e32 v145, s34, v23
	v_fmac_f32_e32 v146, s34, v24
	v_fmac_f32_e32 v147, s34, v25
	v_fmac_f32_e32 v148, s35, v22
	v_fmac_f32_e32 v149, s35, v23
	v_fmac_f32_e32 v150, s35, v24
	v_fmac_f32_e32 v151, s35, v25
	s_waitcnt vmcnt(25)
	v_readlane_b32 s30, v132, 38
	v_readlane_b32 s31, v133, 38
	v_readlane_b32 s34, v134, 38
	v_readlane_b32 s35, v135, 38
	s_nop 1
	v_fmac_f32_e32 v136, s30, v26
	v_fmac_f32_e32 v137, s30, v27
	v_fmac_f32_e32 v138, s30, v28
	v_fmac_f32_e32 v139, s30, v29
	v_fmac_f32_e32 v140, s31, v26
	v_fmac_f32_e32 v141, s31, v27
	v_fmac_f32_e32 v142, s31, v28
	v_fmac_f32_e32 v143, s31, v29
	v_fmac_f32_e32 v144, s34, v26
	v_fmac_f32_e32 v145, s34, v27
	v_fmac_f32_e32 v146, s34, v28
	v_fmac_f32_e32 v147, s34, v29
	v_fmac_f32_e32 v148, s35, v26
	v_fmac_f32_e32 v149, s35, v27
	v_fmac_f32_e32 v150, s35, v28
	v_fmac_f32_e32 v151, s35, v29
	s_waitcnt vmcnt(24)
	v_readlane_b32 s30, v132, 39
	v_readlane_b32 s31, v133, 39
	v_readlane_b32 s34, v134, 39
	v_readlane_b32 s35, v135, 39
	s_nop 1
	v_fmac_f32_e32 v136, s30, v30
	v_fmac_f32_e32 v137, s30, v31
	v_fmac_f32_e32 v138, s30, v32
	v_fmac_f32_e32 v139, s30, v33
	v_fmac_f32_e32 v140, s31, v30
	v_fmac_f32_e32 v141, s31, v31
	v_fmac_f32_e32 v142, s31, v32
	v_fmac_f32_e32 v143, s31, v33
	v_fmac_f32_e32 v144, s34, v30
	v_fmac_f32_e32 v145, s34, v31
	v_fmac_f32_e32 v146, s34, v32
	v_fmac_f32_e32 v147, s34, v33
	v_fmac_f32_e32 v148, s35, v30
	v_fmac_f32_e32 v149, s35, v31
	v_fmac_f32_e32 v150, s35, v32
	v_fmac_f32_e32 v151, s35, v33
	s_waitcnt vmcnt(23)
	v_readlane_b32 s30, v132, 40
	v_readlane_b32 s31, v133, 40
	v_readlane_b32 s34, v134, 40
	v_readlane_b32 s35, v135, 40
	s_nop 1
	v_fmac_f32_e32 v136, s30, v34
	v_fmac_f32_e32 v137, s30, v35
	v_fmac_f32_e32 v138, s30, v36
	v_fmac_f32_e32 v139, s30, v37
	v_fmac_f32_e32 v140, s31, v34
	v_fmac_f32_e32 v141, s31, v35
	v_fmac_f32_e32 v142, s31, v36
	v_fmac_f32_e32 v143, s31, v37
	v_fmac_f32_e32 v144, s34, v34
	v_fmac_f32_e32 v145, s34, v35
	v_fmac_f32_e32 v146, s34, v36
	v_fmac_f32_e32 v147, s34, v37
	v_fmac_f32_e32 v148, s35, v34
	v_fmac_f32_e32 v149, s35, v35
	v_fmac_f32_e32 v150, s35, v36
	v_fmac_f32_e32 v151, s35, v37
	s_waitcnt vmcnt(22)
	v_readlane_b32 s30, v132, 41
	v_readlane_b32 s31, v133, 41
	v_readlane_b32 s34, v134, 41
	v_readlane_b32 s35, v135, 41
	s_nop 1
	v_fmac_f32_e32 v136, s30, v38
	v_fmac_f32_e32 v137, s30, v39
	v_fmac_f32_e32 v138, s30, v40
	v_fmac_f32_e32 v139, s30, v41
	v_fmac_f32_e32 v140, s31, v38
	v_fmac_f32_e32 v141, s31, v39
	v_fmac_f32_e32 v142, s31, v40
	v_fmac_f32_e32 v143, s31, v41
	v_fmac_f32_e32 v144, s34, v38
	v_fmac_f32_e32 v145, s34, v39
	v_fmac_f32_e32 v146, s34, v40
	v_fmac_f32_e32 v147, s34, v41
	v_fmac_f32_e32 v148, s35, v38
	v_fmac_f32_e32 v149, s35, v39
	v_fmac_f32_e32 v150, s35, v40
	v_fmac_f32_e32 v151, s35, v41
	s_waitcnt vmcnt(21)
	v_readlane_b32 s30, v132, 42
	v_readlane_b32 s31, v133, 42
	v_readlane_b32 s34, v134, 42
	v_readlane_b32 s35, v135, 42
	s_nop 1
	v_fmac_f32_e32 v136, s30, v42
	v_fmac_f32_e32 v137, s30, v43
	v_fmac_f32_e32 v138, s30, v44
	v_fmac_f32_e32 v139, s30, v45
	v_fmac_f32_e32 v140, s31, v42
	v_fmac_f32_e32 v141, s31, v43
	v_fmac_f32_e32 v142, s31, v44
	v_fmac_f32_e32 v143, s31, v45
	v_fmac_f32_e32 v144, s34, v42
	v_fmac_f32_e32 v145, s34, v43
	v_fmac_f32_e32 v146, s34, v44
	v_fmac_f32_e32 v147, s34, v45
	v_fmac_f32_e32 v148, s35, v42
	v_fmac_f32_e32 v149, s35, v43
	v_fmac_f32_e32 v150, s35, v44
	v_fmac_f32_e32 v151, s35, v45
	s_waitcnt vmcnt(20)
	v_readlane_b32 s30, v132, 43
	v_readlane_b32 s31, v133, 43
	v_readlane_b32 s34, v134, 43
	v_readlane_b32 s35, v135, 43
	s_nop 1
	v_fmac_f32_e32 v136, s30, v46
	v_fmac_f32_e32 v137, s30, v47
	v_fmac_f32_e32 v138, s30, v48
	v_fmac_f32_e32 v139, s30, v49
	v_fmac_f32_e32 v140, s31, v46
	v_fmac_f32_e32 v141, s31, v47
	v_fmac_f32_e32 v142, s31, v48
	v_fmac_f32_e32 v143, s31, v49
	v_fmac_f32_e32 v144, s34, v46
	v_fmac_f32_e32 v145, s34, v47
	v_fmac_f32_e32 v146, s34, v48
	v_fmac_f32_e32 v147, s34, v49
	v_fmac_f32_e32 v148, s35, v46
	v_fmac_f32_e32 v149, s35, v47
	v_fmac_f32_e32 v150, s35, v48
	v_fmac_f32_e32 v151, s35, v49
	s_waitcnt vmcnt(19)
	v_readlane_b32 s30, v132, 44
	v_readlane_b32 s31, v133, 44
	v_readlane_b32 s34, v134, 44
	v_readlane_b32 s35, v135, 44
	s_nop 1
	v_fmac_f32_e32 v136, s30, v50
	v_fmac_f32_e32 v137, s30, v51
	v_fmac_f32_e32 v138, s30, v52
	v_fmac_f32_e32 v139, s30, v53
	v_fmac_f32_e32 v140, s31, v50
	v_fmac_f32_e32 v141, s31, v51
	v_fmac_f32_e32 v142, s31, v52
	v_fmac_f32_e32 v143, s31, v53
	v_fmac_f32_e32 v144, s34, v50
	v_fmac_f32_e32 v145, s34, v51
	v_fmac_f32_e32 v146, s34, v52
	v_fmac_f32_e32 v147, s34, v53
	v_fmac_f32_e32 v148, s35, v50
	v_fmac_f32_e32 v149, s35, v51
	v_fmac_f32_e32 v150, s35, v52
	v_fmac_f32_e32 v151, s35, v53
	s_waitcnt vmcnt(18)
	v_readlane_b32 s30, v132, 45
	v_readlane_b32 s31, v133, 45
	v_readlane_b32 s34, v134, 45
	v_readlane_b32 s35, v135, 45
	s_nop 1
	v_fmac_f32_e32 v136, s30, v54
	v_fmac_f32_e32 v137, s30, v55
	v_fmac_f32_e32 v138, s30, v56
	v_fmac_f32_e32 v139, s30, v57
	v_fmac_f32_e32 v140, s31, v54
	v_fmac_f32_e32 v141, s31, v55
	v_fmac_f32_e32 v142, s31, v56
	v_fmac_f32_e32 v143, s31, v57
	v_fmac_f32_e32 v144, s34, v54
	v_fmac_f32_e32 v145, s34, v55
	v_fmac_f32_e32 v146, s34, v56
	v_fmac_f32_e32 v147, s34, v57
	v_fmac_f32_e32 v148, s35, v54
	v_fmac_f32_e32 v149, s35, v55
	v_fmac_f32_e32 v150, s35, v56
	v_fmac_f32_e32 v151, s35, v57
	s_waitcnt vmcnt(17)
	v_readlane_b32 s30, v132, 46
	v_readlane_b32 s31, v133, 46
	v_readlane_b32 s34, v134, 46
	v_readlane_b32 s35, v135, 46
	s_nop 1
	v_fmac_f32_e32 v136, s30, v58
	v_fmac_f32_e32 v137, s30, v59
	v_fmac_f32_e32 v138, s30, v60
	v_fmac_f32_e32 v139, s30, v61
	v_fmac_f32_e32 v140, s31, v58
	v_fmac_f32_e32 v141, s31, v59
	v_fmac_f32_e32 v142, s31, v60
	v_fmac_f32_e32 v143, s31, v61
	v_fmac_f32_e32 v144, s34, v58
	v_fmac_f32_e32 v145, s34, v59
	v_fmac_f32_e32 v146, s34, v60
	v_fmac_f32_e32 v147, s34, v61
	v_fmac_f32_e32 v148, s35, v58
	v_fmac_f32_e32 v149, s35, v59
	v_fmac_f32_e32 v150, s35, v60
	v_fmac_f32_e32 v151, s35, v61
	s_waitcnt vmcnt(16)
	v_readlane_b32 s30, v132, 47
	v_readlane_b32 s31, v133, 47
	v_readlane_b32 s34, v134, 47
	v_readlane_b32 s35, v135, 47
	s_nop 1
	v_fmac_f32_e32 v136, s30, v62
	v_fmac_f32_e32 v137, s30, v63
	v_fmac_f32_e32 v138, s30, v64
	v_fmac_f32_e32 v139, s30, v65
	v_fmac_f32_e32 v140, s31, v62
	v_fmac_f32_e32 v141, s31, v63
	v_fmac_f32_e32 v142, s31, v64
	v_fmac_f32_e32 v143, s31, v65
	v_fmac_f32_e32 v144, s34, v62
	v_fmac_f32_e32 v145, s34, v63
	v_fmac_f32_e32 v146, s34, v64
	v_fmac_f32_e32 v147, s34, v65
	v_fmac_f32_e32 v148, s35, v62
	v_fmac_f32_e32 v149, s35, v63
	v_fmac_f32_e32 v150, s35, v64
	v_fmac_f32_e32 v151, s35, v65
	s_waitcnt vmcnt(15)
	v_readlane_b32 s30, v132, 48
	v_readlane_b32 s31, v133, 48
	v_readlane_b32 s34, v134, 48
	v_readlane_b32 s35, v135, 48
	s_nop 1
	v_fmac_f32_e32 v136, s30, v66
	v_fmac_f32_e32 v137, s30, v67
	v_fmac_f32_e32 v138, s30, v68
	v_fmac_f32_e32 v139, s30, v69
	v_fmac_f32_e32 v140, s31, v66
	v_fmac_f32_e32 v141, s31, v67
	v_fmac_f32_e32 v142, s31, v68
	v_fmac_f32_e32 v143, s31, v69
	v_fmac_f32_e32 v144, s34, v66
	v_fmac_f32_e32 v145, s34, v67
	v_fmac_f32_e32 v146, s34, v68
	v_fmac_f32_e32 v147, s34, v69
	v_fmac_f32_e32 v148, s35, v66
	v_fmac_f32_e32 v149, s35, v67
	v_fmac_f32_e32 v150, s35, v68
	v_fmac_f32_e32 v151, s35, v69
	s_waitcnt vmcnt(14)
	v_readlane_b32 s30, v132, 49
	v_readlane_b32 s31, v133, 49
	v_readlane_b32 s34, v134, 49
	v_readlane_b32 s35, v135, 49
	s_nop 1
	v_fmac_f32_e32 v136, s30, v70
	v_fmac_f32_e32 v137, s30, v71
	v_fmac_f32_e32 v138, s30, v72
	v_fmac_f32_e32 v139, s30, v73
	v_fmac_f32_e32 v140, s31, v70
	v_fmac_f32_e32 v141, s31, v71
	v_fmac_f32_e32 v142, s31, v72
	v_fmac_f32_e32 v143, s31, v73
	v_fmac_f32_e32 v144, s34, v70
	v_fmac_f32_e32 v145, s34, v71
	v_fmac_f32_e32 v146, s34, v72
	v_fmac_f32_e32 v147, s34, v73
	v_fmac_f32_e32 v148, s35, v70
	v_fmac_f32_e32 v149, s35, v71
	v_fmac_f32_e32 v150, s35, v72
	v_fmac_f32_e32 v151, s35, v73
	s_waitcnt vmcnt(13)
	v_readlane_b32 s30, v132, 50
	v_readlane_b32 s31, v133, 50
	v_readlane_b32 s34, v134, 50
	v_readlane_b32 s35, v135, 50
	s_nop 1
	v_fmac_f32_e32 v136, s30, v74
	v_fmac_f32_e32 v137, s30, v75
	v_fmac_f32_e32 v138, s30, v76
	v_fmac_f32_e32 v139, s30, v77
	v_fmac_f32_e32 v140, s31, v74
	v_fmac_f32_e32 v141, s31, v75
	v_fmac_f32_e32 v142, s31, v76
	v_fmac_f32_e32 v143, s31, v77
	v_fmac_f32_e32 v144, s34, v74
	v_fmac_f32_e32 v145, s34, v75
	v_fmac_f32_e32 v146, s34, v76
	v_fmac_f32_e32 v147, s34, v77
	v_fmac_f32_e32 v148, s35, v74
	v_fmac_f32_e32 v149, s35, v75
	v_fmac_f32_e32 v150, s35, v76
	v_fmac_f32_e32 v151, s35, v77
	s_waitcnt vmcnt(12)
	v_readlane_b32 s30, v132, 51
	v_readlane_b32 s31, v133, 51
	v_readlane_b32 s34, v134, 51
	v_readlane_b32 s35, v135, 51
	s_nop 1
	v_fmac_f32_e32 v136, s30, v78
	v_fmac_f32_e32 v137, s30, v79
	v_fmac_f32_e32 v138, s30, v80
	v_fmac_f32_e32 v139, s30, v81
	v_fmac_f32_e32 v140, s31, v78
	v_fmac_f32_e32 v141, s31, v79
	v_fmac_f32_e32 v142, s31, v80
	v_fmac_f32_e32 v143, s31, v81
	v_fmac_f32_e32 v144, s34, v78
	v_fmac_f32_e32 v145, s34, v79
	v_fmac_f32_e32 v146, s34, v80
	v_fmac_f32_e32 v147, s34, v81
	v_fmac_f32_e32 v148, s35, v78
	v_fmac_f32_e32 v149, s35, v79
	v_fmac_f32_e32 v150, s35, v80
	v_fmac_f32_e32 v151, s35, v81
	s_waitcnt vmcnt(11)
	v_readlane_b32 s30, v132, 52
	v_readlane_b32 s31, v133, 52
	v_readlane_b32 s34, v134, 52
	v_readlane_b32 s35, v135, 52
	s_nop 1
	v_fmac_f32_e32 v136, s30, v82
	v_fmac_f32_e32 v137, s30, v83
	v_fmac_f32_e32 v138, s30, v84
	v_fmac_f32_e32 v139, s30, v85
	v_fmac_f32_e32 v140, s31, v82
	v_fmac_f32_e32 v141, s31, v83
	v_fmac_f32_e32 v142, s31, v84
	v_fmac_f32_e32 v143, s31, v85
	v_fmac_f32_e32 v144, s34, v82
	v_fmac_f32_e32 v145, s34, v83
	v_fmac_f32_e32 v146, s34, v84
	v_fmac_f32_e32 v147, s34, v85
	v_fmac_f32_e32 v148, s35, v82
	v_fmac_f32_e32 v149, s35, v83
	v_fmac_f32_e32 v150, s35, v84
	v_fmac_f32_e32 v151, s35, v85
	s_waitcnt vmcnt(10)
	v_readlane_b32 s30, v132, 53
	v_readlane_b32 s31, v133, 53
	v_readlane_b32 s34, v134, 53
	v_readlane_b32 s35, v135, 53
	s_nop 1
	v_fmac_f32_e32 v136, s30, v86
	v_fmac_f32_e32 v137, s30, v87
	v_fmac_f32_e32 v138, s30, v88
	v_fmac_f32_e32 v139, s30, v89
	v_fmac_f32_e32 v140, s31, v86
	v_fmac_f32_e32 v141, s31, v87
	v_fmac_f32_e32 v142, s31, v88
	v_fmac_f32_e32 v143, s31, v89
	v_fmac_f32_e32 v144, s34, v86
	v_fmac_f32_e32 v145, s34, v87
	v_fmac_f32_e32 v146, s34, v88
	v_fmac_f32_e32 v147, s34, v89
	v_fmac_f32_e32 v148, s35, v86
	v_fmac_f32_e32 v149, s35, v87
	v_fmac_f32_e32 v150, s35, v88
	v_fmac_f32_e32 v151, s35, v89
	s_waitcnt vmcnt(9)
	v_readlane_b32 s30, v132, 54
	v_readlane_b32 s31, v133, 54
	v_readlane_b32 s34, v134, 54
	v_readlane_b32 s35, v135, 54
	s_nop 1
	v_fmac_f32_e32 v136, s30, v90
	v_fmac_f32_e32 v137, s30, v91
	v_fmac_f32_e32 v138, s30, v92
	v_fmac_f32_e32 v139, s30, v93
	v_fmac_f32_e32 v140, s31, v90
	v_fmac_f32_e32 v141, s31, v91
	v_fmac_f32_e32 v142, s31, v92
	v_fmac_f32_e32 v143, s31, v93
	v_fmac_f32_e32 v144, s34, v90
	v_fmac_f32_e32 v145, s34, v91
	v_fmac_f32_e32 v146, s34, v92
	v_fmac_f32_e32 v147, s34, v93
	v_fmac_f32_e32 v148, s35, v90
	v_fmac_f32_e32 v149, s35, v91
	v_fmac_f32_e32 v150, s35, v92
	v_fmac_f32_e32 v151, s35, v93
	s_waitcnt vmcnt(8)
	v_readlane_b32 s30, v132, 55
	v_readlane_b32 s31, v133, 55
	v_readlane_b32 s34, v134, 55
	v_readlane_b32 s35, v135, 55
	s_nop 1
	v_fmac_f32_e32 v136, s30, v94
	v_fmac_f32_e32 v137, s30, v95
	v_fmac_f32_e32 v138, s30, v96
	v_fmac_f32_e32 v139, s30, v97
	v_fmac_f32_e32 v140, s31, v94
	v_fmac_f32_e32 v141, s31, v95
	v_fmac_f32_e32 v142, s31, v96
	v_fmac_f32_e32 v143, s31, v97
	v_fmac_f32_e32 v144, s34, v94
	v_fmac_f32_e32 v145, s34, v95
	v_fmac_f32_e32 v146, s34, v96
	v_fmac_f32_e32 v147, s34, v97
	v_fmac_f32_e32 v148, s35, v94
	v_fmac_f32_e32 v149, s35, v95
	v_fmac_f32_e32 v150, s35, v96
	v_fmac_f32_e32 v151, s35, v97
	s_waitcnt vmcnt(7)
	v_readlane_b32 s30, v132, 56
	v_readlane_b32 s31, v133, 56
	v_readlane_b32 s34, v134, 56
	v_readlane_b32 s35, v135, 56
	s_nop 1
	v_fmac_f32_e32 v136, s30, v98
	v_fmac_f32_e32 v137, s30, v99
	v_fmac_f32_e32 v138, s30, v100
	v_fmac_f32_e32 v139, s30, v101
	v_fmac_f32_e32 v140, s31, v98
	v_fmac_f32_e32 v141, s31, v99
	v_fmac_f32_e32 v142, s31, v100
	v_fmac_f32_e32 v143, s31, v101
	v_fmac_f32_e32 v144, s34, v98
	v_fmac_f32_e32 v145, s34, v99
	v_fmac_f32_e32 v146, s34, v100
	v_fmac_f32_e32 v147, s34, v101
	v_fmac_f32_e32 v148, s35, v98
	v_fmac_f32_e32 v149, s35, v99
	v_fmac_f32_e32 v150, s35, v100
	v_fmac_f32_e32 v151, s35, v101
	s_waitcnt vmcnt(6)
	v_readlane_b32 s30, v132, 57
	v_readlane_b32 s31, v133, 57
	v_readlane_b32 s34, v134, 57
	v_readlane_b32 s35, v135, 57
	s_nop 1
	v_fmac_f32_e32 v136, s30, v102
	v_fmac_f32_e32 v137, s30, v103
	v_fmac_f32_e32 v138, s30, v104
	v_fmac_f32_e32 v139, s30, v105
	v_fmac_f32_e32 v140, s31, v102
	v_fmac_f32_e32 v141, s31, v103
	v_fmac_f32_e32 v142, s31, v104
	v_fmac_f32_e32 v143, s31, v105
	v_fmac_f32_e32 v144, s34, v102
	v_fmac_f32_e32 v145, s34, v103
	v_fmac_f32_e32 v146, s34, v104
	v_fmac_f32_e32 v147, s34, v105
	v_fmac_f32_e32 v148, s35, v102
	v_fmac_f32_e32 v149, s35, v103
	v_fmac_f32_e32 v150, s35, v104
	v_fmac_f32_e32 v151, s35, v105
	s_waitcnt vmcnt(5)
	v_readlane_b32 s30, v132, 58
	v_readlane_b32 s31, v133, 58
	v_readlane_b32 s34, v134, 58
	v_readlane_b32 s35, v135, 58
	s_nop 1
	v_fmac_f32_e32 v136, s30, v106
	v_fmac_f32_e32 v137, s30, v107
	v_fmac_f32_e32 v138, s30, v108
	v_fmac_f32_e32 v139, s30, v109
	v_fmac_f32_e32 v140, s31, v106
	v_fmac_f32_e32 v141, s31, v107
	v_fmac_f32_e32 v142, s31, v108
	v_fmac_f32_e32 v143, s31, v109
	v_fmac_f32_e32 v144, s34, v106
	v_fmac_f32_e32 v145, s34, v107
	v_fmac_f32_e32 v146, s34, v108
	v_fmac_f32_e32 v147, s34, v109
	v_fmac_f32_e32 v148, s35, v106
	v_fmac_f32_e32 v149, s35, v107
	v_fmac_f32_e32 v150, s35, v108
	v_fmac_f32_e32 v151, s35, v109
	s_waitcnt vmcnt(4)
	v_readlane_b32 s30, v132, 59
	v_readlane_b32 s31, v133, 59
	v_readlane_b32 s34, v134, 59
	v_readlane_b32 s35, v135, 59
	s_nop 1
	v_fmac_f32_e32 v136, s30, v110
	v_fmac_f32_e32 v137, s30, v111
	v_fmac_f32_e32 v138, s30, v112
	v_fmac_f32_e32 v139, s30, v113
	v_fmac_f32_e32 v140, s31, v110
	v_fmac_f32_e32 v141, s31, v111
	v_fmac_f32_e32 v142, s31, v112
	v_fmac_f32_e32 v143, s31, v113
	v_fmac_f32_e32 v144, s34, v110
	v_fmac_f32_e32 v145, s34, v111
	v_fmac_f32_e32 v146, s34, v112
	v_fmac_f32_e32 v147, s34, v113
	v_fmac_f32_e32 v148, s35, v110
	v_fmac_f32_e32 v149, s35, v111
	v_fmac_f32_e32 v150, s35, v112
	v_fmac_f32_e32 v151, s35, v113
	s_waitcnt vmcnt(3)
	v_readlane_b32 s30, v132, 60
	v_readlane_b32 s31, v133, 60
	v_readlane_b32 s34, v134, 60
	v_readlane_b32 s35, v135, 60
	s_nop 1
	v_fmac_f32_e32 v136, s30, v114
	v_fmac_f32_e32 v137, s30, v115
	v_fmac_f32_e32 v138, s30, v116
	v_fmac_f32_e32 v139, s30, v117
	v_fmac_f32_e32 v140, s31, v114
	v_fmac_f32_e32 v141, s31, v115
	v_fmac_f32_e32 v142, s31, v116
	v_fmac_f32_e32 v143, s31, v117
	v_fmac_f32_e32 v144, s34, v114
	v_fmac_f32_e32 v145, s34, v115
	v_fmac_f32_e32 v146, s34, v116
	v_fmac_f32_e32 v147, s34, v117
	v_fmac_f32_e32 v148, s35, v114
	v_fmac_f32_e32 v149, s35, v115
	v_fmac_f32_e32 v150, s35, v116
	v_fmac_f32_e32 v151, s35, v117
	s_waitcnt vmcnt(2)
	v_readlane_b32 s30, v132, 61
	v_readlane_b32 s31, v133, 61
	v_readlane_b32 s34, v134, 61
	v_readlane_b32 s35, v135, 61
	s_nop 1
	v_fmac_f32_e32 v136, s30, v118
	v_fmac_f32_e32 v137, s30, v119
	v_fmac_f32_e32 v138, s30, v120
	v_fmac_f32_e32 v139, s30, v121
	v_fmac_f32_e32 v140, s31, v118
	v_fmac_f32_e32 v141, s31, v119
	v_fmac_f32_e32 v142, s31, v120
	v_fmac_f32_e32 v143, s31, v121
	v_fmac_f32_e32 v144, s34, v118
	v_fmac_f32_e32 v145, s34, v119
	v_fmac_f32_e32 v146, s34, v120
	v_fmac_f32_e32 v147, s34, v121
	v_fmac_f32_e32 v148, s35, v118
	v_fmac_f32_e32 v149, s35, v119
	v_fmac_f32_e32 v150, s35, v120
	v_fmac_f32_e32 v151, s35, v121
	s_waitcnt vmcnt(1)
	v_readlane_b32 s30, v132, 62
	v_readlane_b32 s31, v133, 62
	v_readlane_b32 s34, v134, 62
	v_readlane_b32 s35, v135, 62
	s_nop 1
	v_fmac_f32_e32 v136, s30, v122
	v_fmac_f32_e32 v137, s30, v123
	v_fmac_f32_e32 v138, s30, v124
	v_fmac_f32_e32 v139, s30, v125
	v_fmac_f32_e32 v140, s31, v122
	v_fmac_f32_e32 v141, s31, v123
	v_fmac_f32_e32 v142, s31, v124
	v_fmac_f32_e32 v143, s31, v125
	v_fmac_f32_e32 v144, s34, v122
	v_fmac_f32_e32 v145, s34, v123
	v_fmac_f32_e32 v146, s34, v124
	v_fmac_f32_e32 v147, s34, v125
	v_fmac_f32_e32 v148, s35, v122
	v_fmac_f32_e32 v149, s35, v123
	v_fmac_f32_e32 v150, s35, v124
	v_fmac_f32_e32 v151, s35, v125
	s_waitcnt vmcnt(0)
	v_readlane_b32 s30, v132, 63
	v_readlane_b32 s31, v133, 63
	v_readlane_b32 s34, v134, 63
	v_readlane_b32 s35, v135, 63
	s_nop 1
	v_fmac_f32_e32 v136, s30, v126
	v_fmac_f32_e32 v137, s30, v127
	v_fmac_f32_e32 v138, s30, v128
	v_fmac_f32_e32 v139, s30, v129
	v_fmac_f32_e32 v140, s31, v126
	v_fmac_f32_e32 v141, s31, v127
	v_fmac_f32_e32 v142, s31, v128
	v_fmac_f32_e32 v143, s31, v129
	v_fmac_f32_e32 v144, s34, v126
	v_fmac_f32_e32 v145, s34, v127
	v_fmac_f32_e32 v146, s34, v128
	v_fmac_f32_e32 v147, s34, v129
	v_fmac_f32_e32 v148, s35, v126
	v_fmac_f32_e32 v149, s35, v127
	v_fmac_f32_e32 v150, s35, v128
	v_fmac_f32_e32 v151, s35, v129
	s_lshl_b32 s37, s51, 12
	v_add_u32_e32 v168, s37, v131
	ds_write_b128 v168, v[136:139] offset:34816
	ds_write_b128 v168, v[140:143] offset:35840
	ds_write_b128 v168, v[144:147] offset:36864
	ds_write_b128 v168, v[148:151] offset:37888
	s_waitcnt lgkmcnt(0)
	s_barrier
	s_lshl_b32 s37, s51, 10
	v_add_u32_e32 v168, s37, v131
	ds_read_b128 v[2:5], v168 offset:34816
	ds_read_b128 v[6:9], v168 offset:38912
	ds_read_b128 v[10:13], v168 offset:43008
	ds_read_b128 v[14:17], v168 offset:47104
	s_mul_i32 s37, s26, 0x6000
	s_lshl_b32 s43, s27, 2
	s_add_i32 s37, s37, s43
	s_add_u32 s54, s54, s37
	s_addc_u32 s55, s55, 0
	v_mov_b32_e32 v136, 0
	v_mov_b32_e32 v137, 0
	v_mov_b32_e32 v138, 0
	v_mov_b32_e32 v139, 0
	s_cmp_eq_u32 s28, 0
	s_cbranch_scc0 .Lmd_nob
	global_load_dwordx4 v[136:139], v131, s[54:55]
.Lmd_nob:
	s_lshl_b32 s37, s26, 2
	s_add_i32 s37, s37, s51
	s_mul_i32 s37, s37, 0x6000
	s_add_i32 s37, s37, s43
	s_mul_i32 s43, s28, 0x30000
	s_add_i32 s37, s37, s43
	s_add_u32 s56, s56, s37
	s_addc_u32 s57, s57, 0
	s_waitcnt lgkmcnt(0)
	v_add_f32_e32 v2, v2, v6
	v_add_f32_e32 v10, v10, v14
	v_add_f32_e32 v3, v3, v7
	v_add_f32_e32 v11, v11, v15
	v_add_f32_e32 v4, v4, v8
	v_add_f32_e32 v12, v12, v16
	v_add_f32_e32 v5, v5, v9
	v_add_f32_e32 v13, v13, v17
	v_add_f32_e32 v2, v2, v10
	v_add_f32_e32 v3, v3, v11
	v_add_f32_e32 v4, v4, v12
	v_add_f32_e32 v5, v5, v13
	s_waitcnt vmcnt(0)
	v_add_f32_e32 v2, v2, v136
	v_add_f32_e32 v3, v3, v137
	v_add_f32_e32 v4, v4, v138
	v_add_f32_e32 v5, v5, v139
	global_store_dwordx4 v131, v[2:5], s[56:57]
	s_barrier
	v_mov_b32_e32 v98, 0x4800
	v_mov_b32_e32 v100, 0x4804
	v_mov_b32_e32 v102, 0x4808
	v_mov_b32_e32 v104, 0x480c
	s_branch .Lcv_p0b
.Lcv_p0a:
	s_mov_b32 s28, 0
	s_mov_b32 s29, 0
	s_add_i32 s26, s3, 0xffffff40
	s_add_i32 s27, s71, 0xffffff40
	s_lshl_b32 s89, s27, 3
	s_branch .Lcv_go
.Lcv_p0b:
	s_mov_b32 s28, 0
	s_mov_b32 s29, 2
	s_add_i32 s37, s71, 0xffffff40
	s_lshl_b32 s37, s37, 1
	s_add_i32 s26, s3, s37
	s_mov_b32 s27, s71
	s_movk_i32 s89, 0x1a00
	s_branch .Lcv_go
.Lcv_p10:
	s_mov_b32 s28, 1
	s_mov_b32 s29, 1
	s_mov_b32 s26, s3
	s_mov_b32 s27, s71
	s_movk_i32 s89, 0x1a00
.Lcv_go:
	s_load_dwordx2 s[54:55], s[0:1], 0x30
	s_load_dwordx2 s[56:57], s[0:1], 0x58
	s_load_dwordx2 s[58:59], s[0:1], 0x70
	s_load_dwordx2 s[60:61], s[0:1], 0x88
	s_load_dwordx2 s[92:93], s[0:1], 0x98
	s_load_dwordx2 s[96:97], s[0:1], 0xa0
	s_load_dwordx2 s[62:63], s[0:1], 0xa8
	s_load_dwordx2 s[48:49], s[0:1], 0xb0
	v_and_b32_e32 v34, 63, v154
	v_lshrrev_b32_e32 v35, 6, v154
	s_nop 0
	v_readfirstlane_b32 s51, v35
	v_lshrrev_b32_e32 v35, 4, v34
	v_and_b32_e32 v36, 15, v34
	s_nop 0
	s_lshl_b32 s26, s26, 2
	s_add_i32 s26, s26, s51
	s_lshl_b32 s27, s27, 2
	s_mulk_i32 s51, 8704
	v_mul_u32_u24_e32 v46, 272, v35
	v_lshl_add_u32 v46, v36, 4, v46
	v_add_u32_e32 v46, s51, v46
	v_lshl_add_u32 v47, v34, 2, s51
	s_waitcnt lgkmcnt(0)
	s_cmp_lt_u32 s26, s89
	s_cbranch_scc0 .Lcv_done
.Lcv_again:
	s_cmpk_lt_u32 s26, 0x780
	s_cbranch_scc0 .Lcv_m1a
	s_mul_hi_u32 s34, s26, 0x4444445
	s_mul_i32 s37, s34, 60
	s_sub_i32 s35, s26, s37
	s_mov_b64 s[38:39], s[54:55]
	s_mov_b64 s[40:41], s[92:93]
	s_mov_b32 s43, 0xe90000
	s_movk_i32 s36, 0x3a40
	s_mov_b32 s37, 0x3c000
	s_movk_i32 s32, 0
	s_branch .Lcv_deca
.Lcv_m1a:
	s_cmpk_lt_u32 s26, 0x980
	s_cbranch_scc0 .Lcv_m2a
	s_add_i32 s37, s26, 0xfffff880
	s_lshr_b32 s34, s37, 4
	s_and_b32 s35, s37, 15
	s_mov_b64 s[38:39], s[56:57]
	s_mov_b64 s[40:41], s[96:97]
	s_mov_b32 s43, 0x400000
	s_movk_i32 s36, 0x1000
	s_movk_i32 s37, 64
	s_movk_i32 s32, 1
	s_branch .Lcv_deca
.Lcv_m2a:
	s_cmpk_lt_u32 s26, 0x1480
	s_cbranch_scc0 .Lcv_m3a
	s_add_i32 s37, s26, 0xfffff680
	s_mul_hi_u32 s34, s37, 0x2e8ba2f
	s_mul_i32 s35, s34, 88
	s_sub_i32 s35, s37, s35
	s_mov_b64 s[38:39], s[58:59]
	s_mov_b64 s[40:41], s[62:63]
	s_mov_b32 s43, 0x1600000
	s_movk_i32 s36, 0x5800
	s_mov_b32 s37, 0x58000
	s_movk_i32 s32, 2
	s_branch .Lcv_deca
.Lcv_m3a:
	s_add_i32 s37, s26, 0xffffeb80
	s_lshr_b32 s34, s37, 4
	s_and_b32 s35, s37, 15
	s_mov_b64 s[38:39], s[60:61]
	s_mov_b64 s[40:41], s[48:49]
	s_mov_b32 s43, 0xb00000
	s_movk_i32 s36, 0x1000
	s_mov_b32 s37, 0x10000
	s_movk_i32 s32, 3
.Lcv_deca:
	s_mul_i32 s37, s37, s34
	s_cmp_eq_u32 s32, 1
	s_cselect_b32 s42, 0x800, 64
	s_lshl_b32 s53, s35, 6
	s_mul_i32 s53, s53, s42
	s_add_i32 s37, s37, s53
	v_mul_lo_u32 v48, v34, s42
	s_add_u32 s40, s40, s37
	s_addc_u32 s41, s41, 0
	s_mul_i32 s43, s43, s28
	s_lshl_b32 s52, s34, 5
	s_mul_i32 s52, s52, s36
	s_add_u32 s43, s43, s52
	s_add_u32 s38, s38, s43
	s_addc_u32 s39, s39, 0
	v_lshlrev_b32_e32 v37, 2, v36
	s_cmp_eq_u32 s32, 2
	s_cbranch_scc1 .Lcv_upa
	s_lshl_b32 s52, s35, 6
	v_add_u32_e32 v37, s52, v37
	s_branch .Lcv_cola
.Lcv_upa:
	s_lshl_b32 s52, s35, 5
	v_add_u32_e32 v37, s52, v37
	v_cmp_lt_u32_e32 vcc, 7, v36
	v_mov_b32_e32 v38, 0xae0
	s_nop 1
	v_cndmask_b32_e32 v38, 0, v38, vcc
	v_add_u32_e32 v37, v38, v37
.Lcv_cola:
	v_mul_lo_u32 v38, v35, s36
	v_lshl_add_u32 v38, v37, 2, v38
	s_lshl_b32 s52, s36, 2
	v_add_u32_e32 v39, s52, v38
	v_add_u32_e32 v40, s52, v39
	v_add_u32_e32 v41, s52, v40
	v_add_u32_e32 v42, s52, v41
	v_add_u32_e32 v43, s52, v42
	v_add_u32_e32 v44, s52, v43
	v_add_u32_e32 v45, s52, v44
	v_mov_b32_e32 v2, 0
	v_mov_b32_e32 v3, 0
	v_mov_b32_e32 v4, 0
	v_mov_b32_e32 v5, 0
	v_mov_b32_e32 v6, 0
	v_mov_b32_e32 v7, 0
	v_mov_b32_e32 v8, 0
	v_mov_b32_e32 v9, 0
	v_mov_b32_e32 v10, 0
	v_mov_b32_e32 v11, 0
	v_mov_b32_e32 v12, 0
	v_mov_b32_e32 v13, 0
	v_mov_b32_e32 v14, 0
	v_mov_b32_e32 v15, 0
	v_mov_b32_e32 v16, 0
	v_mov_b32_e32 v17, 0
	v_mov_b32_e32 v18, 0
	v_mov_b32_e32 v19, 0
	v_mov_b32_e32 v20, 0
	v_mov_b32_e32 v21, 0
	v_mov_b32_e32 v22, 0
	v_mov_b32_e32 v23, 0
	v_mov_b32_e32 v24, 0
	v_mov_b32_e32 v25, 0
	v_mov_b32_e32 v26, 0
	v_mov_b32_e32 v27, 0
	v_mov_b32_e32 v28, 0
	v_mov_b32_e32 v29, 0
	v_mov_b32_e32 v30, 0
	v_mov_b32_e32 v31, 0
	v_mov_b32_e32 v32, 0
	v_mov_b32_e32 v33, 0
	s_mov_b32 s52, 0x7fffffff
	s_cmp_eq_u32 s32, 0
	s_cselect_b32 s52, 0xe90, s52
	v_cmp_gt_u32_e32 vcc, s52, v37
	s_and_saveexec_b64 s[30:31], vcc
	global_load_dwordx4 v[2:5], v38, s[38:39] nt
	global_load_dwordx4 v[6:9], v39, s[38:39] nt
	global_load_dwordx4 v[10:13], v40, s[38:39] nt
	global_load_dwordx4 v[14:17], v41, s[38:39] nt
	global_load_dwordx4 v[18:21], v42, s[38:39] nt
	global_load_dwordx4 v[22:25], v43, s[38:39] nt
	global_load_dwordx4 v[26:29], v44, s[38:39] nt
	global_load_dwordx4 v[30:33], v45, s[38:39] nt
	s_mov_b64 exec, s[30:31]
	s_add_i32 s26, s26, s27
	s_waitcnt vmcnt(0)
	s_branch .Lcv_mid
.Lcv_top:
	s_waitcnt vmcnt(4)
.Lcv_mid:
	v_mov_b32_e32 v114, v2
	v_mov_b32_e32 v115, v3
	v_mov_b32_e32 v116, v4
	v_mov_b32_e32 v117, v5
	v_mov_b32_e32 v118, v6
	v_mov_b32_e32 v119, v7
	v_mov_b32_e32 v120, v8
	v_mov_b32_e32 v121, v9
	v_mov_b32_e32 v122, v10
	v_mov_b32_e32 v123, v11
	v_mov_b32_e32 v124, v12
	v_mov_b32_e32 v125, v13
	v_mov_b32_e32 v126, v14
	v_mov_b32_e32 v127, v15
	v_mov_b32_e32 v128, v16
	v_mov_b32_e32 v129, v17
	v_mov_b32_e32 v130, v18
	v_mov_b32_e32 v131, v19
	v_mov_b32_e32 v132, v20
	v_mov_b32_e32 v133, v21
	v_mov_b32_e32 v134, v22
	v_mov_b32_e32 v135, v23
	v_mov_b32_e32 v136, v24
	v_mov_b32_e32 v137, v25
	v_mov_b32_e32 v138, v26
	v_mov_b32_e32 v139, v27
	v_mov_b32_e32 v140, v28
	v_mov_b32_e32 v141, v29
	v_mov_b32_e32 v142, v30
	v_mov_b32_e32 v143, v31
	v_mov_b32_e32 v144, v32
	v_mov_b32_e32 v145, v33
	v_mov_b32_e32 v49, v48
	s_mov_b64 s[82:83], s[40:41]
	s_cmp_lt_u32 s26, s89
	s_cselect_b32 s43, 1, 0
	s_cbranch_scc0 .Lcv_proc
	s_cmpk_lt_u32 s26, 0x780
	s_cbranch_scc0 .Lcv_m1b
	s_mul_hi_u32 s34, s26, 0x4444445
	s_mul_i32 s37, s34, 60
	s_sub_i32 s35, s26, s37
	s_mov_b64 s[38:39], s[54:55]
	s_mov_b64 s[40:41], s[92:93]
	s_mov_b32 s43, 0xe90000
	s_movk_i32 s36, 0x3a40
	s_mov_b32 s37, 0x3c000
	s_movk_i32 s32, 0
	s_branch .Lcv_decb

.Lcv_colb:
	v_mul_lo_u32 v38, v35, s36
	v_lshl_add_u32 v38, v37, 2, v38
	s_lshl_b32 s52, s36, 2
	v_add_u32_e32 v39, s52, v38
	v_add_u32_e32 v40, s52, v39
	v_add_u32_e32 v41, s52, v40
	v_add_u32_e32 v42, s52, v41
	v_add_u32_e32 v43, s52, v42
	v_add_u32_e32 v44, s52, v43
	v_add_u32_e32 v45, s52, v44
	v_mov_b32_e32 v2, 0
	v_mov_b32_e32 v3, 0
	v_mov_b32_e32 v4, 0
	v_mov_b32_e32 v5, 0
	v_mov_b32_e32 v6, 0
	v_mov_b32_e32 v7, 0
	v_mov_b32_e32 v8, 0
	v_mov_b32_e32 v9, 0
	v_mov_b32_e32 v10, 0
	v_mov_b32_e32 v11, 0
	v_mov_b32_e32 v12, 0
	v_mov_b32_e32 v13, 0
	v_mov_b32_e32 v14, 0
	v_mov_b32_e32 v15, 0
	v_mov_b32_e32 v16, 0
	v_mov_b32_e32 v17, 0
	v_mov_b32_e32 v18, 0
	v_mov_b32_e32 v19, 0
	v_mov_b32_e32 v20, 0
	v_mov_b32_e32 v21, 0
	v_mov_b32_e32 v22, 0
	v_mov_b32_e32 v23, 0
	v_mov_b32_e32 v24, 0
	v_mov_b32_e32 v25, 0
	v_mov_b32_e32 v26, 0
	v_mov_b32_e32 v27, 0
	v_mov_b32_e32 v28, 0
	v_mov_b32_e32 v29, 0
	v_mov_b32_e32 v30, 0
	v_mov_b32_e32 v31, 0
	v_mov_b32_e32 v32, 0
	v_mov_b32_e32 v33, 0
	s_mov_b32 s52, 0x7fffffff
	s_cmp_eq_u32 s32, 0
	s_cselect_b32 s52, 0xe90, s52
	v_cmp_gt_u32_e32 vcc, s52, v37
	s_and_saveexec_b64 s[30:31], vcc
	global_load_dwordx4 v[2:5], v38, s[38:39] nt
	global_load_dwordx4 v[6:9], v39, s[38:39] nt
	global_load_dwordx4 v[10:13], v40, s[38:39] nt
	global_load_dwordx4 v[14:17], v41, s[38:39] nt
	global_load_dwordx4 v[18:21], v42, s[38:39] nt
	global_load_dwordx4 v[22:25], v43, s[38:39] nt
	global_load_dwordx4 v[26:29], v44, s[38:39] nt
	global_load_dwordx4 v[30:33], v45, s[38:39] nt
	s_mov_b64 exec, s[30:31]
	s_add_i32 s26, s26, s27
	s_mov_b32 s43, 1
.Lcv_proc:
	ds_write_b128 v46, v[114:117] offset:0
	ds_write_b128 v46, v[118:121] offset:1088
	ds_write_b128 v46, v[122:125] offset:2176
	ds_write_b128 v46, v[126:129] offset:3264
	ds_write_b128 v46, v[130:133] offset:4352
	ds_write_b128 v46, v[134:137] offset:5440
	ds_write_b128 v46, v[138:141] offset:6528
	ds_write_b128 v46, v[142:145] offset:7616
	ds_read_b32 v50, v47 offset:0
	ds_read_b32 v51, v47 offset:272
	ds_read_b32 v52, v47 offset:544
	ds_read_b32 v53, v47 offset:816
	ds_read_b32 v54, v47 offset:1088
	ds_read_b32 v55, v47 offset:1360
	ds_read_b32 v56, v47 offset:1632
	ds_read_b32 v57, v47 offset:1904
	ds_read_b32 v58, v47 offset:2176
	ds_read_b32 v59, v47 offset:2448
	ds_read_b32 v60, v47 offset:2720
	ds_read_b32 v61, v47 offset:2992
	ds_read_b32 v62, v47 offset:3264
	ds_read_b32 v63, v47 offset:3536
	ds_read_b32 v64, v47 offset:3808
	ds_read_b32 v65, v47 offset:4080
	ds_read_b32 v66, v47 offset:4352
	ds_read_b32 v67, v47 offset:4624
	ds_read_b32 v68, v47 offset:4896
	ds_read_b32 v69, v47 offset:5168
	ds_read_b32 v70, v47 offset:5440
	ds_read_b32 v71, v47 offset:5712
	ds_read_b32 v72, v47 offset:5984
	ds_read_b32 v73, v47 offset:6256
	ds_read_b32 v74, v47 offset:6528
	ds_read_b32 v75, v47 offset:6800
	ds_read_b32 v76, v47 offset:7072
	ds_read_b32 v77, v47 offset:7344
	ds_read_b32 v78, v47 offset:7616
	ds_read_b32 v79, v47 offset:7888
	ds_read_b32 v80, v47 offset:8160
	ds_read_b32 v81, v47 offset:8432
	s_waitcnt lgkmcnt(0)
	v_cvt_pk_bf16_f32 v50, v50, v51
	v_cvt_pk_bf16_f32 v51, v52, v53
	v_cvt_pk_bf16_f32 v52, v54, v55
	v_cvt_pk_bf16_f32 v53, v56, v57
	v_cvt_pk_bf16_f32 v54, v58, v59
	v_cvt_pk_bf16_f32 v55, v60, v61
	v_cvt_pk_bf16_f32 v56, v62, v63
	v_cvt_pk_bf16_f32 v57, v64, v65
	v_cvt_pk_bf16_f32 v58, v66, v67
	v_cvt_pk_bf16_f32 v59, v68, v69
	v_cvt_pk_bf16_f32 v60, v70, v71
	v_cvt_pk_bf16_f32 v61, v72, v73
	v_cvt_pk_bf16_f32 v62, v74, v75
	v_cvt_pk_bf16_f32 v63, v76, v77
	v_cvt_pk_bf16_f32 v64, v78, v79
	v_cvt_pk_bf16_f32 v65, v80, v81
	global_store_dwordx4 v49, v[50:53], s[82:83]
	global_store_dwordx4 v49, v[54:57], s[82:83] offset:16
	global_store_dwordx4 v49, v[58:61], s[82:83] offset:32
	global_store_dwordx4 v49, v[62:65], s[82:83] offset:48
	s_cmp_lg_u32 s43, 0
	s_cbranch_scc1 .Lcv_top
.Lcv_done:
	s_cmp_eq_u32 s29, 0
	s_cbranch_scc1 .Lcv_p0b
	s_cmp_eq_u32 s29, 1
	s_cbranch_scc1 .LBB0_518
	s_branch .LBB0_435

.Lgy_nn_a:
	s_waitcnt vmcnt(6) lgkmcnt(0)
	s_barrier
	v_add_u32_e32 v240, s61, v238
	v_add_u32_e32 v241, s61, v239
	s_add_i32 m0, s60, s62
	v_mfma_f32_16x16x32_bf16 v[2:5], v[162:165], v[130:133], 0
	global_load_lds_dwordx4 v226, s[54:55]
	v_mfma_f32_16x16x32_bf16 v[6:9], v[166:169], v[130:133], 0
	global_load_lds_dwordx4 v226, s[54:55] offset:1024
	v_mfma_f32_16x16x32_bf16 v[10:13], v[170:173], v[130:133], 0
	global_load_lds_dwordx4 v226, s[54:55] offset:2048
	v_mfma_f32_16x16x32_bf16 v[14:17], v[174:177], v[130:133], 0
	global_load_lds_dwordx4 v226, s[54:55] offset:3072
	s_add_i32 m0, s60, s63
	v_mfma_f32_16x16x32_bf16 v[18:21], v[162:165], v[134:137], 0
	global_load_lds_dwordx4 v230, s[56:57]
	v_mfma_f32_16x16x32_bf16 v[22:25], v[166:169], v[134:137], 0
	global_load_lds_dwordx4 v231, s[56:57] offset:1024
	v_mfma_f32_16x16x32_bf16 v[26:29], v[170:173], v[134:137], 0
	v_mfma_f32_16x16x32_bf16 v[30:33], v[174:177], v[134:137], 0
	v_mfma_f32_16x16x32_bf16 v[34:37], v[162:165], v[138:141], 0
	ds_read_b128 v[210:213], v241 offset:0
	v_mfma_f32_16x16x32_bf16 v[38:41], v[166:169], v[138:141], 0
	ds_read_b128 v[214:217], v241 offset:256
	v_mfma_f32_16x16x32_bf16 v[42:45], v[170:173], v[138:141], 0
	ds_read_b128 v[218:221], v241 offset:512
	v_mfma_f32_16x16x32_bf16 v[46:49], v[174:177], v[138:141], 0
	ds_read_b128 v[222:225], v241 offset:768
	v_mfma_f32_16x16x32_bf16 v[50:53], v[162:165], v[142:145], 0
	ds_read_b128 v[178:181], v240 offset:0
	v_mfma_f32_16x16x32_bf16 v[54:57], v[166:169], v[142:145], 0
	ds_read_b128 v[182:185], v240 offset:1024
	v_mfma_f32_16x16x32_bf16 v[58:61], v[170:173], v[142:145], 0
	ds_read_b128 v[186:189], v240 offset:2048
	v_mfma_f32_16x16x32_bf16 v[62:65], v[174:177], v[142:145], 0
	ds_read_b128 v[190:193], v240 offset:3072
	v_mfma_f32_16x16x32_bf16 v[66:69], v[162:165], v[146:149], 0
	ds_read_b128 v[194:197], v240 offset:4096
	v_mfma_f32_16x16x32_bf16 v[70:73], v[166:169], v[146:149], 0
	ds_read_b128 v[198:201], v240 offset:5120
	v_mfma_f32_16x16x32_bf16 v[74:77], v[170:173], v[146:149], 0
	ds_read_b128 v[202:205], v240 offset:6144
	v_mfma_f32_16x16x32_bf16 v[78:81], v[174:177], v[146:149], 0
	ds_read_b128 v[206:209], v240 offset:7168
	s_setprio 1
	v_mfma_f32_16x16x32_bf16 v[82:85], v[162:165], v[150:153], 0
	v_mfma_f32_16x16x32_bf16 v[86:89], v[166:169], v[150:153], 0
	v_mfma_f32_16x16x32_bf16 v[90:93], v[170:173], v[150:153], 0
	v_mfma_f32_16x16x32_bf16 v[94:97], v[174:177], v[150:153], 0
	v_mfma_f32_16x16x32_bf16 v[98:101], v[162:165], v[154:157], 0
	v_mfma_f32_16x16x32_bf16 v[102:105], v[166:169], v[154:157], 0
	v_mfma_f32_16x16x32_bf16 v[106:109], v[170:173], v[154:157], 0
	v_mfma_f32_16x16x32_bf16 v[110:113], v[174:177], v[154:157], 0
	v_mfma_f32_16x16x32_bf16 v[114:117], v[162:165], v[158:161], 0
	v_mfma_f32_16x16x32_bf16 v[118:121], v[166:169], v[158:161], 0
	v_mfma_f32_16x16x32_bf16 v[122:125], v[170:173], v[158:161], 0
	v_mfma_f32_16x16x32_bf16 v[126:129], v[174:177], v[158:161], 0
	s_setprio 0
	s_add_i32 s60, s60, 0x6000
	s_cmp_eq_u32 s60, 0x12000
	s_cselect_b32 s60, 0, s60
	s_add_u32 s54, s54, s72
	s_addc_u32 s55, s55, 0
	s_add_u32 s56, s56, s73
	s_addc_u32 s57, s57, 0
	s_add_i32 s61, s61, 0x6000
	s_cmp_eq_u32 s61, 0x12000
	s_cselect_b32 s61, 0, s61
	s_waitcnt vmcnt(6) lgkmcnt(0)
	s_barrier
	v_add_u32_e32 v240, s61, v238
	v_add_u32_e32 v241, s61, v239
	s_add_i32 m0, s60, s62
	v_mfma_f32_16x16x32_bf16 v[2:5], v[210:213], v[178:181], v[2:5]
	global_load_lds_dwordx4 v226, s[54:55]
	v_mfma_f32_16x16x32_bf16 v[6:9], v[214:217], v[178:181], v[6:9]
	global_load_lds_dwordx4 v226, s[54:55] offset:1024
	v_mfma_f32_16x16x32_bf16 v[10:13], v[218:221], v[178:181], v[10:13]
	global_load_lds_dwordx4 v226, s[54:55] offset:2048
	v_mfma_f32_16x16x32_bf16 v[14:17], v[222:225], v[178:181], v[14:17]
	global_load_lds_dwordx4 v226, s[54:55] offset:3072
	s_add_i32 m0, s60, s63
	v_mfma_f32_16x16x32_bf16 v[18:21], v[210:213], v[182:185], v[18:21]
	global_load_lds_dwordx4 v230, s[56:57]
	v_mfma_f32_16x16x32_bf16 v[22:25], v[214:217], v[182:185], v[22:25]
	global_load_lds_dwordx4 v231, s[56:57] offset:1024
	v_mfma_f32_16x16x32_bf16 v[26:29], v[218:221], v[182:185], v[26:29]
	v_mfma_f32_16x16x32_bf16 v[30:33], v[222:225], v[182:185], v[30:33]
	v_mfma_f32_16x16x32_bf16 v[34:37], v[210:213], v[186:189], v[34:37]
	ds_read_b128 v[162:165], v241 offset:0
	v_mfma_f32_16x16x32_bf16 v[38:41], v[214:217], v[186:189], v[38:41]
	ds_read_b128 v[166:169], v241 offset:256
	v_mfma_f32_16x16x32_bf16 v[42:45], v[218:221], v[186:189], v[42:45]
	ds_read_b128 v[170:173], v241 offset:512
	v_mfma_f32_16x16x32_bf16 v[46:49], v[222:225], v[186:189], v[46:49]
	ds_read_b128 v[174:177], v241 offset:768
	v_mfma_f32_16x16x32_bf16 v[50:53], v[210:213], v[190:193], v[50:53]
	ds_read_b128 v[130:133], v240 offset:0
	v_mfma_f32_16x16x32_bf16 v[54:57], v[214:217], v[190:193], v[54:57]
	ds_read_b128 v[134:137], v240 offset:1024
	v_mfma_f32_16x16x32_bf16 v[58:61], v[218:221], v[190:193], v[58:61]
	ds_read_b128 v[138:141], v240 offset:2048
	v_mfma_f32_16x16x32_bf16 v[62:65], v[222:225], v[190:193], v[62:65]
	ds_read_b128 v[142:145], v240 offset:3072
	v_mfma_f32_16x16x32_bf16 v[66:69], v[210:213], v[194:197], v[66:69]
	ds_read_b128 v[146:149], v240 offset:4096
	v_mfma_f32_16x16x32_bf16 v[70:73], v[214:217], v[194:197], v[70:73]
	ds_read_b128 v[150:153], v240 offset:5120
	v_mfma_f32_16x16x32_bf16 v[74:77], v[218:221], v[194:197], v[74:77]
	ds_read_b128 v[154:157], v240 offset:6144
	v_mfma_f32_16x16x32_bf16 v[78:81], v[222:225], v[194:197], v[78:81]
	ds_read_b128 v[158:161], v240 offset:7168
	s_setprio 1
	v_mfma_f32_16x16x32_bf16 v[82:85], v[210:213], v[198:201], v[82:85]
	v_mfma_f32_16x16x32_bf16 v[86:89], v[214:217], v[198:201], v[86:89]
	v_mfma_f32_16x16x32_bf16 v[90:93], v[218:221], v[198:201], v[90:93]
	v_mfma_f32_16x16x32_bf16 v[94:97], v[222:225], v[198:201], v[94:97]
	v_mfma_f32_16x16x32_bf16 v[98:101], v[210:213], v[202:205], v[98:101]
	v_mfma_f32_16x16x32_bf16 v[102:105], v[214:217], v[202:205], v[102:105]
	v_mfma_f32_16x16x32_bf16 v[106:109], v[218:221], v[202:205], v[106:109]
	v_mfma_f32_16x16x32_bf16 v[110:113], v[222:225], v[202:205], v[110:113]
	v_mfma_f32_16x16x32_bf16 v[114:117], v[210:213], v[206:209], v[114:117]
	v_mfma_f32_16x16x32_bf16 v[118:121], v[214:217], v[206:209], v[118:121]
	v_mfma_f32_16x16x32_bf16 v[122:125], v[218:221], v[206:209], v[122:125]
	v_mfma_f32_16x16x32_bf16 v[126:129], v[222:225], v[206:209], v[126:129]
	s_setprio 0
	s_add_i32 s60, s60, 0x6000
	s_cmp_eq_u32 s60, 0x12000
	s_cselect_b32 s60, 0, s60
	s_add_u32 s54, s54, s72
	s_addc_u32 s55, s55, 0
	s_add_u32 s56, s56, s73
	s_addc_u32 s57, s57, 0
	s_add_i32 s61, s61, 0x6000
	s_cmp_eq_u32 s61, 0x12000
	s_cselect_b32 s61, 0, s61
	s_branch .Lgy_main

.Lgy_nn_b:
	s_waitcnt vmcnt(22) lgkmcnt(0)
	s_barrier
	v_add_u32_e32 v240, s61, v238
	v_add_u32_e32 v241, s61, v239
	s_add_i32 m0, s60, s62
	v_mfma_f32_16x16x32_bf16 v[2:5], v[162:165], v[130:133], 0
	global_load_lds_dwordx4 v226, s[54:55]
	v_mfma_f32_16x16x32_bf16 v[6:9], v[166:169], v[130:133], 0
	global_load_lds_dwordx4 v226, s[54:55] offset:1024
	v_mfma_f32_16x16x32_bf16 v[10:13], v[170:173], v[130:133], 0
	global_load_lds_dwordx4 v226, s[54:55] offset:2048
	v_mfma_f32_16x16x32_bf16 v[14:17], v[174:177], v[130:133], 0
	global_load_lds_dwordx4 v226, s[54:55] offset:3072
	s_add_i32 m0, s60, s63
	v_mfma_f32_16x16x32_bf16 v[18:21], v[162:165], v[134:137], 0
	global_load_lds_dwordx4 v230, s[56:57]
	v_mfma_f32_16x16x32_bf16 v[22:25], v[166:169], v[134:137], 0
	global_load_lds_dwordx4 v231, s[56:57] offset:1024
	v_mfma_f32_16x16x32_bf16 v[26:29], v[170:173], v[134:137], 0
	v_mfma_f32_16x16x32_bf16 v[30:33], v[174:177], v[134:137], 0
	v_mfma_f32_16x16x32_bf16 v[34:37], v[162:165], v[138:141], 0
	ds_read_b128 v[210:213], v241 offset:0
	v_mfma_f32_16x16x32_bf16 v[38:41], v[166:169], v[138:141], 0
	ds_read_b128 v[214:217], v241 offset:256
	v_mfma_f32_16x16x32_bf16 v[42:45], v[170:173], v[138:141], 0
	ds_read_b128 v[218:221], v241 offset:512
	v_mfma_f32_16x16x32_bf16 v[46:49], v[174:177], v[138:141], 0
	ds_read_b128 v[222:225], v241 offset:768
	v_mfma_f32_16x16x32_bf16 v[50:53], v[162:165], v[142:145], 0
	ds_read_b128 v[178:181], v240 offset:0
	v_mfma_f32_16x16x32_bf16 v[54:57], v[166:169], v[142:145], 0
	ds_read_b128 v[182:185], v240 offset:1024
	v_mfma_f32_16x16x32_bf16 v[58:61], v[170:173], v[142:145], 0
	ds_read_b128 v[186:189], v240 offset:2048
	v_mfma_f32_16x16x32_bf16 v[62:65], v[174:177], v[142:145], 0
	ds_read_b128 v[190:193], v240 offset:3072
	v_mfma_f32_16x16x32_bf16 v[66:69], v[162:165], v[146:149], 0
	ds_read_b128 v[194:197], v240 offset:4096
	v_mfma_f32_16x16x32_bf16 v[70:73], v[166:169], v[146:149], 0
	ds_read_b128 v[198:201], v240 offset:5120
	v_mfma_f32_16x16x32_bf16 v[74:77], v[170:173], v[146:149], 0
	ds_read_b128 v[202:205], v240 offset:6144
	v_mfma_f32_16x16x32_bf16 v[78:81], v[174:177], v[146:149], 0
	ds_read_b128 v[206:209], v240 offset:7168
	s_setprio 1
	v_mfma_f32_16x16x32_bf16 v[82:85], v[162:165], v[150:153], 0
	v_mfma_f32_16x16x32_bf16 v[86:89], v[166:169], v[150:153], 0
	v_mfma_f32_16x16x32_bf16 v[90:93], v[170:173], v[150:153], 0
	v_mfma_f32_16x16x32_bf16 v[94:97], v[174:177], v[150:153], 0
	v_mfma_f32_16x16x32_bf16 v[98:101], v[162:165], v[154:157], 0
	v_mfma_f32_16x16x32_bf16 v[102:105], v[166:169], v[154:157], 0
	v_mfma_f32_16x16x32_bf16 v[106:109], v[170:173], v[154:157], 0
	v_mfma_f32_16x16x32_bf16 v[110:113], v[174:177], v[154:157], 0
	v_mfma_f32_16x16x32_bf16 v[114:117], v[162:165], v[158:161], 0
	v_mfma_f32_16x16x32_bf16 v[118:121], v[166:169], v[158:161], 0
	v_mfma_f32_16x16x32_bf16 v[122:125], v[170:173], v[158:161], 0
	v_mfma_f32_16x16x32_bf16 v[126:129], v[174:177], v[158:161], 0
	s_setprio 0
	s_add_i32 s60, s60, 0x6000
	s_cmp_eq_u32 s60, 0x12000
	s_cselect_b32 s60, 0, s60
	s_add_u32 s54, s54, s72
	s_addc_u32 s55, s55, 0
	s_add_u32 s56, s56, s73
	s_addc_u32 s57, s57, 0
	s_add_i32 s61, s61, 0x6000
	s_cmp_eq_u32 s61, 0x12000
	s_cselect_b32 s61, 0, s61
	s_waitcnt vmcnt(22) lgkmcnt(0)
	s_barrier
	v_add_u32_e32 v240, s61, v238
	v_add_u32_e32 v241, s61, v239
	s_add_i32 m0, s60, s62
	v_mfma_f32_16x16x32_bf16 v[2:5], v[210:213], v[178:181], v[2:5]
	global_load_lds_dwordx4 v226, s[54:55]
	v_mfma_f32_16x16x32_bf16 v[6:9], v[214:217], v[178:181], v[6:9]
	global_load_lds_dwordx4 v226, s[54:55] offset:1024
	v_mfma_f32_16x16x32_bf16 v[10:13], v[218:221], v[178:181], v[10:13]
	global_load_lds_dwordx4 v226, s[54:55] offset:2048
	v_mfma_f32_16x16x32_bf16 v[14:17], v[222:225], v[178:181], v[14:17]
	global_load_lds_dwordx4 v226, s[54:55] offset:3072
	s_add_i32 m0, s60, s63
	v_mfma_f32_16x16x32_bf16 v[18:21], v[210:213], v[182:185], v[18:21]
	global_load_lds_dwordx4 v230, s[56:57]
	v_mfma_f32_16x16x32_bf16 v[22:25], v[214:217], v[182:185], v[22:25]
	global_load_lds_dwordx4 v231, s[56:57] offset:1024
	v_mfma_f32_16x16x32_bf16 v[26:29], v[218:221], v[182:185], v[26:29]
	v_mfma_f32_16x16x32_bf16 v[30:33], v[222:225], v[182:185], v[30:33]
	v_mfma_f32_16x16x32_bf16 v[34:37], v[210:213], v[186:189], v[34:37]
	ds_read_b128 v[162:165], v241 offset:0
	v_mfma_f32_16x16x32_bf16 v[38:41], v[214:217], v[186:189], v[38:41]
	ds_read_b128 v[166:169], v241 offset:256
	v_mfma_f32_16x16x32_bf16 v[42:45], v[218:221], v[186:189], v[42:45]
	ds_read_b128 v[170:173], v241 offset:512
	v_mfma_f32_16x16x32_bf16 v[46:49], v[222:225], v[186:189], v[46:49]
	ds_read_b128 v[174:177], v241 offset:768
	v_mfma_f32_16x16x32_bf16 v[50:53], v[210:213], v[190:193], v[50:53]
	ds_read_b128 v[130:133], v240 offset:0
	v_mfma_f32_16x16x32_bf16 v[54:57], v[214:217], v[190:193], v[54:57]
	ds_read_b128 v[134:137], v240 offset:1024
	v_mfma_f32_16x16x32_bf16 v[58:61], v[218:221], v[190:193], v[58:61]
	ds_read_b128 v[138:141], v240 offset:2048
	v_mfma_f32_16x16x32_bf16 v[62:65], v[222:225], v[190:193], v[62:65]
	ds_read_b128 v[142:145], v240 offset:3072
	v_mfma_f32_16x16x32_bf16 v[66:69], v[210:213], v[194:197], v[66:69]
	ds_read_b128 v[146:149], v240 offset:4096
	v_mfma_f32_16x16x32_bf16 v[70:73], v[214:217], v[194:197], v[70:73]
	ds_read_b128 v[150:153], v240 offset:5120
	v_mfma_f32_16x16x32_bf16 v[74:77], v[218:221], v[194:197], v[74:77]
	ds_read_b128 v[154:157], v240 offset:6144
	v_mfma_f32_16x16x32_bf16 v[78:81], v[222:225], v[194:197], v[78:81]
	ds_read_b128 v[158:161], v240 offset:7168
	s_setprio 1
	v_mfma_f32_16x16x32_bf16 v[82:85], v[210:213], v[198:201], v[82:85]
	v_mfma_f32_16x16x32_bf16 v[86:89], v[214:217], v[198:201], v[86:89]
	v_mfma_f32_16x16x32_bf16 v[90:93], v[218:221], v[198:201], v[90:93]
	v_mfma_f32_16x16x32_bf16 v[94:97], v[222:225], v[198:201], v[94:97]
	v_mfma_f32_16x16x32_bf16 v[98:101], v[210:213], v[202:205], v[98:101]
	v_mfma_f32_16x16x32_bf16 v[102:105], v[214:217], v[202:205], v[102:105]
	v_mfma_f32_16x16x32_bf16 v[106:109], v[218:221], v[202:205], v[106:109]
	v_mfma_f32_16x16x32_bf16 v[110:113], v[222:225], v[202:205], v[110:113]
	v_mfma_f32_16x16x32_bf16 v[114:117], v[210:213], v[206:209], v[114:117]
	v_mfma_f32_16x16x32_bf16 v[118:121], v[214:217], v[206:209], v[118:121]
	v_mfma_f32_16x16x32_bf16 v[122:125], v[218:221], v[206:209], v[122:125]
	v_mfma_f32_16x16x32_bf16 v[126:129], v[222:225], v[206:209], v[126:129]
	s_setprio 0
	s_add_i32 s60, s60, 0x6000
	s_cmp_eq_u32 s60, 0x12000
	s_cselect_b32 s60, 0, s60
	s_add_u32 s54, s54, s72
	s_addc_u32 s55, s55, 0
	s_add_u32 s56, s56, s73
	s_addc_u32 s57, s57, 0
	s_add_i32 s61, s61, 0x6000
	s_cmp_eq_u32 s61, 0x12000
	s_cselect_b32 s61, 0, s61

.Lgy_kloop:
	s_waitcnt vmcnt(6) lgkmcnt(0)
	s_barrier
	v_add_u32_e32 v240, s61, v238
	v_add_u32_e32 v241, s61, v239
	s_add_i32 m0, s60, s62
	v_mfma_f32_16x16x32_bf16 v[2:5], v[162:165], v[130:133], v[2:5]
	global_load_lds_dwordx4 v226, s[54:55]
	v_mfma_f32_16x16x32_bf16 v[6:9], v[166:169], v[130:133], v[6:9]
	global_load_lds_dwordx4 v226, s[54:55] offset:1024
	v_mfma_f32_16x16x32_bf16 v[10:13], v[170:173], v[130:133], v[10:13]
	global_load_lds_dwordx4 v226, s[54:55] offset:2048
	v_mfma_f32_16x16x32_bf16 v[14:17], v[174:177], v[130:133], v[14:17]
	global_load_lds_dwordx4 v226, s[54:55] offset:3072
	s_add_i32 m0, s60, s63
	v_mfma_f32_16x16x32_bf16 v[18:21], v[162:165], v[134:137], v[18:21]
	global_load_lds_dwordx4 v230, s[56:57]
	v_mfma_f32_16x16x32_bf16 v[22:25], v[166:169], v[134:137], v[22:25]
	global_load_lds_dwordx4 v231, s[56:57] offset:1024
	v_mfma_f32_16x16x32_bf16 v[26:29], v[170:173], v[134:137], v[26:29]
	v_mfma_f32_16x16x32_bf16 v[30:33], v[174:177], v[134:137], v[30:33]
	v_mfma_f32_16x16x32_bf16 v[34:37], v[162:165], v[138:141], v[34:37]
	ds_read_b128 v[210:213], v241 offset:0
	v_mfma_f32_16x16x32_bf16 v[38:41], v[166:169], v[138:141], v[38:41]
	ds_read_b128 v[214:217], v241 offset:256
	v_mfma_f32_16x16x32_bf16 v[42:45], v[170:173], v[138:141], v[42:45]
	ds_read_b128 v[218:221], v241 offset:512
	v_mfma_f32_16x16x32_bf16 v[46:49], v[174:177], v[138:141], v[46:49]
	ds_read_b128 v[222:225], v241 offset:768
	v_mfma_f32_16x16x32_bf16 v[50:53], v[162:165], v[142:145], v[50:53]
	ds_read_b128 v[178:181], v240 offset:0
	v_mfma_f32_16x16x32_bf16 v[54:57], v[166:169], v[142:145], v[54:57]
	ds_read_b128 v[182:185], v240 offset:1024
	v_mfma_f32_16x16x32_bf16 v[58:61], v[170:173], v[142:145], v[58:61]
	ds_read_b128 v[186:189], v240 offset:2048
	v_mfma_f32_16x16x32_bf16 v[62:65], v[174:177], v[142:145], v[62:65]
	ds_read_b128 v[190:193], v240 offset:3072
	v_mfma_f32_16x16x32_bf16 v[66:69], v[162:165], v[146:149], v[66:69]
	ds_read_b128 v[194:197], v240 offset:4096
	v_mfma_f32_16x16x32_bf16 v[70:73], v[166:169], v[146:149], v[70:73]
	ds_read_b128 v[198:201], v240 offset:5120
	v_mfma_f32_16x16x32_bf16 v[74:77], v[170:173], v[146:149], v[74:77]
	ds_read_b128 v[202:205], v240 offset:6144
	v_mfma_f32_16x16x32_bf16 v[78:81], v[174:177], v[146:149], v[78:81]
	ds_read_b128 v[206:209], v240 offset:7168
	s_setprio 1
	v_mfma_f32_16x16x32_bf16 v[82:85], v[162:165], v[150:153], v[82:85]
	v_mfma_f32_16x16x32_bf16 v[86:89], v[166:169], v[150:153], v[86:89]
	v_mfma_f32_16x16x32_bf16 v[90:93], v[170:173], v[150:153], v[90:93]
	v_mfma_f32_16x16x32_bf16 v[94:97], v[174:177], v[150:153], v[94:97]
	v_mfma_f32_16x16x32_bf16 v[98:101], v[162:165], v[154:157], v[98:101]
	v_mfma_f32_16x16x32_bf16 v[102:105], v[166:169], v[154:157], v[102:105]
	v_mfma_f32_16x16x32_bf16 v[106:109], v[170:173], v[154:157], v[106:109]
	v_mfma_f32_16x16x32_bf16 v[110:113], v[174:177], v[154:157], v[110:113]
	v_mfma_f32_16x16x32_bf16 v[114:117], v[162:165], v[158:161], v[114:117]
	v_mfma_f32_16x16x32_bf16 v[118:121], v[166:169], v[158:161], v[118:121]
	v_mfma_f32_16x16x32_bf16 v[122:125], v[170:173], v[158:161], v[122:125]
	v_mfma_f32_16x16x32_bf16 v[126:129], v[174:177], v[158:161], v[126:129]
	s_setprio 0
	s_add_i32 s60, s60, 0x6000
	s_cmp_eq_u32 s60, 0x12000
	s_cselect_b32 s60, 0, s60
	s_add_u32 s54, s54, s72
	s_addc_u32 s55, s55, 0
	s_add_u32 s56, s56, s73
	s_addc_u32 s57, s57, 0
	s_add_i32 s61, s61, 0x6000
	s_cmp_eq_u32 s61, 0x12000
	s_cselect_b32 s61, 0, s61
	s_waitcnt vmcnt(6) lgkmcnt(0)
	s_barrier
	v_add_u32_e32 v240, s61, v238
	v_add_u32_e32 v241, s61, v239
	s_add_i32 m0, s60, s62
	v_mfma_f32_16x16x32_bf16 v[2:5], v[210:213], v[178:181], v[2:5]
	global_load_lds_dwordx4 v226, s[54:55]
	v_mfma_f32_16x16x32_bf16 v[6:9], v[214:217], v[178:181], v[6:9]
	global_load_lds_dwordx4 v226, s[54:55] offset:1024
	v_mfma_f32_16x16x32_bf16 v[10:13], v[218:221], v[178:181], v[10:13]
	global_load_lds_dwordx4 v226, s[54:55] offset:2048
	v_mfma_f32_16x16x32_bf16 v[14:17], v[222:225], v[178:181], v[14:17]
	global_load_lds_dwordx4 v226, s[54:55] offset:3072
	s_add_i32 m0, s60, s63
	v_mfma_f32_16x16x32_bf16 v[18:21], v[210:213], v[182:185], v[18:21]
	global_load_lds_dwordx4 v230, s[56:57]
	v_mfma_f32_16x16x32_bf16 v[22:25], v[214:217], v[182:185], v[22:25]
	global_load_lds_dwordx4 v231, s[56:57] offset:1024
	v_mfma_f32_16x16x32_bf16 v[26:29], v[218:221], v[182:185], v[26:29]
	v_mfma_f32_16x16x32_bf16 v[30:33], v[222:225], v[182:185], v[30:33]
	v_mfma_f32_16x16x32_bf16 v[34:37], v[210:213], v[186:189], v[34:37]
	ds_read_b128 v[162:165], v241 offset:0
	v_mfma_f32_16x16x32_bf16 v[38:41], v[214:217], v[186:189], v[38:41]
	ds_read_b128 v[166:169], v241 offset:256
	v_mfma_f32_16x16x32_bf16 v[42:45], v[218:221], v[186:189], v[42:45]
	ds_read_b128 v[170:173], v241 offset:512
	v_mfma_f32_16x16x32_bf16 v[46:49], v[222:225], v[186:189], v[46:49]
	ds_read_b128 v[174:177], v241 offset:768
	v_mfma_f32_16x16x32_bf16 v[50:53], v[210:213], v[190:193], v[50:53]
	ds_read_b128 v[130:133], v240 offset:0
	v_mfma_f32_16x16x32_bf16 v[54:57], v[214:217], v[190:193], v[54:57]
	ds_read_b128 v[134:137], v240 offset:1024
	v_mfma_f32_16x16x32_bf16 v[58:61], v[218:221], v[190:193], v[58:61]
	ds_read_b128 v[138:141], v240 offset:2048
	v_mfma_f32_16x16x32_bf16 v[62:65], v[222:225], v[190:193], v[62:65]
	ds_read_b128 v[142:145], v240 offset:3072
	v_mfma_f32_16x16x32_bf16 v[66:69], v[210:213], v[194:197], v[66:69]
	ds_read_b128 v[146:149], v240 offset:4096
	v_mfma_f32_16x16x32_bf16 v[70:73], v[214:217], v[194:197], v[70:73]
	ds_read_b128 v[150:153], v240 offset:5120
	v_mfma_f32_16x16x32_bf16 v[74:77], v[218:221], v[194:197], v[74:77]
	ds_read_b128 v[154:157], v240 offset:6144
	v_mfma_f32_16x16x32_bf16 v[78:81], v[222:225], v[194:197], v[78:81]
	ds_read_b128 v[158:161], v240 offset:7168
	s_setprio 1
	v_mfma_f32_16x16x32_bf16 v[82:85], v[210:213], v[198:201], v[82:85]
	v_mfma_f32_16x16x32_bf16 v[86:89], v[214:217], v[198:201], v[86:89]
	v_mfma_f32_16x16x32_bf16 v[90:93], v[218:221], v[198:201], v[90:93]
	v_mfma_f32_16x16x32_bf16 v[94:97], v[222:225], v[198:201], v[94:97]
	v_mfma_f32_16x16x32_bf16 v[98:101], v[210:213], v[202:205], v[98:101]
	v_mfma_f32_16x16x32_bf16 v[102:105], v[214:217], v[202:205], v[102:105]
	v_mfma_f32_16x16x32_bf16 v[106:109], v[218:221], v[202:205], v[106:109]
	v_mfma_f32_16x16x32_bf16 v[110:113], v[222:225], v[202:205], v[110:113]
	v_mfma_f32_16x16x32_bf16 v[114:117], v[210:213], v[206:209], v[114:117]
	v_mfma_f32_16x16x32_bf16 v[118:121], v[214:217], v[206:209], v[118:121]
	v_mfma_f32_16x16x32_bf16 v[122:125], v[218:221], v[206:209], v[122:125]
	v_mfma_f32_16x16x32_bf16 v[126:129], v[222:225], v[206:209], v[126:129]
	s_setprio 0
	s_add_i32 s60, s60, 0x6000
	s_cmp_eq_u32 s60, 0x12000
	s_cselect_b32 s60, 0, s60
	s_add_u32 s54, s54, s72
	s_addc_u32 s55, s55, 0
	s_add_u32 s56, s56, s73
	s_addc_u32 s57, s57, 0
	s_add_i32 s61, s61, 0x6000
	s_cmp_eq_u32 s61, 0x12000
	s_cselect_b32 s61, 0, s61
	s_add_i32 s40, s40, -1
	s_cmp_lg_u32 s40, 0
	s_cbranch_scc1 .Lgy_kloop
	s_cmp_eq_u32 s37, 0
	s_cbranch_scc1 .Lgy_tail_last
	s_waitcnt vmcnt(6) lgkmcnt(0)
	s_barrier
	v_add_u32_e32 v240, s61, v238
	v_add_u32_e32 v241, s61, v239
	s_add_i32 m0, s60, s62
	v_mfma_f32_16x16x32_bf16 v[2:5], v[162:165], v[130:133], v[2:5]
	global_load_lds_dwordx4 v226, s[54:55]
	v_mfma_f32_16x16x32_bf16 v[6:9], v[166:169], v[130:133], v[6:9]
	global_load_lds_dwordx4 v226, s[54:55] offset:1024
	v_mfma_f32_16x16x32_bf16 v[10:13], v[170:173], v[130:133], v[10:13]
	global_load_lds_dwordx4 v226, s[54:55] offset:2048
	v_mfma_f32_16x16x32_bf16 v[14:17], v[174:177], v[130:133], v[14:17]
	global_load_lds_dwordx4 v226, s[54:55] offset:3072
	s_add_i32 m0, s60, s63
	v_mfma_f32_16x16x32_bf16 v[18:21], v[162:165], v[134:137], v[18:21]
	global_load_lds_dwordx4 v230, s[56:57]
	v_mfma_f32_16x16x32_bf16 v[22:25], v[166:169], v[134:137], v[22:25]
	global_load_lds_dwordx4 v231, s[56:57] offset:1024
	v_mfma_f32_16x16x32_bf16 v[26:29], v[170:173], v[134:137], v[26:29]
	v_mfma_f32_16x16x32_bf16 v[30:33], v[174:177], v[134:137], v[30:33]
	v_mfma_f32_16x16x32_bf16 v[34:37], v[162:165], v[138:141], v[34:37]
	ds_read_b128 v[210:213], v241 offset:0
	v_mfma_f32_16x16x32_bf16 v[38:41], v[166:169], v[138:141], v[38:41]
	ds_read_b128 v[214:217], v241 offset:256
	v_mfma_f32_16x16x32_bf16 v[42:45], v[170:173], v[138:141], v[42:45]
	ds_read_b128 v[218:221], v241 offset:512
	v_mfma_f32_16x16x32_bf16 v[46:49], v[174:177], v[138:141], v[46:49]
	ds_read_b128 v[222:225], v241 offset:768
	v_mfma_f32_16x16x32_bf16 v[50:53], v[162:165], v[142:145], v[50:53]
	ds_read_b128 v[178:181], v240 offset:0
	v_mfma_f32_16x16x32_bf16 v[54:57], v[166:169], v[142:145], v[54:57]
	ds_read_b128 v[182:185], v240 offset:1024
	v_mfma_f32_16x16x32_bf16 v[58:61], v[170:173], v[142:145], v[58:61]
	ds_read_b128 v[186:189], v240 offset:2048
	v_mfma_f32_16x16x32_bf16 v[62:65], v[174:177], v[142:145], v[62:65]
	ds_read_b128 v[190:193], v240 offset:3072
	v_mfma_f32_16x16x32_bf16 v[66:69], v[162:165], v[146:149], v[66:69]
	ds_read_b128 v[194:197], v240 offset:4096
	v_mfma_f32_16x16x32_bf16 v[70:73], v[166:169], v[146:149], v[70:73]
	ds_read_b128 v[198:201], v240 offset:5120
	v_mfma_f32_16x16x32_bf16 v[74:77], v[170:173], v[146:149], v[74:77]
	ds_read_b128 v[202:205], v240 offset:6144
	v_mfma_f32_16x16x32_bf16 v[78:81], v[174:177], v[146:149], v[78:81]
	ds_read_b128 v[206:209], v240 offset:7168
	s_setprio 1
	v_mfma_f32_16x16x32_bf16 v[82:85], v[162:165], v[150:153], v[82:85]
	v_mfma_f32_16x16x32_bf16 v[86:89], v[166:169], v[150:153], v[86:89]
	v_mfma_f32_16x16x32_bf16 v[90:93], v[170:173], v[150:153], v[90:93]
	v_mfma_f32_16x16x32_bf16 v[94:97], v[174:177], v[150:153], v[94:97]
	v_mfma_f32_16x16x32_bf16 v[98:101], v[162:165], v[154:157], v[98:101]
	v_mfma_f32_16x16x32_bf16 v[102:105], v[166:169], v[154:157], v[102:105]
	v_mfma_f32_16x16x32_bf16 v[106:109], v[170:173], v[154:157], v[106:109]
	v_mfma_f32_16x16x32_bf16 v[110:113], v[174:177], v[154:157], v[110:113]
	v_mfma_f32_16x16x32_bf16 v[114:117], v[162:165], v[158:161], v[114:117]
	v_mfma_f32_16x16x32_bf16 v[118:121], v[166:169], v[158:161], v[118:121]
	v_mfma_f32_16x16x32_bf16 v[122:125], v[170:173], v[158:161], v[122:125]
	v_mfma_f32_16x16x32_bf16 v[126:129], v[174:177], v[158:161], v[126:129]
	s_setprio 0
	s_add_i32 s60, s60, 0x6000
	s_cmp_eq_u32 s60, 0x12000
	s_cselect_b32 s60, 0, s60
	s_add_u32 s54, s54, s72
	s_addc_u32 s55, s55, 0
	s_add_u32 s56, s56, s73
	s_addc_u32 s57, s57, 0
	s_add_i32 s61, s61, 0x6000
	s_cmp_eq_u32 s61, 0x12000
	s_cselect_b32 s61, 0, s61
	v_mov_b32_e32 v226, v232
	v_mov_b32_e32 v230, v236
	v_mov_b32_e32 v231, v237
	s_mov_b64 s[54:55], s[48:49]
	s_mov_b64 s[56:57], s[50:51]
	s_waitcnt vmcnt(6) lgkmcnt(0)
	s_barrier
	v_add_u32_e32 v240, s61, v238
	v_add_u32_e32 v241, s61, v239
	s_add_i32 m0, s60, s62
	v_mfma_f32_16x16x32_bf16 v[2:5], v[210:213], v[178:181], v[2:5]
	global_load_lds_dwordx4 v226, s[54:55]
	v_mfma_f32_16x16x32_bf16 v[6:9], v[214:217], v[178:181], v[6:9]
	global_load_lds_dwordx4 v226, s[54:55] offset:1024
	v_mfma_f32_16x16x32_bf16 v[10:13], v[218:221], v[178:181], v[10:13]
	global_load_lds_dwordx4 v226, s[54:55] offset:2048
	v_mfma_f32_16x16x32_bf16 v[14:17], v[222:225], v[178:181], v[14:17]
	global_load_lds_dwordx4 v226, s[54:55] offset:3072
	s_add_i32 m0, s60, s63
	v_mfma_f32_16x16x32_bf16 v[18:21], v[210:213], v[182:185], v[18:21]
	global_load_lds_dwordx4 v230, s[56:57]
	v_mfma_f32_16x16x32_bf16 v[22:25], v[214:217], v[182:185], v[22:25]
	global_load_lds_dwordx4 v231, s[56:57] offset:1024
	v_mfma_f32_16x16x32_bf16 v[26:29], v[218:221], v[182:185], v[26:29]
	v_mfma_f32_16x16x32_bf16 v[30:33], v[222:225], v[182:185], v[30:33]
	v_mfma_f32_16x16x32_bf16 v[34:37], v[210:213], v[186:189], v[34:37]
	ds_read_b128 v[162:165], v241 offset:0
	v_mfma_f32_16x16x32_bf16 v[38:41], v[214:217], v[186:189], v[38:41]
	ds_read_b128 v[166:169], v241 offset:256
	v_mfma_f32_16x16x32_bf16 v[42:45], v[218:221], v[186:189], v[42:45]
	ds_read_b128 v[170:173], v241 offset:512
	v_mfma_f32_16x16x32_bf16 v[46:49], v[222:225], v[186:189], v[46:49]
	ds_read_b128 v[174:177], v241 offset:768
	v_mfma_f32_16x16x32_bf16 v[50:53], v[210:213], v[190:193], v[50:53]
	ds_read_b128 v[130:133], v240 offset:0
	v_mfma_f32_16x16x32_bf16 v[54:57], v[214:217], v[190:193], v[54:57]
	ds_read_b128 v[134:137], v240 offset:1024
	v_mfma_f32_16x16x32_bf16 v[58:61], v[218:221], v[190:193], v[58:61]
	ds_read_b128 v[138:141], v240 offset:2048
	v_mfma_f32_16x16x32_bf16 v[62:65], v[222:225], v[190:193], v[62:65]
	ds_read_b128 v[142:145], v240 offset:3072
	v_mfma_f32_16x16x32_bf16 v[66:69], v[210:213], v[194:197], v[66:69]
	ds_read_b128 v[146:149], v240 offset:4096
	v_mfma_f32_16x16x32_bf16 v[70:73], v[214:217], v[194:197], v[70:73]
	ds_read_b128 v[150:153], v240 offset:5120
	v_mfma_f32_16x16x32_bf16 v[74:77], v[218:221], v[194:197], v[74:77]
	ds_read_b128 v[154:157], v240 offset:6144
	v_mfma_f32_16x16x32_bf16 v[78:81], v[222:225], v[194:197], v[78:81]
	ds_read_b128 v[158:161], v240 offset:7168
	s_setprio 1
	v_mfma_f32_16x16x32_bf16 v[82:85], v[210:213], v[198:201], v[82:85]
	v_mfma_f32_16x16x32_bf16 v[86:89], v[214:217], v[198:201], v[86:89]
	v_mfma_f32_16x16x32_bf16 v[90:93], v[218:221], v[198:201], v[90:93]
	v_mfma_f32_16x16x32_bf16 v[94:97], v[222:225], v[198:201], v[94:97]
	v_mfma_f32_16x16x32_bf16 v[98:101], v[210:213], v[202:205], v[98:101]
	v_mfma_f32_16x16x32_bf16 v[102:105], v[214:217], v[202:205], v[102:105]
	v_mfma_f32_16x16x32_bf16 v[106:109], v[218:221], v[202:205], v[106:109]
	v_mfma_f32_16x16x32_bf16 v[110:113], v[222:225], v[202:205], v[110:113]
	v_mfma_f32_16x16x32_bf16 v[114:117], v[210:213], v[206:209], v[114:117]
	v_mfma_f32_16x16x32_bf16 v[118:121], v[214:217], v[206:209], v[118:121]
	v_mfma_f32_16x16x32_bf16 v[122:125], v[218:221], v[206:209], v[122:125]
	v_mfma_f32_16x16x32_bf16 v[126:129], v[222:225], v[206:209], v[126:129]
	s_setprio 0
	s_add_i32 s60, s60, 0x6000
	s_cmp_eq_u32 s60, 0x12000
	s_cselect_b32 s60, 0, s60
	s_add_u32 s54, s54, s72
	s_addc_u32 s55, s55, 0
	s_add_u32 s56, s56, s73
	s_addc_u32 s57, s57, 0
	s_add_i32 s61, s61, 0x6000
	s_cmp_eq_u32 s61, 0x12000
	s_cselect_b32 s61, 0, s61
	s_waitcnt vmcnt(6) lgkmcnt(0)
	s_barrier
	v_add_u32_e32 v240, s61, v238
	v_add_u32_e32 v241, s61, v239
	s_add_i32 m0, s60, s62
	v_mfma_f32_16x16x32_bf16 v[2:5], v[162:165], v[130:133], v[2:5]
	global_load_lds_dwordx4 v226, s[54:55]
	v_mfma_f32_16x16x32_bf16 v[6:9], v[166:169], v[130:133], v[6:9]
	global_load_lds_dwordx4 v226, s[54:55] offset:1024
	v_mfma_f32_16x16x32_bf16 v[10:13], v[170:173], v[130:133], v[10:13]
	global_load_lds_dwordx4 v226, s[54:55] offset:2048
	v_mfma_f32_16x16x32_bf16 v[14:17], v[174:177], v[130:133], v[14:17]
	global_load_lds_dwordx4 v226, s[54:55] offset:3072
	s_add_i32 m0, s60, s63
	v_mfma_f32_16x16x32_bf16 v[18:21], v[162:165], v[134:137], v[18:21]
	global_load_lds_dwordx4 v230, s[56:57]
	v_mfma_f32_16x16x32_bf16 v[22:25], v[166:169], v[134:137], v[22:25]
	global_load_lds_dwordx4 v231, s[56:57] offset:1024
	v_mfma_f32_16x16x32_bf16 v[26:29], v[170:173], v[134:137], v[26:29]
	v_mfma_f32_16x16x32_bf16 v[30:33], v[174:177], v[134:137], v[30:33]
	v_mfma_f32_16x16x32_bf16 v[34:37], v[162:165], v[138:141], v[34:37]
	ds_read_b128 v[210:213], v241 offset:0
	v_mfma_f32_16x16x32_bf16 v[38:41], v[166:169], v[138:141], v[38:41]
	ds_read_b128 v[214:217], v241 offset:256
	v_mfma_f32_16x16x32_bf16 v[42:45], v[170:173], v[138:141], v[42:45]
	ds_read_b128 v[218:221], v241 offset:512
	v_mfma_f32_16x16x32_bf16 v[46:49], v[174:177], v[138:141], v[46:49]
	ds_read_b128 v[222:225], v241 offset:768
	v_mfma_f32_16x16x32_bf16 v[50:53], v[162:165], v[142:145], v[50:53]
	ds_read_b128 v[178:181], v240 offset:0
	v_mfma_f32_16x16x32_bf16 v[54:57], v[166:169], v[142:145], v[54:57]
	ds_read_b128 v[182:185], v240 offset:1024
	v_mfma_f32_16x16x32_bf16 v[58:61], v[170:173], v[142:145], v[58:61]
	ds_read_b128 v[186:189], v240 offset:2048
	v_mfma_f32_16x16x32_bf16 v[62:65], v[174:177], v[142:145], v[62:65]
	ds_read_b128 v[190:193], v240 offset:3072
	v_mfma_f32_16x16x32_bf16 v[66:69], v[162:165], v[146:149], v[66:69]
	ds_read_b128 v[194:197], v240 offset:4096
	v_mfma_f32_16x16x32_bf16 v[70:73], v[166:169], v[146:149], v[70:73]
	ds_read_b128 v[198:201], v240 offset:5120
	v_mfma_f32_16x16x32_bf16 v[74:77], v[170:173], v[146:149], v[74:77]
	ds_read_b128 v[202:205], v240 offset:6144
	v_mfma_f32_16x16x32_bf16 v[78:81], v[174:177], v[146:149], v[78:81]
	ds_read_b128 v[206:209], v240 offset:7168
	s_setprio 1
	v_mfma_f32_16x16x32_bf16 v[82:85], v[162:165], v[150:153], v[82:85]
	v_mfma_f32_16x16x32_bf16 v[86:89], v[166:169], v[150:153], v[86:89]
	v_mfma_f32_16x16x32_bf16 v[90:93], v[170:173], v[150:153], v[90:93]
	v_mfma_f32_16x16x32_bf16 v[94:97], v[174:177], v[150:153], v[94:97]
	v_mfma_f32_16x16x32_bf16 v[98:101], v[162:165], v[154:157], v[98:101]
	v_mfma_f32_16x16x32_bf16 v[102:105], v[166:169], v[154:157], v[102:105]
	v_mfma_f32_16x16x32_bf16 v[106:109], v[170:173], v[154:157], v[106:109]
	v_mfma_f32_16x16x32_bf16 v[110:113], v[174:177], v[154:157], v[110:113]
	v_mfma_f32_16x16x32_bf16 v[114:117], v[162:165], v[158:161], v[114:117]
	v_mfma_f32_16x16x32_bf16 v[118:121], v[166:169], v[158:161], v[118:121]
	v_mfma_f32_16x16x32_bf16 v[122:125], v[170:173], v[158:161], v[122:125]
	v_mfma_f32_16x16x32_bf16 v[126:129], v[174:177], v[158:161], v[126:129]
	s_setprio 0
	s_add_i32 s60, s60, 0x6000
	s_cmp_eq_u32 s60, 0x12000
	s_cselect_b32 s60, 0, s60
	s_add_u32 s54, s54, s72
	s_addc_u32 s55, s55, 0
	s_add_u32 s56, s56, s73
	s_addc_u32 s57, s57, 0
	s_add_i32 s61, s61, 0x6000
	s_cmp_eq_u32 s61, 0x12000
	s_cselect_b32 s61, 0, s61
	s_waitcnt vmcnt(6) lgkmcnt(0)
	s_barrier
	v_add_u32_e32 v240, s61, v238
	v_add_u32_e32 v241, s61, v239
	s_add_i32 m0, s60, s62
	v_mfma_f32_16x16x32_bf16 v[2:5], v[210:213], v[178:181], v[2:5]
	global_load_lds_dwordx4 v226, s[54:55]
	v_mfma_f32_16x16x32_bf16 v[6:9], v[214:217], v[178:181], v[6:9]
	global_load_lds_dwordx4 v226, s[54:55] offset:1024
	v_mfma_f32_16x16x32_bf16 v[10:13], v[218:221], v[178:181], v[10:13]
	global_load_lds_dwordx4 v226, s[54:55] offset:2048
	v_mfma_f32_16x16x32_bf16 v[14:17], v[222:225], v[178:181], v[14:17]
	global_load_lds_dwordx4 v226, s[54:55] offset:3072
	s_add_i32 m0, s60, s63
	v_mfma_f32_16x16x32_bf16 v[18:21], v[210:213], v[182:185], v[18:21]
	global_load_lds_dwordx4 v230, s[56:57]
	v_mfma_f32_16x16x32_bf16 v[22:25], v[214:217], v[182:185], v[22:25]
	global_load_lds_dwordx4 v231, s[56:57] offset:1024
	v_mfma_f32_16x16x32_bf16 v[26:29], v[218:221], v[182:185], v[26:29]
	v_mfma_f32_16x16x32_bf16 v[30:33], v[222:225], v[182:185], v[30:33]
	v_mfma_f32_16x16x32_bf16 v[34:37], v[210:213], v[186:189], v[34:37]
	ds_read_b128 v[162:165], v241 offset:0
	v_mfma_f32_16x16x32_bf16 v[38:41], v[214:217], v[186:189], v[38:41]
	ds_read_b128 v[166:169], v241 offset:256
	v_mfma_f32_16x16x32_bf16 v[42:45], v[218:221], v[186:189], v[42:45]
	ds_read_b128 v[170:173], v241 offset:512
	v_mfma_f32_16x16x32_bf16 v[46:49], v[222:225], v[186:189], v[46:49]
	ds_read_b128 v[174:177], v241 offset:768
	v_mfma_f32_16x16x32_bf16 v[50:53], v[210:213], v[190:193], v[50:53]
	ds_read_b128 v[130:133], v240 offset:0
	v_mfma_f32_16x16x32_bf16 v[54:57], v[214:217], v[190:193], v[54:57]
	ds_read_b128 v[134:137], v240 offset:1024
	v_mfma_f32_16x16x32_bf16 v[58:61], v[218:221], v[190:193], v[58:61]
	ds_read_b128 v[138:141], v240 offset:2048
	v_mfma_f32_16x16x32_bf16 v[62:65], v[222:225], v[190:193], v[62:65]
	ds_read_b128 v[142:145], v240 offset:3072
	v_mfma_f32_16x16x32_bf16 v[66:69], v[210:213], v[194:197], v[66:69]
	ds_read_b128 v[146:149], v240 offset:4096
	v_mfma_f32_16x16x32_bf16 v[70:73], v[214:217], v[194:197], v[70:73]
	ds_read_b128 v[150:153], v240 offset:5120
	v_mfma_f32_16x16x32_bf16 v[74:77], v[218:221], v[194:197], v[74:77]
	ds_read_b128 v[154:157], v240 offset:6144
	v_mfma_f32_16x16x32_bf16 v[78:81], v[222:225], v[194:197], v[78:81]
	ds_read_b128 v[158:161], v240 offset:7168
	s_setprio 1
	v_mfma_f32_16x16x32_bf16 v[82:85], v[210:213], v[198:201], v[82:85]
	v_mfma_f32_16x16x32_bf16 v[86:89], v[214:217], v[198:201], v[86:89]
	v_mfma_f32_16x16x32_bf16 v[90:93], v[218:221], v[198:201], v[90:93]
	v_mfma_f32_16x16x32_bf16 v[94:97], v[222:225], v[198:201], v[94:97]
	v_mfma_f32_16x16x32_bf16 v[98:101], v[210:213], v[202:205], v[98:101]
	v_mfma_f32_16x16x32_bf16 v[102:105], v[214:217], v[202:205], v[102:105]
	v_mfma_f32_16x16x32_bf16 v[106:109], v[218:221], v[202:205], v[106:109]
	v_mfma_f32_16x16x32_bf16 v[110:113], v[222:225], v[202:205], v[110:113]
	v_mfma_f32_16x16x32_bf16 v[114:117], v[210:213], v[206:209], v[114:117]
	v_mfma_f32_16x16x32_bf16 v[118:121], v[214:217], v[206:209], v[118:121]
	v_mfma_f32_16x16x32_bf16 v[122:125], v[218:221], v[206:209], v[122:125]
	v_mfma_f32_16x16x32_bf16 v[126:129], v[222:225], v[206:209], v[126:129]
	s_setprio 0
	s_add_i32 s60, s60, 0x6000
	s_cmp_eq_u32 s60, 0x12000
	s_cselect_b32 s60, 0, s60
	s_add_u32 s54, s54, s72
	s_addc_u32 s55, s55, 0
	s_add_u32 s56, s56, s73
	s_addc_u32 s57, s57, 0
	s_add_i32 s61, s61, 0x6000
	s_cmp_eq_u32 s61, 0x12000
	s_cselect_b32 s61, 0, s61
	s_nop 7
	s_nop 1
	s_lshl_b32 s26, s35, 11
	s_lshl_b32 s27, s36, 1
	s_add_i32 s26, s26, s27
	s_add_u32 s18, s52, s26
	s_addc_u32 s19, s53, 0
	v_cvt_pk_bf16_f32 v2, v2, v3
	v_cvt_pk_bf16_f32 v3, v4, v5
	v_cvt_pk_bf16_f32 v4, v6, v7
	v_cvt_pk_bf16_f32 v5, v8, v9
	v_cvt_pk_bf16_f32 v6, v10, v11
	v_cvt_pk_bf16_f32 v7, v12, v13
	v_cvt_pk_bf16_f32 v8, v14, v15
	v_cvt_pk_bf16_f32 v9, v16, v17
	global_store_dwordx4 v242, v[2:5], s[18:19]
	global_store_dwordx4 v242, v[6:9], s[18:19] offset:16
	s_add_u32 s18, s18, 0x8000
	s_addc_u32 s19, s19, 0
	v_cvt_pk_bf16_f32 v18, v18, v19
	v_cvt_pk_bf16_f32 v19, v20, v21
	v_cvt_pk_bf16_f32 v20, v22, v23
	v_cvt_pk_bf16_f32 v21, v24, v25
	v_cvt_pk_bf16_f32 v22, v26, v27
	v_cvt_pk_bf16_f32 v23, v28, v29
	v_cvt_pk_bf16_f32 v24, v30, v31
	v_cvt_pk_bf16_f32 v25, v32, v33
	global_store_dwordx4 v242, v[18:21], s[18:19]
	global_store_dwordx4 v242, v[22:25], s[18:19] offset:16
	s_add_u32 s18, s18, 0x8000
	s_addc_u32 s19, s19, 0
	v_cvt_pk_bf16_f32 v34, v34, v35
	v_cvt_pk_bf16_f32 v35, v36, v37
	v_cvt_pk_bf16_f32 v36, v38, v39
	v_cvt_pk_bf16_f32 v37, v40, v41
	v_cvt_pk_bf16_f32 v38, v42, v43
	v_cvt_pk_bf16_f32 v39, v44, v45
	v_cvt_pk_bf16_f32 v40, v46, v47
	v_cvt_pk_bf16_f32 v41, v48, v49
	global_store_dwordx4 v242, v[34:37], s[18:19]
	global_store_dwordx4 v242, v[38:41], s[18:19] offset:16
	s_add_u32 s18, s18, 0x8000
	s_addc_u32 s19, s19, 0
	v_cvt_pk_bf16_f32 v50, v50, v51
	v_cvt_pk_bf16_f32 v51, v52, v53
	v_cvt_pk_bf16_f32 v52, v54, v55
	v_cvt_pk_bf16_f32 v53, v56, v57
	v_cvt_pk_bf16_f32 v54, v58, v59
	v_cvt_pk_bf16_f32 v55, v60, v61
	v_cvt_pk_bf16_f32 v56, v62, v63
	v_cvt_pk_bf16_f32 v57, v64, v65
	global_store_dwordx4 v242, v[50:53], s[18:19]
	global_store_dwordx4 v242, v[54:57], s[18:19] offset:16
	s_add_u32 s18, s18, 0x8000
	s_addc_u32 s19, s19, 0
	v_cvt_pk_bf16_f32 v66, v66, v67
	v_cvt_pk_bf16_f32 v67, v68, v69
	v_cvt_pk_bf16_f32 v68, v70, v71
	v_cvt_pk_bf16_f32 v69, v72, v73
	v_cvt_pk_bf16_f32 v70, v74, v75
	v_cvt_pk_bf16_f32 v71, v76, v77
	v_cvt_pk_bf16_f32 v72, v78, v79
	v_cvt_pk_bf16_f32 v73, v80, v81
	global_store_dwordx4 v242, v[66:69], s[18:19]
	global_store_dwordx4 v242, v[70:73], s[18:19] offset:16
	s_add_u32 s18, s18, 0x8000
	s_addc_u32 s19, s19, 0
	v_cvt_pk_bf16_f32 v82, v82, v83
	v_cvt_pk_bf16_f32 v83, v84, v85
	v_cvt_pk_bf16_f32 v84, v86, v87
	v_cvt_pk_bf16_f32 v85, v88, v89
	v_cvt_pk_bf16_f32 v86, v90, v91
	v_cvt_pk_bf16_f32 v87, v92, v93
	v_cvt_pk_bf16_f32 v88, v94, v95
	v_cvt_pk_bf16_f32 v89, v96, v97
	global_store_dwordx4 v242, v[82:85], s[18:19]
	global_store_dwordx4 v242, v[86:89], s[18:19] offset:16
	s_add_u32 s18, s18, 0x8000
	s_addc_u32 s19, s19, 0
	v_cvt_pk_bf16_f32 v98, v98, v99
	v_cvt_pk_bf16_f32 v99, v100, v101
	v_cvt_pk_bf16_f32 v100, v102, v103
	v_cvt_pk_bf16_f32 v101, v104, v105
	v_cvt_pk_bf16_f32 v102, v106, v107
	v_cvt_pk_bf16_f32 v103, v108, v109
	v_cvt_pk_bf16_f32 v104, v110, v111
	v_cvt_pk_bf16_f32 v105, v112, v113
	global_store_dwordx4 v242, v[98:101], s[18:19]
	global_store_dwordx4 v242, v[102:105], s[18:19] offset:16
	s_add_u32 s18, s18, 0x8000
	s_addc_u32 s19, s19, 0
	v_cvt_pk_bf16_f32 v114, v114, v115
	v_cvt_pk_bf16_f32 v115, v116, v117
	v_cvt_pk_bf16_f32 v116, v118, v119
	v_cvt_pk_bf16_f32 v117, v120, v121
	v_cvt_pk_bf16_f32 v118, v122, v123
	v_cvt_pk_bf16_f32 v119, v124, v125
	v_cvt_pk_bf16_f32 v120, v126, v127
	v_cvt_pk_bf16_f32 v121, v128, v129
	global_store_dwordx4 v242, v[114:117], s[18:19]
	global_store_dwordx4 v242, v[118:121], s[18:19] offset:16
	s_mov_b32 s34, s38
	s_mov_b32 s35, s30
	s_mov_b32 s36, s31
	s_branch .Lgy_tile
.Lgy_tail_last:
	s_waitcnt vmcnt(6) lgkmcnt(0)
	s_barrier
	v_add_u32_e32 v240, s61, v238
	v_add_u32_e32 v241, s61, v239
	s_add_i32 m0, s60, s62
	v_mfma_f32_16x16x32_bf16 v[2:5], v[162:165], v[130:133], v[2:5]
	global_load_lds_dwordx4 v226, s[54:55]
	v_mfma_f32_16x16x32_bf16 v[6:9], v[166:169], v[130:133], v[6:9]
	global_load_lds_dwordx4 v226, s[54:55] offset:1024
	v_mfma_f32_16x16x32_bf16 v[10:13], v[170:173], v[130:133], v[10:13]
	global_load_lds_dwordx4 v226, s[54:55] offset:2048
	v_mfma_f32_16x16x32_bf16 v[14:17], v[174:177], v[130:133], v[14:17]
	global_load_lds_dwordx4 v226, s[54:55] offset:3072
	s_add_i32 m0, s60, s63
	v_mfma_f32_16x16x32_bf16 v[18:21], v[162:165], v[134:137], v[18:21]
	global_load_lds_dwordx4 v230, s[56:57]
	v_mfma_f32_16x16x32_bf16 v[22:25], v[166:169], v[134:137], v[22:25]
	global_load_lds_dwordx4 v231, s[56:57] offset:1024
	v_mfma_f32_16x16x32_bf16 v[26:29], v[170:173], v[134:137], v[26:29]
	v_mfma_f32_16x16x32_bf16 v[30:33], v[174:177], v[134:137], v[30:33]
	v_mfma_f32_16x16x32_bf16 v[34:37], v[162:165], v[138:141], v[34:37]
	ds_read_b128 v[210:213], v241 offset:0
	v_mfma_f32_16x16x32_bf16 v[38:41], v[166:169], v[138:141], v[38:41]
	ds_read_b128 v[214:217], v241 offset:256
	v_mfma_f32_16x16x32_bf16 v[42:45], v[170:173], v[138:141], v[42:45]
	ds_read_b128 v[218:221], v241 offset:512
	v_mfma_f32_16x16x32_bf16 v[46:49], v[174:177], v[138:141], v[46:49]
	ds_read_b128 v[222:225], v241 offset:768
	v_mfma_f32_16x16x32_bf16 v[50:53], v[162:165], v[142:145], v[50:53]
	ds_read_b128 v[178:181], v240 offset:0
	v_mfma_f32_16x16x32_bf16 v[54:57], v[166:169], v[142:145], v[54:57]
	ds_read_b128 v[182:185], v240 offset:1024
	v_mfma_f32_16x16x32_bf16 v[58:61], v[170:173], v[142:145], v[58:61]
	ds_read_b128 v[186:189], v240 offset:2048
	v_mfma_f32_16x16x32_bf16 v[62:65], v[174:177], v[142:145], v[62:65]
	ds_read_b128 v[190:193], v240 offset:3072
	v_mfma_f32_16x16x32_bf16 v[66:69], v[162:165], v[146:149], v[66:69]
	ds_read_b128 v[194:197], v240 offset:4096
	v_mfma_f32_16x16x32_bf16 v[70:73], v[166:169], v[146:149], v[70:73]
	ds_read_b128 v[198:201], v240 offset:5120
	v_mfma_f32_16x16x32_bf16 v[74:77], v[170:173], v[146:149], v[74:77]
	ds_read_b128 v[202:205], v240 offset:6144
	v_mfma_f32_16x16x32_bf16 v[78:81], v[174:177], v[146:149], v[78:81]
	ds_read_b128 v[206:209], v240 offset:7168
	s_setprio 1
	v_mfma_f32_16x16x32_bf16 v[82:85], v[162:165], v[150:153], v[82:85]
	v_mfma_f32_16x16x32_bf16 v[86:89], v[166:169], v[150:153], v[86:89]
	v_mfma_f32_16x16x32_bf16 v[90:93], v[170:173], v[150:153], v[90:93]
	v_mfma_f32_16x16x32_bf16 v[94:97], v[174:177], v[150:153], v[94:97]
	v_mfma_f32_16x16x32_bf16 v[98:101], v[162:165], v[154:157], v[98:101]
	v_mfma_f32_16x16x32_bf16 v[102:105], v[166:169], v[154:157], v[102:105]
	v_mfma_f32_16x16x32_bf16 v[106:109], v[170:173], v[154:157], v[106:109]
	v_mfma_f32_16x16x32_bf16 v[110:113], v[174:177], v[154:157], v[110:113]
	v_mfma_f32_16x16x32_bf16 v[114:117], v[162:165], v[158:161], v[114:117]
	v_mfma_f32_16x16x32_bf16 v[118:121], v[166:169], v[158:161], v[118:121]
	v_mfma_f32_16x16x32_bf16 v[122:125], v[170:173], v[158:161], v[122:125]
	v_mfma_f32_16x16x32_bf16 v[126:129], v[174:177], v[158:161], v[126:129]
	s_setprio 0
	s_add_i32 s60, s60, 0x6000
	s_cmp_eq_u32 s60, 0x12000
	s_cselect_b32 s60, 0, s60
	s_add_u32 s54, s54, s72
	s_addc_u32 s55, s55, 0
	s_add_u32 s56, s56, s73
	s_addc_u32 s57, s57, 0
	s_add_i32 s61, s61, 0x6000
	s_cmp_eq_u32 s61, 0x12000
	s_cselect_b32 s61, 0, s61
	s_waitcnt vmcnt(6) lgkmcnt(0)
	s_barrier
	v_add_u32_e32 v240, s61, v238
	v_add_u32_e32 v241, s61, v239
	v_mfma_f32_16x16x32_bf16 v[2:5], v[210:213], v[178:181], v[2:5]
	v_mfma_f32_16x16x32_bf16 v[6:9], v[214:217], v[178:181], v[6:9]
	v_mfma_f32_16x16x32_bf16 v[10:13], v[218:221], v[178:181], v[10:13]
	v_mfma_f32_16x16x32_bf16 v[14:17], v[222:225], v[178:181], v[14:17]
	v_mfma_f32_16x16x32_bf16 v[18:21], v[210:213], v[182:185], v[18:21]
	v_mfma_f32_16x16x32_bf16 v[22:25], v[214:217], v[182:185], v[22:25]
	v_mfma_f32_16x16x32_bf16 v[26:29], v[218:221], v[182:185], v[26:29]
	v_mfma_f32_16x16x32_bf16 v[30:33], v[222:225], v[182:185], v[30:33]
	v_mfma_f32_16x16x32_bf16 v[34:37], v[210:213], v[186:189], v[34:37]
	ds_read_b128 v[162:165], v241 offset:0
	v_mfma_f32_16x16x32_bf16 v[38:41], v[214:217], v[186:189], v[38:41]
	ds_read_b128 v[166:169], v241 offset:256
	v_mfma_f32_16x16x32_bf16 v[42:45], v[218:221], v[186:189], v[42:45]
	ds_read_b128 v[170:173], v241 offset:512
	v_mfma_f32_16x16x32_bf16 v[46:49], v[222:225], v[186:189], v[46:49]
	ds_read_b128 v[174:177], v241 offset:768
	v_mfma_f32_16x16x32_bf16 v[50:53], v[210:213], v[190:193], v[50:53]
	ds_read_b128 v[130:133], v240 offset:0
	v_mfma_f32_16x16x32_bf16 v[54:57], v[214:217], v[190:193], v[54:57]
	ds_read_b128 v[134:137], v240 offset:1024
	v_mfma_f32_16x16x32_bf16 v[58:61], v[218:221], v[190:193], v[58:61]
	ds_read_b128 v[138:141], v240 offset:2048
	v_mfma_f32_16x16x32_bf16 v[62:65], v[222:225], v[190:193], v[62:65]
	ds_read_b128 v[142:145], v240 offset:3072
	v_mfma_f32_16x16x32_bf16 v[66:69], v[210:213], v[194:197], v[66:69]
	ds_read_b128 v[146:149], v240 offset:4096
	v_mfma_f32_16x16x32_bf16 v[70:73], v[214:217], v[194:197], v[70:73]
	ds_read_b128 v[150:153], v240 offset:5120
	v_mfma_f32_16x16x32_bf16 v[74:77], v[218:221], v[194:197], v[74:77]
	ds_read_b128 v[154:157], v240 offset:6144
	v_mfma_f32_16x16x32_bf16 v[78:81], v[222:225], v[194:197], v[78:81]
	ds_read_b128 v[158:161], v240 offset:7168
	s_setprio 1
	v_mfma_f32_16x16x32_bf16 v[82:85], v[210:213], v[198:201], v[82:85]
	v_mfma_f32_16x16x32_bf16 v[86:89], v[214:217], v[198:201], v[86:89]
	v_mfma_f32_16x16x32_bf16 v[90:93], v[218:221], v[198:201], v[90:93]
	v_mfma_f32_16x16x32_bf16 v[94:97], v[222:225], v[198:201], v[94:97]
	v_mfma_f32_16x16x32_bf16 v[98:101], v[210:213], v[202:205], v[98:101]
	v_mfma_f32_16x16x32_bf16 v[102:105], v[214:217], v[202:205], v[102:105]
	v_mfma_f32_16x16x32_bf16 v[106:109], v[218:221], v[202:205], v[106:109]
	v_mfma_f32_16x16x32_bf16 v[110:113], v[222:225], v[202:205], v[110:113]
	v_mfma_f32_16x16x32_bf16 v[114:117], v[210:213], v[206:209], v[114:117]
	v_mfma_f32_16x16x32_bf16 v[118:121], v[214:217], v[206:209], v[118:121]
	v_mfma_f32_16x16x32_bf16 v[122:125], v[218:221], v[206:209], v[122:125]
	v_mfma_f32_16x16x32_bf16 v[126:129], v[222:225], v[206:209], v[126:129]
	s_setprio 0
	s_add_i32 s61, s61, 0x6000
	s_cmp_eq_u32 s61, 0x12000
	s_cselect_b32 s61, 0, s61
	s_waitcnt vmcnt(0) lgkmcnt(0)
	s_barrier
	v_add_u32_e32 v240, s61, v238
	v_add_u32_e32 v241, s61, v239
	v_mfma_f32_16x16x32_bf16 v[2:5], v[162:165], v[130:133], v[2:5]
	v_mfma_f32_16x16x32_bf16 v[6:9], v[166:169], v[130:133], v[6:9]
	v_mfma_f32_16x16x32_bf16 v[10:13], v[170:173], v[130:133], v[10:13]
	v_mfma_f32_16x16x32_bf16 v[14:17], v[174:177], v[130:133], v[14:17]
	v_mfma_f32_16x16x32_bf16 v[18:21], v[162:165], v[134:137], v[18:21]
	v_mfma_f32_16x16x32_bf16 v[22:25], v[166:169], v[134:137], v[22:25]
	v_mfma_f32_16x16x32_bf16 v[26:29], v[170:173], v[134:137], v[26:29]
	v_mfma_f32_16x16x32_bf16 v[30:33], v[174:177], v[134:137], v[30:33]
	v_mfma_f32_16x16x32_bf16 v[34:37], v[162:165], v[138:141], v[34:37]
	ds_read_b128 v[210:213], v241 offset:0
	v_mfma_f32_16x16x32_bf16 v[38:41], v[166:169], v[138:141], v[38:41]
	ds_read_b128 v[214:217], v241 offset:256
	v_mfma_f32_16x16x32_bf16 v[42:45], v[170:173], v[138:141], v[42:45]
	ds_read_b128 v[218:221], v241 offset:512
	v_mfma_f32_16x16x32_bf16 v[46:49], v[174:177], v[138:141], v[46:49]
	ds_read_b128 v[222:225], v241 offset:768
	v_mfma_f32_16x16x32_bf16 v[50:53], v[162:165], v[142:145], v[50:53]
	ds_read_b128 v[178:181], v240 offset:0
	v_mfma_f32_16x16x32_bf16 v[54:57], v[166:169], v[142:145], v[54:57]
	ds_read_b128 v[182:185], v240 offset:1024
	v_mfma_f32_16x16x32_bf16 v[58:61], v[170:173], v[142:145], v[58:61]
	ds_read_b128 v[186:189], v240 offset:2048
	v_mfma_f32_16x16x32_bf16 v[62:65], v[174:177], v[142:145], v[62:65]
	ds_read_b128 v[190:193], v240 offset:3072
	v_mfma_f32_16x16x32_bf16 v[66:69], v[162:165], v[146:149], v[66:69]
	ds_read_b128 v[194:197], v240 offset:4096
	v_mfma_f32_16x16x32_bf16 v[70:73], v[166:169], v[146:149], v[70:73]
	ds_read_b128 v[198:201], v240 offset:5120
	v_mfma_f32_16x16x32_bf16 v[74:77], v[170:173], v[146:149], v[74:77]
	ds_read_b128 v[202:205], v240 offset:6144
	v_mfma_f32_16x16x32_bf16 v[78:81], v[174:177], v[146:149], v[78:81]
	ds_read_b128 v[206:209], v240 offset:7168
	s_setprio 1
	v_mfma_f32_16x16x32_bf16 v[82:85], v[162:165], v[150:153], v[82:85]
	v_mfma_f32_16x16x32_bf16 v[86:89], v[166:169], v[150:153], v[86:89]
	v_mfma_f32_16x16x32_bf16 v[90:93], v[170:173], v[150:153], v[90:93]
	v_mfma_f32_16x16x32_bf16 v[94:97], v[174:177], v[150:153], v[94:97]
	v_mfma_f32_16x16x32_bf16 v[98:101], v[162:165], v[154:157], v[98:101]
	v_mfma_f32_16x16x32_bf16 v[102:105], v[166:169], v[154:157], v[102:105]
	v_mfma_f32_16x16x32_bf16 v[106:109], v[170:173], v[154:157], v[106:109]
	v_mfma_f32_16x16x32_bf16 v[110:113], v[174:177], v[154:157], v[110:113]
	v_mfma_f32_16x16x32_bf16 v[114:117], v[162:165], v[158:161], v[114:117]
	v_mfma_f32_16x16x32_bf16 v[118:121], v[166:169], v[158:161], v[118:121]
	v_mfma_f32_16x16x32_bf16 v[122:125], v[170:173], v[158:161], v[122:125]
	v_mfma_f32_16x16x32_bf16 v[126:129], v[174:177], v[158:161], v[126:129]
	s_setprio 0
	s_add_i32 s61, s61, 0x6000
	s_cmp_eq_u32 s61, 0x12000
	s_cselect_b32 s61, 0, s61
	s_waitcnt lgkmcnt(0)
	s_barrier
	v_mfma_f32_16x16x32_bf16 v[2:5], v[210:213], v[178:181], v[2:5]
	v_mfma_f32_16x16x32_bf16 v[6:9], v[214:217], v[178:181], v[6:9]
	v_mfma_f32_16x16x32_bf16 v[10:13], v[218:221], v[178:181], v[10:13]
	v_mfma_f32_16x16x32_bf16 v[14:17], v[222:225], v[178:181], v[14:17]
	v_mfma_f32_16x16x32_bf16 v[18:21], v[210:213], v[182:185], v[18:21]
	v_mfma_f32_16x16x32_bf16 v[22:25], v[214:217], v[182:185], v[22:25]
	v_mfma_f32_16x16x32_bf16 v[26:29], v[218:221], v[182:185], v[26:29]
	v_mfma_f32_16x16x32_bf16 v[30:33], v[222:225], v[182:185], v[30:33]
	v_mfma_f32_16x16x32_bf16 v[34:37], v[210:213], v[186:189], v[34:37]
	v_mfma_f32_16x16x32_bf16 v[38:41], v[214:217], v[186:189], v[38:41]
	v_mfma_f32_16x16x32_bf16 v[42:45], v[218:221], v[186:189], v[42:45]
	v_mfma_f32_16x16x32_bf16 v[46:49], v[222:225], v[186:189], v[46:49]
	v_mfma_f32_16x16x32_bf16 v[50:53], v[210:213], v[190:193], v[50:53]
	v_mfma_f32_16x16x32_bf16 v[54:57], v[214:217], v[190:193], v[54:57]
	v_mfma_f32_16x16x32_bf16 v[58:61], v[218:221], v[190:193], v[58:61]
	v_mfma_f32_16x16x32_bf16 v[62:65], v[222:225], v[190:193], v[62:65]
	v_mfma_f32_16x16x32_bf16 v[66:69], v[210:213], v[194:197], v[66:69]
	v_mfma_f32_16x16x32_bf16 v[70:73], v[214:217], v[194:197], v[70:73]
	v_mfma_f32_16x16x32_bf16 v[74:77], v[218:221], v[194:197], v[74:77]
	v_mfma_f32_16x16x32_bf16 v[78:81], v[222:225], v[194:197], v[78:81]
	s_setprio 1
	v_mfma_f32_16x16x32_bf16 v[82:85], v[210:213], v[198:201], v[82:85]
	v_mfma_f32_16x16x32_bf16 v[86:89], v[214:217], v[198:201], v[86:89]
	v_mfma_f32_16x16x32_bf16 v[90:93], v[218:221], v[198:201], v[90:93]
	v_mfma_f32_16x16x32_bf16 v[94:97], v[222:225], v[198:201], v[94:97]
	v_mfma_f32_16x16x32_bf16 v[98:101], v[210:213], v[202:205], v[98:101]
	v_mfma_f32_16x16x32_bf16 v[102:105], v[214:217], v[202:205], v[102:105]
	v_mfma_f32_16x16x32_bf16 v[106:109], v[218:221], v[202:205], v[106:109]
	v_mfma_f32_16x16x32_bf16 v[110:113], v[222:225], v[202:205], v[110:113]
	v_mfma_f32_16x16x32_bf16 v[114:117], v[210:213], v[206:209], v[114:117]
	v_mfma_f32_16x16x32_bf16 v[118:121], v[214:217], v[206:209], v[118:121]
	v_mfma_f32_16x16x32_bf16 v[122:125], v[218:221], v[206:209], v[122:125]
	v_mfma_f32_16x16x32_bf16 v[126:129], v[222:225], v[206:209], v[126:129]
	s_setprio 0
	s_nop 7
	s_nop 1
	s_lshl_b32 s26, s35, 11
	s_lshl_b32 s27, s36, 1
	s_add_i32 s26, s26, s27
	s_add_u32 s18, s52, s26
	s_addc_u32 s19, s53, 0
	v_cvt_pk_bf16_f32 v2, v2, v3
	v_cvt_pk_bf16_f32 v3, v4, v5
	v_cvt_pk_bf16_f32 v4, v6, v7
	v_cvt_pk_bf16_f32 v5, v8, v9
	v_cvt_pk_bf16_f32 v6, v10, v11
	v_cvt_pk_bf16_f32 v7, v12, v13
	v_cvt_pk_bf16_f32 v8, v14, v15
	v_cvt_pk_bf16_f32 v9, v16, v17
	global_store_dwordx4 v242, v[2:5], s[18:19]
	global_store_dwordx4 v242, v[6:9], s[18:19] offset:16
	s_add_u32 s18, s18, 0x8000
	s_addc_u32 s19, s19, 0
	v_cvt_pk_bf16_f32 v18, v18, v19
	v_cvt_pk_bf16_f32 v19, v20, v21
	v_cvt_pk_bf16_f32 v20, v22, v23
	v_cvt_pk_bf16_f32 v21, v24, v25
	v_cvt_pk_bf16_f32 v22, v26, v27
	v_cvt_pk_bf16_f32 v23, v28, v29
	v_cvt_pk_bf16_f32 v24, v30, v31
	v_cvt_pk_bf16_f32 v25, v32, v33
	global_store_dwordx4 v242, v[18:21], s[18:19]
	global_store_dwordx4 v242, v[22:25], s[18:19] offset:16
	s_add_u32 s18, s18, 0x8000
	s_addc_u32 s19, s19, 0
	v_cvt_pk_bf16_f32 v34, v34, v35
	v_cvt_pk_bf16_f32 v35, v36, v37
	v_cvt_pk_bf16_f32 v36, v38, v39
	v_cvt_pk_bf16_f32 v37, v40, v41
	v_cvt_pk_bf16_f32 v38, v42, v43
	v_cvt_pk_bf16_f32 v39, v44, v45
	v_cvt_pk_bf16_f32 v40, v46, v47
	v_cvt_pk_bf16_f32 v41, v48, v49
	global_store_dwordx4 v242, v[34:37], s[18:19]
	global_store_dwordx4 v242, v[38:41], s[18:19] offset:16
	s_add_u32 s18, s18, 0x8000
	s_addc_u32 s19, s19, 0
	v_cvt_pk_bf16_f32 v50, v50, v51
	v_cvt_pk_bf16_f32 v51, v52, v53
	v_cvt_pk_bf16_f32 v52, v54, v55
	v_cvt_pk_bf16_f32 v53, v56, v57
	v_cvt_pk_bf16_f32 v54, v58, v59
	v_cvt_pk_bf16_f32 v55, v60, v61
	v_cvt_pk_bf16_f32 v56, v62, v63
	v_cvt_pk_bf16_f32 v57, v64, v65
	global_store_dwordx4 v242, v[50:53], s[18:19]
	global_store_dwordx4 v242, v[54:57], s[18:19] offset:16
	s_add_u32 s18, s18, 0x8000
	s_addc_u32 s19, s19, 0
	v_cvt_pk_bf16_f32 v66, v66, v67
	v_cvt_pk_bf16_f32 v67, v68, v69
	v_cvt_pk_bf16_f32 v68, v70, v71
	v_cvt_pk_bf16_f32 v69, v72, v73
	v_cvt_pk_bf16_f32 v70, v74, v75
	v_cvt_pk_bf16_f32 v71, v76, v77
	v_cvt_pk_bf16_f32 v72, v78, v79
	v_cvt_pk_bf16_f32 v73, v80, v81
	global_store_dwordx4 v242, v[66:69], s[18:19]
	global_store_dwordx4 v242, v[70:73], s[18:19] offset:16
	s_add_u32 s18, s18, 0x8000
	s_addc_u32 s19, s19, 0
	v_cvt_pk_bf16_f32 v82, v82, v83
	v_cvt_pk_bf16_f32 v83, v84, v85
	v_cvt_pk_bf16_f32 v84, v86, v87
	v_cvt_pk_bf16_f32 v85, v88, v89
	v_cvt_pk_bf16_f32 v86, v90, v91
	v_cvt_pk_bf16_f32 v87, v92, v93
	v_cvt_pk_bf16_f32 v88, v94, v95
	v_cvt_pk_bf16_f32 v89, v96, v97
	global_store_dwordx4 v242, v[82:85], s[18:19]
	global_store_dwordx4 v242, v[86:89], s[18:19] offset:16
	s_add_u32 s18, s18, 0x8000
	s_addc_u32 s19, s19, 0
	v_cvt_pk_bf16_f32 v98, v98, v99
	v_cvt_pk_bf16_f32 v99, v100, v101
	v_cvt_pk_bf16_f32 v100, v102, v103
	v_cvt_pk_bf16_f32 v101, v104, v105
	v_cvt_pk_bf16_f32 v102, v106, v107
	v_cvt_pk_bf16_f32 v103, v108, v109
	v_cvt_pk_bf16_f32 v104, v110, v111
	v_cvt_pk_bf16_f32 v105, v112, v113
	global_store_dwordx4 v242, v[98:101], s[18:19]
	global_store_dwordx4 v242, v[102:105], s[18:19] offset:16
	s_add_u32 s18, s18, 0x8000
	s_addc_u32 s19, s19, 0
	v_cvt_pk_bf16_f32 v114, v114, v115
	v_cvt_pk_bf16_f32 v115, v116, v117
	v_cvt_pk_bf16_f32 v116, v118, v119
	v_cvt_pk_bf16_f32 v117, v120, v121
	v_cvt_pk_bf16_f32 v118, v122, v123
	v_cvt_pk_bf16_f32 v119, v124, v125
	v_cvt_pk_bf16_f32 v120, v126, v127
	v_cvt_pk_bf16_f32 v121, v128, v129
	global_store_dwordx4 v242, v[114:117], s[18:19]
	global_store_dwordx4 v242, v[118:121], s[18:19] offset:16

.Lup_nn_a:
	s_waitcnt vmcnt(6) lgkmcnt(0)
	s_barrier
	v_add_u32_e32 v240, s61, v238
	v_add_u32_e32 v241, s61, v239
	s_add_i32 m0, s60, s62
	v_mfma_f32_16x16x32_bf16 v[2:5], v[162:165], v[130:133], 0
	global_load_lds_dwordx4 v226, s[54:55]
	v_mfma_f32_16x16x32_bf16 v[6:9], v[166:169], v[130:133], 0
	global_load_lds_dwordx4 v226, s[54:55] offset:1024
	v_mfma_f32_16x16x32_bf16 v[10:13], v[170:173], v[130:133], 0
	global_load_lds_dwordx4 v226, s[54:55] offset:2048
	v_mfma_f32_16x16x32_bf16 v[14:17], v[174:177], v[130:133], 0
	global_load_lds_dwordx4 v226, s[54:55] offset:3072
	s_add_i32 m0, s60, s63
	v_mfma_f32_16x16x32_bf16 v[18:21], v[162:165], v[134:137], 0
	global_load_lds_dwordx4 v230, s[56:57]
	v_mfma_f32_16x16x32_bf16 v[22:25], v[166:169], v[134:137], 0
	global_load_lds_dwordx4 v231, s[56:57] offset:1024
	v_mfma_f32_16x16x32_bf16 v[26:29], v[170:173], v[134:137], 0
	v_mfma_f32_16x16x32_bf16 v[30:33], v[174:177], v[134:137], 0
	v_mfma_f32_16x16x32_bf16 v[34:37], v[162:165], v[138:141], 0
	ds_read_b128 v[210:213], v241 offset:0
	v_mfma_f32_16x16x32_bf16 v[38:41], v[166:169], v[138:141], 0
	ds_read_b128 v[214:217], v241 offset:256
	v_mfma_f32_16x16x32_bf16 v[42:45], v[170:173], v[138:141], 0
	ds_read_b128 v[218:221], v241 offset:2048
	v_mfma_f32_16x16x32_bf16 v[46:49], v[174:177], v[138:141], 0
	ds_read_b128 v[222:225], v241 offset:2304
	v_mfma_f32_16x16x32_bf16 v[50:53], v[162:165], v[142:145], 0
	ds_read_b128 v[178:181], v240 offset:0
	v_mfma_f32_16x16x32_bf16 v[54:57], v[166:169], v[142:145], 0
	ds_read_b128 v[182:185], v240 offset:1024
	v_mfma_f32_16x16x32_bf16 v[58:61], v[170:173], v[142:145], 0
	ds_read_b128 v[186:189], v240 offset:2048
	v_mfma_f32_16x16x32_bf16 v[62:65], v[174:177], v[142:145], 0
	ds_read_b128 v[190:193], v240 offset:3072
	v_mfma_f32_16x16x32_bf16 v[66:69], v[162:165], v[146:149], 0
	ds_read_b128 v[194:197], v240 offset:4096
	v_mfma_f32_16x16x32_bf16 v[70:73], v[166:169], v[146:149], 0
	ds_read_b128 v[198:201], v240 offset:5120
	v_mfma_f32_16x16x32_bf16 v[74:77], v[170:173], v[146:149], 0
	ds_read_b128 v[202:205], v240 offset:6144
	v_mfma_f32_16x16x32_bf16 v[78:81], v[174:177], v[146:149], 0
	ds_read_b128 v[206:209], v240 offset:7168
	s_setprio 1
	v_mfma_f32_16x16x32_bf16 v[82:85], v[162:165], v[150:153], 0
	v_mfma_f32_16x16x32_bf16 v[86:89], v[166:169], v[150:153], 0
	v_mfma_f32_16x16x32_bf16 v[90:93], v[170:173], v[150:153], 0
	v_mfma_f32_16x16x32_bf16 v[94:97], v[174:177], v[150:153], 0
	v_mfma_f32_16x16x32_bf16 v[98:101], v[162:165], v[154:157], 0
	v_mfma_f32_16x16x32_bf16 v[102:105], v[166:169], v[154:157], 0
	v_mfma_f32_16x16x32_bf16 v[106:109], v[170:173], v[154:157], 0
	v_mfma_f32_16x16x32_bf16 v[110:113], v[174:177], v[154:157], 0
	v_mfma_f32_16x16x32_bf16 v[114:117], v[162:165], v[158:161], 0
	v_mfma_f32_16x16x32_bf16 v[118:121], v[166:169], v[158:161], 0
	v_mfma_f32_16x16x32_bf16 v[122:125], v[170:173], v[158:161], 0
	v_mfma_f32_16x16x32_bf16 v[126:129], v[174:177], v[158:161], 0
	s_setprio 0
	s_add_i32 s60, s60, 0x6000
	s_cmp_eq_u32 s60, 0x12000
	s_cselect_b32 s60, 0, s60
	s_add_u32 s54, s54, s72
	s_addc_u32 s55, s55, 0
	s_add_u32 s56, s56, s73
	s_addc_u32 s57, s57, 0
	s_add_i32 s61, s61, 0x6000
	s_cmp_eq_u32 s61, 0x12000
	s_cselect_b32 s61, 0, s61
	v_mbcnt_lo_u32_b32 v0, -1, 0
	v_lshlrev_b32_e32 v0, 4, v0
	s_lshl_b32 s26, s36, 1
	v_add_u32_e32 v0, s26, v0
	s_lshl_b32 s26, s41, 8
	s_add_i32 m0, s26, 0x13010
	s_mov_b64 exec, 0xffff
	global_load_lds_dwordx4 v0, s[82:83]
	s_mov_b64 exec, -1
	s_waitcnt vmcnt(6) lgkmcnt(0)
	s_barrier
	v_add_u32_e32 v240, s61, v238
	v_add_u32_e32 v241, s61, v239
	s_add_i32 m0, s60, s62
	v_mfma_f32_16x16x32_bf16 v[2:5], v[210:213], v[178:181], v[2:5]
	global_load_lds_dwordx4 v226, s[54:55]
	v_mfma_f32_16x16x32_bf16 v[6:9], v[214:217], v[178:181], v[6:9]
	global_load_lds_dwordx4 v226, s[54:55] offset:1024
	v_mfma_f32_16x16x32_bf16 v[10:13], v[218:221], v[178:181], v[10:13]
	global_load_lds_dwordx4 v226, s[54:55] offset:2048
	v_mfma_f32_16x16x32_bf16 v[14:17], v[222:225], v[178:181], v[14:17]
	global_load_lds_dwordx4 v226, s[54:55] offset:3072
	s_add_i32 m0, s60, s63
	v_mfma_f32_16x16x32_bf16 v[18:21], v[210:213], v[182:185], v[18:21]
	global_load_lds_dwordx4 v230, s[56:57]
	v_mfma_f32_16x16x32_bf16 v[22:25], v[214:217], v[182:185], v[22:25]
	global_load_lds_dwordx4 v231, s[56:57] offset:1024
	v_mfma_f32_16x16x32_bf16 v[26:29], v[218:221], v[182:185], v[26:29]
	v_mfma_f32_16x16x32_bf16 v[30:33], v[222:225], v[182:185], v[30:33]
	v_mfma_f32_16x16x32_bf16 v[34:37], v[210:213], v[186:189], v[34:37]
	ds_read_b128 v[162:165], v241 offset:0
	v_mfma_f32_16x16x32_bf16 v[38:41], v[214:217], v[186:189], v[38:41]
	ds_read_b128 v[166:169], v241 offset:256
	v_mfma_f32_16x16x32_bf16 v[42:45], v[218:221], v[186:189], v[42:45]
	ds_read_b128 v[170:173], v241 offset:2048
	v_mfma_f32_16x16x32_bf16 v[46:49], v[222:225], v[186:189], v[46:49]
	ds_read_b128 v[174:177], v241 offset:2304
	v_mfma_f32_16x16x32_bf16 v[50:53], v[210:213], v[190:193], v[50:53]
	ds_read_b128 v[130:133], v240 offset:0
	v_mfma_f32_16x16x32_bf16 v[54:57], v[214:217], v[190:193], v[54:57]
	ds_read_b128 v[134:137], v240 offset:1024
	v_mfma_f32_16x16x32_bf16 v[58:61], v[218:221], v[190:193], v[58:61]
	ds_read_b128 v[138:141], v240 offset:2048
	v_mfma_f32_16x16x32_bf16 v[62:65], v[222:225], v[190:193], v[62:65]
	ds_read_b128 v[142:145], v240 offset:3072
	v_mfma_f32_16x16x32_bf16 v[66:69], v[210:213], v[194:197], v[66:69]
	ds_read_b128 v[146:149], v240 offset:4096
	v_mfma_f32_16x16x32_bf16 v[70:73], v[214:217], v[194:197], v[70:73]
	ds_read_b128 v[150:153], v240 offset:5120
	v_mfma_f32_16x16x32_bf16 v[74:77], v[218:221], v[194:197], v[74:77]
	ds_read_b128 v[154:157], v240 offset:6144
	v_mfma_f32_16x16x32_bf16 v[78:81], v[222:225], v[194:197], v[78:81]
	ds_read_b128 v[158:161], v240 offset:7168
	s_setprio 1
	v_mfma_f32_16x16x32_bf16 v[82:85], v[210:213], v[198:201], v[82:85]
	v_mfma_f32_16x16x32_bf16 v[86:89], v[214:217], v[198:201], v[86:89]
	v_mfma_f32_16x16x32_bf16 v[90:93], v[218:221], v[198:201], v[90:93]
	v_mfma_f32_16x16x32_bf16 v[94:97], v[222:225], v[198:201], v[94:97]
	v_mfma_f32_16x16x32_bf16 v[98:101], v[210:213], v[202:205], v[98:101]
	v_mfma_f32_16x16x32_bf16 v[102:105], v[214:217], v[202:205], v[102:105]
	v_mfma_f32_16x16x32_bf16 v[106:109], v[218:221], v[202:205], v[106:109]
	v_mfma_f32_16x16x32_bf16 v[110:113], v[222:225], v[202:205], v[110:113]
	v_mfma_f32_16x16x32_bf16 v[114:117], v[210:213], v[206:209], v[114:117]
	v_mfma_f32_16x16x32_bf16 v[118:121], v[214:217], v[206:209], v[118:121]
	v_mfma_f32_16x16x32_bf16 v[122:125], v[218:221], v[206:209], v[122:125]
	v_mfma_f32_16x16x32_bf16 v[126:129], v[222:225], v[206:209], v[126:129]
	s_setprio 0
	s_add_i32 s60, s60, 0x6000
	s_cmp_eq_u32 s60, 0x12000
	s_cselect_b32 s60, 0, s60
	s_add_u32 s54, s54, s72
	s_addc_u32 s55, s55, 0
	s_add_u32 s56, s56, s73
	s_addc_u32 s57, s57, 0
	s_add_i32 s61, s61, 0x6000
	s_cmp_eq_u32 s61, 0x12000
	s_cselect_b32 s61, 0, s61
	s_branch .Lup_main

.Lup_nn_b:
	s_waitcnt vmcnt(14) lgkmcnt(0)
	s_barrier
	v_add_u32_e32 v240, s61, v238
	v_add_u32_e32 v241, s61, v239
	s_add_i32 m0, s60, s62
	v_mfma_f32_16x16x32_bf16 v[2:5], v[162:165], v[130:133], 0
	global_load_lds_dwordx4 v226, s[54:55]
	v_mfma_f32_16x16x32_bf16 v[6:9], v[166:169], v[130:133], 0
	global_load_lds_dwordx4 v226, s[54:55] offset:1024
	v_mfma_f32_16x16x32_bf16 v[10:13], v[170:173], v[130:133], 0
	global_load_lds_dwordx4 v226, s[54:55] offset:2048
	v_mfma_f32_16x16x32_bf16 v[14:17], v[174:177], v[130:133], 0
	global_load_lds_dwordx4 v226, s[54:55] offset:3072
	s_add_i32 m0, s60, s63
	v_mfma_f32_16x16x32_bf16 v[18:21], v[162:165], v[134:137], 0
	global_load_lds_dwordx4 v230, s[56:57]
	v_mfma_f32_16x16x32_bf16 v[22:25], v[166:169], v[134:137], 0
	global_load_lds_dwordx4 v231, s[56:57] offset:1024
	v_mfma_f32_16x16x32_bf16 v[26:29], v[170:173], v[134:137], 0
	v_mfma_f32_16x16x32_bf16 v[30:33], v[174:177], v[134:137], 0
	v_mfma_f32_16x16x32_bf16 v[34:37], v[162:165], v[138:141], 0
	ds_read_b128 v[210:213], v241 offset:0
	v_mfma_f32_16x16x32_bf16 v[38:41], v[166:169], v[138:141], 0
	ds_read_b128 v[214:217], v241 offset:256
	v_mfma_f32_16x16x32_bf16 v[42:45], v[170:173], v[138:141], 0
	ds_read_b128 v[218:221], v241 offset:2048
	v_mfma_f32_16x16x32_bf16 v[46:49], v[174:177], v[138:141], 0
	ds_read_b128 v[222:225], v241 offset:2304
	v_mfma_f32_16x16x32_bf16 v[50:53], v[162:165], v[142:145], 0
	ds_read_b128 v[178:181], v240 offset:0
	v_mfma_f32_16x16x32_bf16 v[54:57], v[166:169], v[142:145], 0
	ds_read_b128 v[182:185], v240 offset:1024
	v_mfma_f32_16x16x32_bf16 v[58:61], v[170:173], v[142:145], 0
	ds_read_b128 v[186:189], v240 offset:2048
	v_mfma_f32_16x16x32_bf16 v[62:65], v[174:177], v[142:145], 0
	ds_read_b128 v[190:193], v240 offset:3072
	v_mfma_f32_16x16x32_bf16 v[66:69], v[162:165], v[146:149], 0
	ds_read_b128 v[194:197], v240 offset:4096
	v_mfma_f32_16x16x32_bf16 v[70:73], v[166:169], v[146:149], 0
	ds_read_b128 v[198:201], v240 offset:5120
	v_mfma_f32_16x16x32_bf16 v[74:77], v[170:173], v[146:149], 0
	ds_read_b128 v[202:205], v240 offset:6144
	v_mfma_f32_16x16x32_bf16 v[78:81], v[174:177], v[146:149], 0
	ds_read_b128 v[206:209], v240 offset:7168
	s_setprio 1
	v_mfma_f32_16x16x32_bf16 v[82:85], v[162:165], v[150:153], 0
	v_mfma_f32_16x16x32_bf16 v[86:89], v[166:169], v[150:153], 0
	v_mfma_f32_16x16x32_bf16 v[90:93], v[170:173], v[150:153], 0
	v_mfma_f32_16x16x32_bf16 v[94:97], v[174:177], v[150:153], 0
	v_mfma_f32_16x16x32_bf16 v[98:101], v[162:165], v[154:157], 0
	v_mfma_f32_16x16x32_bf16 v[102:105], v[166:169], v[154:157], 0
	v_mfma_f32_16x16x32_bf16 v[106:109], v[170:173], v[154:157], 0
	v_mfma_f32_16x16x32_bf16 v[110:113], v[174:177], v[154:157], 0
	v_mfma_f32_16x16x32_bf16 v[114:117], v[162:165], v[158:161], 0
	v_mfma_f32_16x16x32_bf16 v[118:121], v[166:169], v[158:161], 0
	v_mfma_f32_16x16x32_bf16 v[122:125], v[170:173], v[158:161], 0
	v_mfma_f32_16x16x32_bf16 v[126:129], v[174:177], v[158:161], 0
	s_setprio 0
	s_add_i32 s60, s60, 0x6000
	s_cmp_eq_u32 s60, 0x12000
	s_cselect_b32 s60, 0, s60
	s_add_u32 s54, s54, s72
	s_addc_u32 s55, s55, 0
	s_add_u32 s56, s56, s73
	s_addc_u32 s57, s57, 0
	s_add_i32 s61, s61, 0x6000
	s_cmp_eq_u32 s61, 0x12000
	s_cselect_b32 s61, 0, s61
	v_mbcnt_lo_u32_b32 v0, -1, 0
	v_lshlrev_b32_e32 v0, 4, v0
	s_lshl_b32 s26, s36, 1
	v_add_u32_e32 v0, s26, v0
	s_lshl_b32 s26, s41, 8
	s_add_i32 m0, s26, 0x13010
	s_mov_b64 exec, 0xffff
	global_load_lds_dwordx4 v0, s[82:83]
	s_mov_b64 exec, -1
	s_waitcnt vmcnt(14) lgkmcnt(0)
	s_barrier
	v_add_u32_e32 v240, s61, v238
	v_add_u32_e32 v241, s61, v239
	s_add_i32 m0, s60, s62
	v_mfma_f32_16x16x32_bf16 v[2:5], v[210:213], v[178:181], v[2:5]
	global_load_lds_dwordx4 v226, s[54:55]
	v_mfma_f32_16x16x32_bf16 v[6:9], v[214:217], v[178:181], v[6:9]
	global_load_lds_dwordx4 v226, s[54:55] offset:1024
	v_mfma_f32_16x16x32_bf16 v[10:13], v[218:221], v[178:181], v[10:13]
	global_load_lds_dwordx4 v226, s[54:55] offset:2048
	v_mfma_f32_16x16x32_bf16 v[14:17], v[222:225], v[178:181], v[14:17]
	global_load_lds_dwordx4 v226, s[54:55] offset:3072
	s_add_i32 m0, s60, s63
	v_mfma_f32_16x16x32_bf16 v[18:21], v[210:213], v[182:185], v[18:21]
	global_load_lds_dwordx4 v230, s[56:57]
	v_mfma_f32_16x16x32_bf16 v[22:25], v[214:217], v[182:185], v[22:25]
	global_load_lds_dwordx4 v231, s[56:57] offset:1024
	v_mfma_f32_16x16x32_bf16 v[26:29], v[218:221], v[182:185], v[26:29]
	v_mfma_f32_16x16x32_bf16 v[30:33], v[222:225], v[182:185], v[30:33]
	v_mfma_f32_16x16x32_bf16 v[34:37], v[210:213], v[186:189], v[34:37]
	ds_read_b128 v[162:165], v241 offset:0
	v_mfma_f32_16x16x32_bf16 v[38:41], v[214:217], v[186:189], v[38:41]
	ds_read_b128 v[166:169], v241 offset:256
	v_mfma_f32_16x16x32_bf16 v[42:45], v[218:221], v[186:189], v[42:45]
	ds_read_b128 v[170:173], v241 offset:2048
	v_mfma_f32_16x16x32_bf16 v[46:49], v[222:225], v[186:189], v[46:49]
	ds_read_b128 v[174:177], v241 offset:2304
	v_mfma_f32_16x16x32_bf16 v[50:53], v[210:213], v[190:193], v[50:53]
	ds_read_b128 v[130:133], v240 offset:0
	v_mfma_f32_16x16x32_bf16 v[54:57], v[214:217], v[190:193], v[54:57]
	ds_read_b128 v[134:137], v240 offset:1024
	v_mfma_f32_16x16x32_bf16 v[58:61], v[218:221], v[190:193], v[58:61]
	ds_read_b128 v[138:141], v240 offset:2048
	v_mfma_f32_16x16x32_bf16 v[62:65], v[222:225], v[190:193], v[62:65]
	ds_read_b128 v[142:145], v240 offset:3072
	v_mfma_f32_16x16x32_bf16 v[66:69], v[210:213], v[194:197], v[66:69]
	ds_read_b128 v[146:149], v240 offset:4096
	v_mfma_f32_16x16x32_bf16 v[70:73], v[214:217], v[194:197], v[70:73]
	ds_read_b128 v[150:153], v240 offset:5120
	v_mfma_f32_16x16x32_bf16 v[74:77], v[218:221], v[194:197], v[74:77]
	ds_read_b128 v[154:157], v240 offset:6144
	v_mfma_f32_16x16x32_bf16 v[78:81], v[222:225], v[194:197], v[78:81]
	ds_read_b128 v[158:161], v240 offset:7168
	s_setprio 1
	v_mfma_f32_16x16x32_bf16 v[82:85], v[210:213], v[198:201], v[82:85]
	v_mfma_f32_16x16x32_bf16 v[86:89], v[214:217], v[198:201], v[86:89]
	v_mfma_f32_16x16x32_bf16 v[90:93], v[218:221], v[198:201], v[90:93]
	v_mfma_f32_16x16x32_bf16 v[94:97], v[222:225], v[198:201], v[94:97]
	v_mfma_f32_16x16x32_bf16 v[98:101], v[210:213], v[202:205], v[98:101]
	v_mfma_f32_16x16x32_bf16 v[102:105], v[214:217], v[202:205], v[102:105]
	v_mfma_f32_16x16x32_bf16 v[106:109], v[218:221], v[202:205], v[106:109]
	v_mfma_f32_16x16x32_bf16 v[110:113], v[222:225], v[202:205], v[110:113]
	v_mfma_f32_16x16x32_bf16 v[114:117], v[210:213], v[206:209], v[114:117]
	v_mfma_f32_16x16x32_bf16 v[118:121], v[214:217], v[206:209], v[118:121]
	v_mfma_f32_16x16x32_bf16 v[122:125], v[218:221], v[206:209], v[122:125]
	v_mfma_f32_16x16x32_bf16 v[126:129], v[222:225], v[206:209], v[126:129]
	s_setprio 0
	s_add_i32 s60, s60, 0x6000
	s_cmp_eq_u32 s60, 0x12000
	s_cselect_b32 s60, 0, s60
	s_add_u32 s54, s54, s72
	s_addc_u32 s55, s55, 0
	s_add_u32 s56, s56, s73
	s_addc_u32 s57, s57, 0
	s_add_i32 s61, s61, 0x6000
	s_cmp_eq_u32 s61, 0x12000
	s_cselect_b32 s61, 0, s61

.Lup_kloop:
	s_waitcnt vmcnt(6) lgkmcnt(0)
	s_barrier
	v_add_u32_e32 v240, s61, v238
	v_add_u32_e32 v241, s61, v239
	s_add_i32 m0, s60, s62
	v_mfma_f32_16x16x32_bf16 v[2:5], v[162:165], v[130:133], v[2:5]
	global_load_lds_dwordx4 v226, s[54:55]
	v_mfma_f32_16x16x32_bf16 v[6:9], v[166:169], v[130:133], v[6:9]
	global_load_lds_dwordx4 v226, s[54:55] offset:1024
	v_mfma_f32_16x16x32_bf16 v[10:13], v[170:173], v[130:133], v[10:13]
	global_load_lds_dwordx4 v226, s[54:55] offset:2048
	v_mfma_f32_16x16x32_bf16 v[14:17], v[174:177], v[130:133], v[14:17]
	global_load_lds_dwordx4 v226, s[54:55] offset:3072
	s_add_i32 m0, s60, s63
	v_mfma_f32_16x16x32_bf16 v[18:21], v[162:165], v[134:137], v[18:21]
	global_load_lds_dwordx4 v230, s[56:57]
	v_mfma_f32_16x16x32_bf16 v[22:25], v[166:169], v[134:137], v[22:25]
	global_load_lds_dwordx4 v231, s[56:57] offset:1024
	v_mfma_f32_16x16x32_bf16 v[26:29], v[170:173], v[134:137], v[26:29]
	v_mfma_f32_16x16x32_bf16 v[30:33], v[174:177], v[134:137], v[30:33]
	v_mfma_f32_16x16x32_bf16 v[34:37], v[162:165], v[138:141], v[34:37]
	ds_read_b128 v[210:213], v241 offset:0
	v_mfma_f32_16x16x32_bf16 v[38:41], v[166:169], v[138:141], v[38:41]
	ds_read_b128 v[214:217], v241 offset:256
	v_mfma_f32_16x16x32_bf16 v[42:45], v[170:173], v[138:141], v[42:45]
	ds_read_b128 v[218:221], v241 offset:2048
	v_mfma_f32_16x16x32_bf16 v[46:49], v[174:177], v[138:141], v[46:49]
	ds_read_b128 v[222:225], v241 offset:2304
	v_mfma_f32_16x16x32_bf16 v[50:53], v[162:165], v[142:145], v[50:53]
	ds_read_b128 v[178:181], v240 offset:0
	v_mfma_f32_16x16x32_bf16 v[54:57], v[166:169], v[142:145], v[54:57]
	ds_read_b128 v[182:185], v240 offset:1024
	v_mfma_f32_16x16x32_bf16 v[58:61], v[170:173], v[142:145], v[58:61]
	ds_read_b128 v[186:189], v240 offset:2048
	v_mfma_f32_16x16x32_bf16 v[62:65], v[174:177], v[142:145], v[62:65]
	ds_read_b128 v[190:193], v240 offset:3072
	v_mfma_f32_16x16x32_bf16 v[66:69], v[162:165], v[146:149], v[66:69]
	ds_read_b128 v[194:197], v240 offset:4096
	v_mfma_f32_16x16x32_bf16 v[70:73], v[166:169], v[146:149], v[70:73]
	ds_read_b128 v[198:201], v240 offset:5120
	v_mfma_f32_16x16x32_bf16 v[74:77], v[170:173], v[146:149], v[74:77]
	ds_read_b128 v[202:205], v240 offset:6144
	v_mfma_f32_16x16x32_bf16 v[78:81], v[174:177], v[146:149], v[78:81]
	ds_read_b128 v[206:209], v240 offset:7168
	s_setprio 1
	v_mfma_f32_16x16x32_bf16 v[82:85], v[162:165], v[150:153], v[82:85]
	v_mfma_f32_16x16x32_bf16 v[86:89], v[166:169], v[150:153], v[86:89]
	v_mfma_f32_16x16x32_bf16 v[90:93], v[170:173], v[150:153], v[90:93]
	v_mfma_f32_16x16x32_bf16 v[94:97], v[174:177], v[150:153], v[94:97]
	v_mfma_f32_16x16x32_bf16 v[98:101], v[162:165], v[154:157], v[98:101]
	v_mfma_f32_16x16x32_bf16 v[102:105], v[166:169], v[154:157], v[102:105]
	v_mfma_f32_16x16x32_bf16 v[106:109], v[170:173], v[154:157], v[106:109]
	v_mfma_f32_16x16x32_bf16 v[110:113], v[174:177], v[154:157], v[110:113]
	v_mfma_f32_16x16x32_bf16 v[114:117], v[162:165], v[158:161], v[114:117]
	v_mfma_f32_16x16x32_bf16 v[118:121], v[166:169], v[158:161], v[118:121]
	v_mfma_f32_16x16x32_bf16 v[122:125], v[170:173], v[158:161], v[122:125]
	v_mfma_f32_16x16x32_bf16 v[126:129], v[174:177], v[158:161], v[126:129]
	s_setprio 0
	s_add_i32 s60, s60, 0x6000
	s_cmp_eq_u32 s60, 0x12000
	s_cselect_b32 s60, 0, s60
	s_add_u32 s54, s54, s72
	s_addc_u32 s55, s55, 0
	s_add_u32 s56, s56, s73
	s_addc_u32 s57, s57, 0
	s_add_i32 s61, s61, 0x6000
	s_cmp_eq_u32 s61, 0x12000
	s_cselect_b32 s61, 0, s61
	s_waitcnt vmcnt(6) lgkmcnt(0)
	s_barrier
	v_add_u32_e32 v240, s61, v238
	v_add_u32_e32 v241, s61, v239
	s_add_i32 m0, s60, s62
	v_mfma_f32_16x16x32_bf16 v[2:5], v[210:213], v[178:181], v[2:5]
	global_load_lds_dwordx4 v226, s[54:55]
	v_mfma_f32_16x16x32_bf16 v[6:9], v[214:217], v[178:181], v[6:9]
	global_load_lds_dwordx4 v226, s[54:55] offset:1024
	v_mfma_f32_16x16x32_bf16 v[10:13], v[218:221], v[178:181], v[10:13]
	global_load_lds_dwordx4 v226, s[54:55] offset:2048
	v_mfma_f32_16x16x32_bf16 v[14:17], v[222:225], v[178:181], v[14:17]
	global_load_lds_dwordx4 v226, s[54:55] offset:3072
	s_add_i32 m0, s60, s63
	v_mfma_f32_16x16x32_bf16 v[18:21], v[210:213], v[182:185], v[18:21]
	global_load_lds_dwordx4 v230, s[56:57]
	v_mfma_f32_16x16x32_bf16 v[22:25], v[214:217], v[182:185], v[22:25]
	global_load_lds_dwordx4 v231, s[56:57] offset:1024
	v_mfma_f32_16x16x32_bf16 v[26:29], v[218:221], v[182:185], v[26:29]
	v_mfma_f32_16x16x32_bf16 v[30:33], v[222:225], v[182:185], v[30:33]
	v_mfma_f32_16x16x32_bf16 v[34:37], v[210:213], v[186:189], v[34:37]
	ds_read_b128 v[162:165], v241 offset:0
	v_mfma_f32_16x16x32_bf16 v[38:41], v[214:217], v[186:189], v[38:41]
	ds_read_b128 v[166:169], v241 offset:256
	v_mfma_f32_16x16x32_bf16 v[42:45], v[218:221], v[186:189], v[42:45]
	ds_read_b128 v[170:173], v241 offset:2048
	v_mfma_f32_16x16x32_bf16 v[46:49], v[222:225], v[186:189], v[46:49]
	ds_read_b128 v[174:177], v241 offset:2304
	v_mfma_f32_16x16x32_bf16 v[50:53], v[210:213], v[190:193], v[50:53]
	ds_read_b128 v[130:133], v240 offset:0
	v_mfma_f32_16x16x32_bf16 v[54:57], v[214:217], v[190:193], v[54:57]
	ds_read_b128 v[134:137], v240 offset:1024
	v_mfma_f32_16x16x32_bf16 v[58:61], v[218:221], v[190:193], v[58:61]
	ds_read_b128 v[138:141], v240 offset:2048
	v_mfma_f32_16x16x32_bf16 v[62:65], v[222:225], v[190:193], v[62:65]
	ds_read_b128 v[142:145], v240 offset:3072
	v_mfma_f32_16x16x32_bf16 v[66:69], v[210:213], v[194:197], v[66:69]
	ds_read_b128 v[146:149], v240 offset:4096
	v_mfma_f32_16x16x32_bf16 v[70:73], v[214:217], v[194:197], v[70:73]
	ds_read_b128 v[150:153], v240 offset:5120
	v_mfma_f32_16x16x32_bf16 v[74:77], v[218:221], v[194:197], v[74:77]
	ds_read_b128 v[154:157], v240 offset:6144
	v_mfma_f32_16x16x32_bf16 v[78:81], v[222:225], v[194:197], v[78:81]
	ds_read_b128 v[158:161], v240 offset:7168
	s_setprio 1
	v_mfma_f32_16x16x32_bf16 v[82:85], v[210:213], v[198:201], v[82:85]
	v_mfma_f32_16x16x32_bf16 v[86:89], v[214:217], v[198:201], v[86:89]
	v_mfma_f32_16x16x32_bf16 v[90:93], v[218:221], v[198:201], v[90:93]
	v_mfma_f32_16x16x32_bf16 v[94:97], v[222:225], v[198:201], v[94:97]
	v_mfma_f32_16x16x32_bf16 v[98:101], v[210:213], v[202:205], v[98:101]
	v_mfma_f32_16x16x32_bf16 v[102:105], v[214:217], v[202:205], v[102:105]
	v_mfma_f32_16x16x32_bf16 v[106:109], v[218:221], v[202:205], v[106:109]
	v_mfma_f32_16x16x32_bf16 v[110:113], v[222:225], v[202:205], v[110:113]
	v_mfma_f32_16x16x32_bf16 v[114:117], v[210:213], v[206:209], v[114:117]
	v_mfma_f32_16x16x32_bf16 v[118:121], v[214:217], v[206:209], v[118:121]
	v_mfma_f32_16x16x32_bf16 v[122:125], v[218:221], v[206:209], v[122:125]
	v_mfma_f32_16x16x32_bf16 v[126:129], v[222:225], v[206:209], v[126:129]
	s_setprio 0
	s_add_i32 s60, s60, 0x6000
	s_cmp_eq_u32 s60, 0x12000
	s_cselect_b32 s60, 0, s60
	s_add_u32 s54, s54, s72
	s_addc_u32 s55, s55, 0
	s_add_u32 s56, s56, s73
	s_addc_u32 s57, s57, 0
	s_add_i32 s61, s61, 0x6000
	s_cmp_eq_u32 s61, 0x12000
	s_cselect_b32 s61, 0, s61
	s_add_i32 s40, s40, -1
	s_cmp_lg_u32 s40, 0
	s_cbranch_scc1 .Lup_kloop
	s_cmp_eq_u32 s37, 0
	s_cbranch_scc1 .Lup_tail_last
	s_waitcnt vmcnt(6) lgkmcnt(0)
	s_barrier
	v_add_u32_e32 v240, s61, v238
	v_add_u32_e32 v241, s61, v239
	s_add_i32 m0, s60, s62
	v_mfma_f32_16x16x32_bf16 v[2:5], v[162:165], v[130:133], v[2:5]
	global_load_lds_dwordx4 v226, s[54:55]
	v_mfma_f32_16x16x32_bf16 v[6:9], v[166:169], v[130:133], v[6:9]
	global_load_lds_dwordx4 v226, s[54:55] offset:1024
	v_mfma_f32_16x16x32_bf16 v[10:13], v[170:173], v[130:133], v[10:13]
	global_load_lds_dwordx4 v226, s[54:55] offset:2048
	v_mfma_f32_16x16x32_bf16 v[14:17], v[174:177], v[130:133], v[14:17]
	global_load_lds_dwordx4 v226, s[54:55] offset:3072
	s_add_i32 m0, s60, s63
	v_mfma_f32_16x16x32_bf16 v[18:21], v[162:165], v[134:137], v[18:21]
	global_load_lds_dwordx4 v230, s[56:57]
	v_mfma_f32_16x16x32_bf16 v[22:25], v[166:169], v[134:137], v[22:25]
	global_load_lds_dwordx4 v231, s[56:57] offset:1024
	v_mfma_f32_16x16x32_bf16 v[26:29], v[170:173], v[134:137], v[26:29]
	v_mfma_f32_16x16x32_bf16 v[30:33], v[174:177], v[134:137], v[30:33]
	v_mfma_f32_16x16x32_bf16 v[34:37], v[162:165], v[138:141], v[34:37]
	ds_read_b128 v[210:213], v241 offset:0
	v_mfma_f32_16x16x32_bf16 v[38:41], v[166:169], v[138:141], v[38:41]
	ds_read_b128 v[214:217], v241 offset:256
	v_mfma_f32_16x16x32_bf16 v[42:45], v[170:173], v[138:141], v[42:45]
	ds_read_b128 v[218:221], v241 offset:2048
	v_mfma_f32_16x16x32_bf16 v[46:49], v[174:177], v[138:141], v[46:49]
	ds_read_b128 v[222:225], v241 offset:2304
	v_mfma_f32_16x16x32_bf16 v[50:53], v[162:165], v[142:145], v[50:53]
	ds_read_b128 v[178:181], v240 offset:0
	v_mfma_f32_16x16x32_bf16 v[54:57], v[166:169], v[142:145], v[54:57]
	ds_read_b128 v[182:185], v240 offset:1024
	v_mfma_f32_16x16x32_bf16 v[58:61], v[170:173], v[142:145], v[58:61]
	ds_read_b128 v[186:189], v240 offset:2048
	v_mfma_f32_16x16x32_bf16 v[62:65], v[174:177], v[142:145], v[62:65]
	ds_read_b128 v[190:193], v240 offset:3072
	v_mfma_f32_16x16x32_bf16 v[66:69], v[162:165], v[146:149], v[66:69]
	ds_read_b128 v[194:197], v240 offset:4096
	v_mfma_f32_16x16x32_bf16 v[70:73], v[166:169], v[146:149], v[70:73]
	ds_read_b128 v[198:201], v240 offset:5120
	v_mfma_f32_16x16x32_bf16 v[74:77], v[170:173], v[146:149], v[74:77]
	ds_read_b128 v[202:205], v240 offset:6144
	v_mfma_f32_16x16x32_bf16 v[78:81], v[174:177], v[146:149], v[78:81]
	ds_read_b128 v[206:209], v240 offset:7168
	s_setprio 1
	v_mfma_f32_16x16x32_bf16 v[82:85], v[162:165], v[150:153], v[82:85]
	v_mfma_f32_16x16x32_bf16 v[86:89], v[166:169], v[150:153], v[86:89]
	v_mfma_f32_16x16x32_bf16 v[90:93], v[170:173], v[150:153], v[90:93]
	v_mfma_f32_16x16x32_bf16 v[94:97], v[174:177], v[150:153], v[94:97]
	v_mfma_f32_16x16x32_bf16 v[98:101], v[162:165], v[154:157], v[98:101]
	v_mfma_f32_16x16x32_bf16 v[102:105], v[166:169], v[154:157], v[102:105]
	v_mfma_f32_16x16x32_bf16 v[106:109], v[170:173], v[154:157], v[106:109]
	v_mfma_f32_16x16x32_bf16 v[110:113], v[174:177], v[154:157], v[110:113]
	v_mfma_f32_16x16x32_bf16 v[114:117], v[162:165], v[158:161], v[114:117]
	v_mfma_f32_16x16x32_bf16 v[118:121], v[166:169], v[158:161], v[118:121]
	v_mfma_f32_16x16x32_bf16 v[122:125], v[170:173], v[158:161], v[122:125]
	v_mfma_f32_16x16x32_bf16 v[126:129], v[174:177], v[158:161], v[126:129]
	s_setprio 0
	s_add_i32 s60, s60, 0x6000
	s_cmp_eq_u32 s60, 0x12000
	s_cselect_b32 s60, 0, s60
	s_add_u32 s54, s54, s72
	s_addc_u32 s55, s55, 0
	s_add_u32 s56, s56, s73
	s_addc_u32 s57, s57, 0
	s_add_i32 s61, s61, 0x6000
	s_cmp_eq_u32 s61, 0x12000
	s_cselect_b32 s61, 0, s61
	v_mov_b32_e32 v226, v232
	v_mov_b32_e32 v230, v236
	v_mov_b32_e32 v231, v237
	s_mov_b64 s[54:55], s[48:49]
	s_mov_b64 s[56:57], s[50:51]
	s_waitcnt vmcnt(6) lgkmcnt(0)
	s_barrier
	v_add_u32_e32 v240, s61, v238
	v_add_u32_e32 v241, s61, v239
	s_add_i32 m0, s60, s62
	v_mfma_f32_16x16x32_bf16 v[2:5], v[210:213], v[178:181], v[2:5]
	global_load_lds_dwordx4 v226, s[54:55]
	v_mfma_f32_16x16x32_bf16 v[6:9], v[214:217], v[178:181], v[6:9]
	global_load_lds_dwordx4 v226, s[54:55] offset:1024
	v_mfma_f32_16x16x32_bf16 v[10:13], v[218:221], v[178:181], v[10:13]
	global_load_lds_dwordx4 v226, s[54:55] offset:2048
	v_mfma_f32_16x16x32_bf16 v[14:17], v[222:225], v[178:181], v[14:17]
	global_load_lds_dwordx4 v226, s[54:55] offset:3072
	s_add_i32 m0, s60, s63
	v_mfma_f32_16x16x32_bf16 v[18:21], v[210:213], v[182:185], v[18:21]
	global_load_lds_dwordx4 v230, s[56:57]
	v_mfma_f32_16x16x32_bf16 v[22:25], v[214:217], v[182:185], v[22:25]
	global_load_lds_dwordx4 v231, s[56:57] offset:1024
	v_mfma_f32_16x16x32_bf16 v[26:29], v[218:221], v[182:185], v[26:29]
	v_mfma_f32_16x16x32_bf16 v[30:33], v[222:225], v[182:185], v[30:33]
	v_mfma_f32_16x16x32_bf16 v[34:37], v[210:213], v[186:189], v[34:37]
	ds_read_b128 v[162:165], v241 offset:0
	v_mfma_f32_16x16x32_bf16 v[38:41], v[214:217], v[186:189], v[38:41]
	ds_read_b128 v[166:169], v241 offset:256
	v_mfma_f32_16x16x32_bf16 v[42:45], v[218:221], v[186:189], v[42:45]
	ds_read_b128 v[170:173], v241 offset:2048
	v_mfma_f32_16x16x32_bf16 v[46:49], v[222:225], v[186:189], v[46:49]
	ds_read_b128 v[174:177], v241 offset:2304
	v_mfma_f32_16x16x32_bf16 v[50:53], v[210:213], v[190:193], v[50:53]
	ds_read_b128 v[130:133], v240 offset:0
	v_mfma_f32_16x16x32_bf16 v[54:57], v[214:217], v[190:193], v[54:57]
	ds_read_b128 v[134:137], v240 offset:1024
	v_mfma_f32_16x16x32_bf16 v[58:61], v[218:221], v[190:193], v[58:61]
	ds_read_b128 v[138:141], v240 offset:2048
	v_mfma_f32_16x16x32_bf16 v[62:65], v[222:225], v[190:193], v[62:65]
	ds_read_b128 v[142:145], v240 offset:3072
	v_mfma_f32_16x16x32_bf16 v[66:69], v[210:213], v[194:197], v[66:69]
	ds_read_b128 v[146:149], v240 offset:4096
	v_mfma_f32_16x16x32_bf16 v[70:73], v[214:217], v[194:197], v[70:73]
	ds_read_b128 v[150:153], v240 offset:5120
	v_mfma_f32_16x16x32_bf16 v[74:77], v[218:221], v[194:197], v[74:77]
	ds_read_b128 v[154:157], v240 offset:6144
	v_mfma_f32_16x16x32_bf16 v[78:81], v[222:225], v[194:197], v[78:81]
	ds_read_b128 v[158:161], v240 offset:7168
	s_setprio 1
	v_mfma_f32_16x16x32_bf16 v[82:85], v[210:213], v[198:201], v[82:85]
	v_mfma_f32_16x16x32_bf16 v[86:89], v[214:217], v[198:201], v[86:89]
	v_mfma_f32_16x16x32_bf16 v[90:93], v[218:221], v[198:201], v[90:93]
	v_mfma_f32_16x16x32_bf16 v[94:97], v[222:225], v[198:201], v[94:97]
	v_mfma_f32_16x16x32_bf16 v[98:101], v[210:213], v[202:205], v[98:101]
	v_mfma_f32_16x16x32_bf16 v[102:105], v[214:217], v[202:205], v[102:105]
	v_mfma_f32_16x16x32_bf16 v[106:109], v[218:221], v[202:205], v[106:109]
	v_mfma_f32_16x16x32_bf16 v[110:113], v[222:225], v[202:205], v[110:113]
	v_mfma_f32_16x16x32_bf16 v[114:117], v[210:213], v[206:209], v[114:117]
	v_mfma_f32_16x16x32_bf16 v[118:121], v[214:217], v[206:209], v[118:121]
	v_mfma_f32_16x16x32_bf16 v[122:125], v[218:221], v[206:209], v[122:125]
	v_mfma_f32_16x16x32_bf16 v[126:129], v[222:225], v[206:209], v[126:129]
	s_setprio 0
	s_add_i32 s60, s60, 0x6000
	s_cmp_eq_u32 s60, 0x12000
	s_cselect_b32 s60, 0, s60
	s_add_u32 s54, s54, s72
	s_addc_u32 s55, s55, 0
	s_add_u32 s56, s56, s73
	s_addc_u32 s57, s57, 0
	s_add_i32 s61, s61, 0x6000
	s_cmp_eq_u32 s61, 0x12000
	s_cselect_b32 s61, 0, s61
	s_waitcnt vmcnt(6) lgkmcnt(0)
	s_barrier
	v_add_u32_e32 v240, s61, v238
	v_add_u32_e32 v241, s61, v239
	s_add_i32 m0, s60, s62
	v_mfma_f32_16x16x32_bf16 v[2:5], v[162:165], v[130:133], v[2:5]
	global_load_lds_dwordx4 v226, s[54:55]
	v_mfma_f32_16x16x32_bf16 v[6:9], v[166:169], v[130:133], v[6:9]
	global_load_lds_dwordx4 v226, s[54:55] offset:1024
	v_mfma_f32_16x16x32_bf16 v[10:13], v[170:173], v[130:133], v[10:13]
	global_load_lds_dwordx4 v226, s[54:55] offset:2048
	v_mfma_f32_16x16x32_bf16 v[14:17], v[174:177], v[130:133], v[14:17]
	global_load_lds_dwordx4 v226, s[54:55] offset:3072
	s_add_i32 m0, s60, s63
	v_mfma_f32_16x16x32_bf16 v[18:21], v[162:165], v[134:137], v[18:21]
	global_load_lds_dwordx4 v230, s[56:57]
	v_mfma_f32_16x16x32_bf16 v[22:25], v[166:169], v[134:137], v[22:25]
	global_load_lds_dwordx4 v231, s[56:57] offset:1024
	v_mfma_f32_16x16x32_bf16 v[26:29], v[170:173], v[134:137], v[26:29]
	v_mfma_f32_16x16x32_bf16 v[30:33], v[174:177], v[134:137], v[30:33]
	v_mfma_f32_16x16x32_bf16 v[34:37], v[162:165], v[138:141], v[34:37]
	ds_read_b128 v[210:213], v241 offset:0
	v_mfma_f32_16x16x32_bf16 v[38:41], v[166:169], v[138:141], v[38:41]
	ds_read_b128 v[214:217], v241 offset:256
	v_mfma_f32_16x16x32_bf16 v[42:45], v[170:173], v[138:141], v[42:45]
	ds_read_b128 v[218:221], v241 offset:2048
	v_mfma_f32_16x16x32_bf16 v[46:49], v[174:177], v[138:141], v[46:49]
	ds_read_b128 v[222:225], v241 offset:2304
	v_mfma_f32_16x16x32_bf16 v[50:53], v[162:165], v[142:145], v[50:53]
	ds_read_b128 v[178:181], v240 offset:0
	v_mfma_f32_16x16x32_bf16 v[54:57], v[166:169], v[142:145], v[54:57]
	ds_read_b128 v[182:185], v240 offset:1024
	v_mfma_f32_16x16x32_bf16 v[58:61], v[170:173], v[142:145], v[58:61]
	ds_read_b128 v[186:189], v240 offset:2048
	v_mfma_f32_16x16x32_bf16 v[62:65], v[174:177], v[142:145], v[62:65]
	ds_read_b128 v[190:193], v240 offset:3072
	v_mfma_f32_16x16x32_bf16 v[66:69], v[162:165], v[146:149], v[66:69]
	ds_read_b128 v[194:197], v240 offset:4096
	v_mfma_f32_16x16x32_bf16 v[70:73], v[166:169], v[146:149], v[70:73]
	ds_read_b128 v[198:201], v240 offset:5120
	v_mfma_f32_16x16x32_bf16 v[74:77], v[170:173], v[146:149], v[74:77]
	ds_read_b128 v[202:205], v240 offset:6144
	v_mfma_f32_16x16x32_bf16 v[78:81], v[174:177], v[146:149], v[78:81]
	ds_read_b128 v[206:209], v240 offset:7168
	s_setprio 1
	v_mfma_f32_16x16x32_bf16 v[82:85], v[162:165], v[150:153], v[82:85]
	v_mfma_f32_16x16x32_bf16 v[86:89], v[166:169], v[150:153], v[86:89]
	v_mfma_f32_16x16x32_bf16 v[90:93], v[170:173], v[150:153], v[90:93]
	v_mfma_f32_16x16x32_bf16 v[94:97], v[174:177], v[150:153], v[94:97]
	v_mfma_f32_16x16x32_bf16 v[98:101], v[162:165], v[154:157], v[98:101]
	v_mfma_f32_16x16x32_bf16 v[102:105], v[166:169], v[154:157], v[102:105]
	v_mfma_f32_16x16x32_bf16 v[106:109], v[170:173], v[154:157], v[106:109]
	v_mfma_f32_16x16x32_bf16 v[110:113], v[174:177], v[154:157], v[110:113]
	v_mfma_f32_16x16x32_bf16 v[114:117], v[162:165], v[158:161], v[114:117]
	v_mfma_f32_16x16x32_bf16 v[118:121], v[166:169], v[158:161], v[118:121]
	v_mfma_f32_16x16x32_bf16 v[122:125], v[170:173], v[158:161], v[122:125]
	v_mfma_f32_16x16x32_bf16 v[126:129], v[174:177], v[158:161], v[126:129]
	s_setprio 0
	s_add_i32 s60, s60, 0x6000
	s_cmp_eq_u32 s60, 0x12000
	s_cselect_b32 s60, 0, s60
	s_add_u32 s54, s54, s72
	s_addc_u32 s55, s55, 0
	s_add_u32 s56, s56, s73
	s_addc_u32 s57, s57, 0
	s_add_i32 s61, s61, 0x6000
	s_cmp_eq_u32 s61, 0x12000
	s_cselect_b32 s61, 0, s61
	s_waitcnt vmcnt(6) lgkmcnt(0)
	s_barrier
	v_add_u32_e32 v240, s61, v238
	v_add_u32_e32 v241, s61, v239
	s_add_i32 m0, s60, s62
	v_mfma_f32_16x16x32_bf16 v[2:5], v[210:213], v[178:181], v[2:5]
	global_load_lds_dwordx4 v226, s[54:55]
	v_mfma_f32_16x16x32_bf16 v[6:9], v[214:217], v[178:181], v[6:9]
	global_load_lds_dwordx4 v226, s[54:55] offset:1024
	v_mfma_f32_16x16x32_bf16 v[10:13], v[218:221], v[178:181], v[10:13]
	global_load_lds_dwordx4 v226, s[54:55] offset:2048
	v_mfma_f32_16x16x32_bf16 v[14:17], v[222:225], v[178:181], v[14:17]
	global_load_lds_dwordx4 v226, s[54:55] offset:3072
	s_add_i32 m0, s60, s63
	v_mfma_f32_16x16x32_bf16 v[18:21], v[210:213], v[182:185], v[18:21]
	global_load_lds_dwordx4 v230, s[56:57]
	v_mfma_f32_16x16x32_bf16 v[22:25], v[214:217], v[182:185], v[22:25]
	global_load_lds_dwordx4 v231, s[56:57] offset:1024
	v_mfma_f32_16x16x32_bf16 v[26:29], v[218:221], v[182:185], v[26:29]
	v_mfma_f32_16x16x32_bf16 v[30:33], v[222:225], v[182:185], v[30:33]
	v_mfma_f32_16x16x32_bf16 v[34:37], v[210:213], v[186:189], v[34:37]
	ds_read_b128 v[162:165], v241 offset:0
	v_mfma_f32_16x16x32_bf16 v[38:41], v[214:217], v[186:189], v[38:41]
	ds_read_b128 v[166:169], v241 offset:256
	v_mfma_f32_16x16x32_bf16 v[42:45], v[218:221], v[186:189], v[42:45]
	ds_read_b128 v[170:173], v241 offset:2048
	v_mfma_f32_16x16x32_bf16 v[46:49], v[222:225], v[186:189], v[46:49]
	ds_read_b128 v[174:177], v241 offset:2304
	v_mfma_f32_16x16x32_bf16 v[50:53], v[210:213], v[190:193], v[50:53]
	ds_read_b128 v[130:133], v240 offset:0
	v_mfma_f32_16x16x32_bf16 v[54:57], v[214:217], v[190:193], v[54:57]
	ds_read_b128 v[134:137], v240 offset:1024
	v_mfma_f32_16x16x32_bf16 v[58:61], v[218:221], v[190:193], v[58:61]
	ds_read_b128 v[138:141], v240 offset:2048
	v_mfma_f32_16x16x32_bf16 v[62:65], v[222:225], v[190:193], v[62:65]
	ds_read_b128 v[142:145], v240 offset:3072
	v_mfma_f32_16x16x32_bf16 v[66:69], v[210:213], v[194:197], v[66:69]
	ds_read_b128 v[146:149], v240 offset:4096
	v_mfma_f32_16x16x32_bf16 v[70:73], v[214:217], v[194:197], v[70:73]
	ds_read_b128 v[150:153], v240 offset:5120
	v_mfma_f32_16x16x32_bf16 v[74:77], v[218:221], v[194:197], v[74:77]
	ds_read_b128 v[154:157], v240 offset:6144
	v_mfma_f32_16x16x32_bf16 v[78:81], v[222:225], v[194:197], v[78:81]
	ds_read_b128 v[158:161], v240 offset:7168
	s_setprio 1
	v_mfma_f32_16x16x32_bf16 v[82:85], v[210:213], v[198:201], v[82:85]
	v_mfma_f32_16x16x32_bf16 v[86:89], v[214:217], v[198:201], v[86:89]
	v_mfma_f32_16x16x32_bf16 v[90:93], v[218:221], v[198:201], v[90:93]
	v_mfma_f32_16x16x32_bf16 v[94:97], v[222:225], v[198:201], v[94:97]
	v_mfma_f32_16x16x32_bf16 v[98:101], v[210:213], v[202:205], v[98:101]
	v_mfma_f32_16x16x32_bf16 v[102:105], v[214:217], v[202:205], v[102:105]
	v_mfma_f32_16x16x32_bf16 v[106:109], v[218:221], v[202:205], v[106:109]
	v_mfma_f32_16x16x32_bf16 v[110:113], v[222:225], v[202:205], v[110:113]
	v_mfma_f32_16x16x32_bf16 v[114:117], v[210:213], v[206:209], v[114:117]
	v_mfma_f32_16x16x32_bf16 v[118:121], v[214:217], v[206:209], v[118:121]
	v_mfma_f32_16x16x32_bf16 v[122:125], v[218:221], v[206:209], v[122:125]
	v_mfma_f32_16x16x32_bf16 v[126:129], v[222:225], v[206:209], v[126:129]
	s_setprio 0
	s_add_i32 s60, s60, 0x6000
	s_cmp_eq_u32 s60, 0x12000
	s_cselect_b32 s60, 0, s60
	s_add_u32 s54, s54, s72
	s_addc_u32 s55, s55, 0
	s_add_u32 s56, s56, s73
	s_addc_u32 s57, s57, 0
	s_add_i32 s61, s61, 0x6000
	s_cmp_eq_u32 s61, 0x12000
	s_cselect_b32 s61, 0, s61
	s_and_b32 s39, s35, 0xfff
	s_lshr_b32 s21, s36, 7
	s_waitcnt vmcnt(18)
	v_mbcnt_lo_u32_b32 v217, -1, 0
	v_mbcnt_hi_u32_b32 v217, -1, v217
	v_lshlrev_b32_e32 v217, 5, v217
	s_lshl_b32 s26, s43, 11
	s_add_i32 s26, s26, 0x12010
	v_add_u32_e32 v217, s26, v217
	s_cmp_eq_u32 s42, 0
	s_cbranch_scc0 .Lup_en_nowr
	ds_write_b128 v217, v[114:117]
	ds_write_b128 v217, v[118:121] offset:16

.Lup_tail_last:
	s_waitcnt vmcnt(6) lgkmcnt(0)
	s_barrier
	v_add_u32_e32 v240, s61, v238
	v_add_u32_e32 v241, s61, v239
	s_add_i32 m0, s60, s62
	v_mfma_f32_16x16x32_bf16 v[2:5], v[162:165], v[130:133], v[2:5]
	global_load_lds_dwordx4 v226, s[54:55]
	v_mfma_f32_16x16x32_bf16 v[6:9], v[166:169], v[130:133], v[6:9]
	global_load_lds_dwordx4 v226, s[54:55] offset:1024
	v_mfma_f32_16x16x32_bf16 v[10:13], v[170:173], v[130:133], v[10:13]
	global_load_lds_dwordx4 v226, s[54:55] offset:2048
	v_mfma_f32_16x16x32_bf16 v[14:17], v[174:177], v[130:133], v[14:17]
	global_load_lds_dwordx4 v226, s[54:55] offset:3072
	s_add_i32 m0, s60, s63
	v_mfma_f32_16x16x32_bf16 v[18:21], v[162:165], v[134:137], v[18:21]
	global_load_lds_dwordx4 v230, s[56:57]
	v_mfma_f32_16x16x32_bf16 v[22:25], v[166:169], v[134:137], v[22:25]
	global_load_lds_dwordx4 v231, s[56:57] offset:1024
	v_mfma_f32_16x16x32_bf16 v[26:29], v[170:173], v[134:137], v[26:29]
	v_mfma_f32_16x16x32_bf16 v[30:33], v[174:177], v[134:137], v[30:33]
	v_mfma_f32_16x16x32_bf16 v[34:37], v[162:165], v[138:141], v[34:37]
	ds_read_b128 v[210:213], v241 offset:0
	v_mfma_f32_16x16x32_bf16 v[38:41], v[166:169], v[138:141], v[38:41]
	ds_read_b128 v[214:217], v241 offset:256
	v_mfma_f32_16x16x32_bf16 v[42:45], v[170:173], v[138:141], v[42:45]
	ds_read_b128 v[218:221], v241 offset:2048
	v_mfma_f32_16x16x32_bf16 v[46:49], v[174:177], v[138:141], v[46:49]
	ds_read_b128 v[222:225], v241 offset:2304
	v_mfma_f32_16x16x32_bf16 v[50:53], v[162:165], v[142:145], v[50:53]
	ds_read_b128 v[178:181], v240 offset:0
	v_mfma_f32_16x16x32_bf16 v[54:57], v[166:169], v[142:145], v[54:57]
	ds_read_b128 v[182:185], v240 offset:1024
	v_mfma_f32_16x16x32_bf16 v[58:61], v[170:173], v[142:145], v[58:61]
	ds_read_b128 v[186:189], v240 offset:2048
	v_mfma_f32_16x16x32_bf16 v[62:65], v[174:177], v[142:145], v[62:65]
	ds_read_b128 v[190:193], v240 offset:3072
	v_mfma_f32_16x16x32_bf16 v[66:69], v[162:165], v[146:149], v[66:69]
	ds_read_b128 v[194:197], v240 offset:4096
	v_mfma_f32_16x16x32_bf16 v[70:73], v[166:169], v[146:149], v[70:73]
	ds_read_b128 v[198:201], v240 offset:5120
	v_mfma_f32_16x16x32_bf16 v[74:77], v[170:173], v[146:149], v[74:77]
	ds_read_b128 v[202:205], v240 offset:6144
	v_mfma_f32_16x16x32_bf16 v[78:81], v[174:177], v[146:149], v[78:81]
	ds_read_b128 v[206:209], v240 offset:7168
	s_setprio 1
	v_mfma_f32_16x16x32_bf16 v[82:85], v[162:165], v[150:153], v[82:85]
	v_mfma_f32_16x16x32_bf16 v[86:89], v[166:169], v[150:153], v[86:89]
	v_mfma_f32_16x16x32_bf16 v[90:93], v[170:173], v[150:153], v[90:93]
	v_mfma_f32_16x16x32_bf16 v[94:97], v[174:177], v[150:153], v[94:97]
	v_mfma_f32_16x16x32_bf16 v[98:101], v[162:165], v[154:157], v[98:101]
	v_mfma_f32_16x16x32_bf16 v[102:105], v[166:169], v[154:157], v[102:105]
	v_mfma_f32_16x16x32_bf16 v[106:109], v[170:173], v[154:157], v[106:109]
	v_mfma_f32_16x16x32_bf16 v[110:113], v[174:177], v[154:157], v[110:113]
	v_mfma_f32_16x16x32_bf16 v[114:117], v[162:165], v[158:161], v[114:117]
	v_mfma_f32_16x16x32_bf16 v[118:121], v[166:169], v[158:161], v[118:121]
	v_mfma_f32_16x16x32_bf16 v[122:125], v[170:173], v[158:161], v[122:125]
	v_mfma_f32_16x16x32_bf16 v[126:129], v[174:177], v[158:161], v[126:129]
	s_setprio 0
	s_add_i32 s60, s60, 0x6000
	s_cmp_eq_u32 s60, 0x12000
	s_cselect_b32 s60, 0, s60
	s_add_u32 s54, s54, s72
	s_addc_u32 s55, s55, 0
	s_add_u32 s56, s56, s73
	s_addc_u32 s57, s57, 0
	s_add_i32 s61, s61, 0x6000
	s_cmp_eq_u32 s61, 0x12000
	s_cselect_b32 s61, 0, s61
	s_waitcnt vmcnt(6) lgkmcnt(0)
	s_barrier
	v_add_u32_e32 v240, s61, v238
	v_add_u32_e32 v241, s61, v239
	v_mfma_f32_16x16x32_bf16 v[2:5], v[210:213], v[178:181], v[2:5]
	v_mfma_f32_16x16x32_bf16 v[6:9], v[214:217], v[178:181], v[6:9]
	v_mfma_f32_16x16x32_bf16 v[10:13], v[218:221], v[178:181], v[10:13]
	v_mfma_f32_16x16x32_bf16 v[14:17], v[222:225], v[178:181], v[14:17]
	v_mfma_f32_16x16x32_bf16 v[18:21], v[210:213], v[182:185], v[18:21]
	v_mfma_f32_16x16x32_bf16 v[22:25], v[214:217], v[182:185], v[22:25]
	v_mfma_f32_16x16x32_bf16 v[26:29], v[218:221], v[182:185], v[26:29]
	v_mfma_f32_16x16x32_bf16 v[30:33], v[222:225], v[182:185], v[30:33]
	v_mfma_f32_16x16x32_bf16 v[34:37], v[210:213], v[186:189], v[34:37]
	ds_read_b128 v[162:165], v241 offset:0
	v_mfma_f32_16x16x32_bf16 v[38:41], v[214:217], v[186:189], v[38:41]
	ds_read_b128 v[166:169], v241 offset:256
	v_mfma_f32_16x16x32_bf16 v[42:45], v[218:221], v[186:189], v[42:45]
	ds_read_b128 v[170:173], v241 offset:2048
	v_mfma_f32_16x16x32_bf16 v[46:49], v[222:225], v[186:189], v[46:49]
	ds_read_b128 v[174:177], v241 offset:2304
	v_mfma_f32_16x16x32_bf16 v[50:53], v[210:213], v[190:193], v[50:53]
	ds_read_b128 v[130:133], v240 offset:0
	v_mfma_f32_16x16x32_bf16 v[54:57], v[214:217], v[190:193], v[54:57]
	ds_read_b128 v[134:137], v240 offset:1024
	v_mfma_f32_16x16x32_bf16 v[58:61], v[218:221], v[190:193], v[58:61]
	ds_read_b128 v[138:141], v240 offset:2048
	v_mfma_f32_16x16x32_bf16 v[62:65], v[222:225], v[190:193], v[62:65]
	ds_read_b128 v[142:145], v240 offset:3072
	v_mfma_f32_16x16x32_bf16 v[66:69], v[210:213], v[194:197], v[66:69]
	ds_read_b128 v[146:149], v240 offset:4096
	v_mfma_f32_16x16x32_bf16 v[70:73], v[214:217], v[194:197], v[70:73]
	ds_read_b128 v[150:153], v240 offset:5120
	v_mfma_f32_16x16x32_bf16 v[74:77], v[218:221], v[194:197], v[74:77]
	ds_read_b128 v[154:157], v240 offset:6144
	v_mfma_f32_16x16x32_bf16 v[78:81], v[222:225], v[194:197], v[78:81]
	ds_read_b128 v[158:161], v240 offset:7168
	s_setprio 1
	v_mfma_f32_16x16x32_bf16 v[82:85], v[210:213], v[198:201], v[82:85]
	v_mfma_f32_16x16x32_bf16 v[86:89], v[214:217], v[198:201], v[86:89]
	v_mfma_f32_16x16x32_bf16 v[90:93], v[218:221], v[198:201], v[90:93]
	v_mfma_f32_16x16x32_bf16 v[94:97], v[222:225], v[198:201], v[94:97]
	v_mfma_f32_16x16x32_bf16 v[98:101], v[210:213], v[202:205], v[98:101]
	v_mfma_f32_16x16x32_bf16 v[102:105], v[214:217], v[202:205], v[102:105]
	v_mfma_f32_16x16x32_bf16 v[106:109], v[218:221], v[202:205], v[106:109]
	v_mfma_f32_16x16x32_bf16 v[110:113], v[222:225], v[202:205], v[110:113]
	v_mfma_f32_16x16x32_bf16 v[114:117], v[210:213], v[206:209], v[114:117]
	v_mfma_f32_16x16x32_bf16 v[118:121], v[214:217], v[206:209], v[118:121]
	v_mfma_f32_16x16x32_bf16 v[122:125], v[218:221], v[206:209], v[122:125]
	v_mfma_f32_16x16x32_bf16 v[126:129], v[222:225], v[206:209], v[126:129]
	s_setprio 0
	s_add_i32 s61, s61, 0x6000
	s_cmp_eq_u32 s61, 0x12000
	s_cselect_b32 s61, 0, s61
	s_waitcnt vmcnt(0) lgkmcnt(0)
	s_barrier
	v_add_u32_e32 v240, s61, v238
	v_add_u32_e32 v241, s61, v239
	v_mfma_f32_16x16x32_bf16 v[2:5], v[162:165], v[130:133], v[2:5]
	v_mfma_f32_16x16x32_bf16 v[6:9], v[166:169], v[130:133], v[6:9]
	v_mfma_f32_16x16x32_bf16 v[10:13], v[170:173], v[130:133], v[10:13]
	v_mfma_f32_16x16x32_bf16 v[14:17], v[174:177], v[130:133], v[14:17]
	v_mfma_f32_16x16x32_bf16 v[18:21], v[162:165], v[134:137], v[18:21]
	v_mfma_f32_16x16x32_bf16 v[22:25], v[166:169], v[134:137], v[22:25]
	v_mfma_f32_16x16x32_bf16 v[26:29], v[170:173], v[134:137], v[26:29]
	v_mfma_f32_16x16x32_bf16 v[30:33], v[174:177], v[134:137], v[30:33]
	v_mfma_f32_16x16x32_bf16 v[34:37], v[162:165], v[138:141], v[34:37]
	ds_read_b128 v[210:213], v241 offset:0
	v_mfma_f32_16x16x32_bf16 v[38:41], v[166:169], v[138:141], v[38:41]
	ds_read_b128 v[214:217], v241 offset:256
	v_mfma_f32_16x16x32_bf16 v[42:45], v[170:173], v[138:141], v[42:45]
	ds_read_b128 v[218:221], v241 offset:2048
	v_mfma_f32_16x16x32_bf16 v[46:49], v[174:177], v[138:141], v[46:49]
	ds_read_b128 v[222:225], v241 offset:2304
	v_mfma_f32_16x16x32_bf16 v[50:53], v[162:165], v[142:145], v[50:53]
	ds_read_b128 v[178:181], v240 offset:0
	v_mfma_f32_16x16x32_bf16 v[54:57], v[166:169], v[142:145], v[54:57]
	ds_read_b128 v[182:185], v240 offset:1024
	v_mfma_f32_16x16x32_bf16 v[58:61], v[170:173], v[142:145], v[58:61]
	ds_read_b128 v[186:189], v240 offset:2048
	v_mfma_f32_16x16x32_bf16 v[62:65], v[174:177], v[142:145], v[62:65]
	ds_read_b128 v[190:193], v240 offset:3072
	v_mfma_f32_16x16x32_bf16 v[66:69], v[162:165], v[146:149], v[66:69]
	ds_read_b128 v[194:197], v240 offset:4096
	v_mfma_f32_16x16x32_bf16 v[70:73], v[166:169], v[146:149], v[70:73]
	ds_read_b128 v[198:201], v240 offset:5120
	v_mfma_f32_16x16x32_bf16 v[74:77], v[170:173], v[146:149], v[74:77]
	ds_read_b128 v[202:205], v240 offset:6144
	v_mfma_f32_16x16x32_bf16 v[78:81], v[174:177], v[146:149], v[78:81]
	ds_read_b128 v[206:209], v240 offset:7168
	s_setprio 1
	v_mfma_f32_16x16x32_bf16 v[82:85], v[162:165], v[150:153], v[82:85]
	v_mfma_f32_16x16x32_bf16 v[86:89], v[166:169], v[150:153], v[86:89]
	v_mfma_f32_16x16x32_bf16 v[90:93], v[170:173], v[150:153], v[90:93]
	v_mfma_f32_16x16x32_bf16 v[94:97], v[174:177], v[150:153], v[94:97]
	v_mfma_f32_16x16x32_bf16 v[98:101], v[162:165], v[154:157], v[98:101]
	v_mfma_f32_16x16x32_bf16 v[102:105], v[166:169], v[154:157], v[102:105]
	v_mfma_f32_16x16x32_bf16 v[106:109], v[170:173], v[154:157], v[106:109]
	v_mfma_f32_16x16x32_bf16 v[110:113], v[174:177], v[154:157], v[110:113]
	v_mfma_f32_16x16x32_bf16 v[114:117], v[162:165], v[158:161], v[114:117]
	v_mfma_f32_16x16x32_bf16 v[118:121], v[166:169], v[158:161], v[118:121]
	v_mfma_f32_16x16x32_bf16 v[122:125], v[170:173], v[158:161], v[122:125]
	v_mfma_f32_16x16x32_bf16 v[126:129], v[174:177], v[158:161], v[126:129]
	s_setprio 0
	s_add_i32 s61, s61, 0x6000
	s_cmp_eq_u32 s61, 0x12000
	s_cselect_b32 s61, 0, s61
	s_waitcnt lgkmcnt(0)
	s_barrier
	v_mfma_f32_16x16x32_bf16 v[2:5], v[210:213], v[178:181], v[2:5]
	v_mfma_f32_16x16x32_bf16 v[6:9], v[214:217], v[178:181], v[6:9]
	v_mfma_f32_16x16x32_bf16 v[10:13], v[218:221], v[178:181], v[10:13]
	v_mfma_f32_16x16x32_bf16 v[14:17], v[222:225], v[178:181], v[14:17]
	v_mfma_f32_16x16x32_bf16 v[18:21], v[210:213], v[182:185], v[18:21]
	v_mfma_f32_16x16x32_bf16 v[22:25], v[214:217], v[182:185], v[22:25]
	v_mfma_f32_16x16x32_bf16 v[26:29], v[218:221], v[182:185], v[26:29]
	v_mfma_f32_16x16x32_bf16 v[30:33], v[222:225], v[182:185], v[30:33]
	v_mfma_f32_16x16x32_bf16 v[34:37], v[210:213], v[186:189], v[34:37]
	v_mfma_f32_16x16x32_bf16 v[38:41], v[214:217], v[186:189], v[38:41]
	v_mfma_f32_16x16x32_bf16 v[42:45], v[218:221], v[186:189], v[42:45]
	v_mfma_f32_16x16x32_bf16 v[46:49], v[222:225], v[186:189], v[46:49]
	v_mfma_f32_16x16x32_bf16 v[50:53], v[210:213], v[190:193], v[50:53]
	v_mfma_f32_16x16x32_bf16 v[54:57], v[214:217], v[190:193], v[54:57]
	v_mfma_f32_16x16x32_bf16 v[58:61], v[218:221], v[190:193], v[58:61]
	v_mfma_f32_16x16x32_bf16 v[62:65], v[222:225], v[190:193], v[62:65]
	v_mfma_f32_16x16x32_bf16 v[66:69], v[210:213], v[194:197], v[66:69]
	v_mfma_f32_16x16x32_bf16 v[70:73], v[214:217], v[194:197], v[70:73]
	v_mfma_f32_16x16x32_bf16 v[74:77], v[218:221], v[194:197], v[74:77]
	v_mfma_f32_16x16x32_bf16 v[78:81], v[222:225], v[194:197], v[78:81]
	s_setprio 1
	v_mfma_f32_16x16x32_bf16 v[82:85], v[210:213], v[198:201], v[82:85]
	v_mfma_f32_16x16x32_bf16 v[86:89], v[214:217], v[198:201], v[86:89]
	v_mfma_f32_16x16x32_bf16 v[90:93], v[218:221], v[198:201], v[90:93]
	v_mfma_f32_16x16x32_bf16 v[94:97], v[222:225], v[198:201], v[94:97]
	v_mfma_f32_16x16x32_bf16 v[98:101], v[210:213], v[202:205], v[98:101]
	v_mfma_f32_16x16x32_bf16 v[102:105], v[214:217], v[202:205], v[102:105]
	v_mfma_f32_16x16x32_bf16 v[106:109], v[218:221], v[202:205], v[106:109]
	v_mfma_f32_16x16x32_bf16 v[110:113], v[222:225], v[202:205], v[110:113]
	v_mfma_f32_16x16x32_bf16 v[114:117], v[210:213], v[206:209], v[114:117]
	v_mfma_f32_16x16x32_bf16 v[118:121], v[214:217], v[206:209], v[118:121]
	v_mfma_f32_16x16x32_bf16 v[122:125], v[218:221], v[206:209], v[122:125]
	v_mfma_f32_16x16x32_bf16 v[126:129], v[222:225], v[206:209], v[126:129]
	s_setprio 0
	s_and_b32 s39, s35, 0xfff
	s_lshr_b32 s21, s36, 7
	s_waitcnt vmcnt(0)
	v_mbcnt_lo_u32_b32 v217, -1, 0
	v_mbcnt_hi_u32_b32 v217, -1, v217
	v_lshlrev_b32_e32 v217, 5, v217
	s_lshl_b32 s26, s43, 11
	s_add_i32 s26, s26, 0x12010
	v_add_u32_e32 v217, s26, v217
	s_cmp_eq_u32 s42, 0
	s_cbranch_scc0 .Lup_el_nowr
	ds_write_b128 v217, v[114:117]
	ds_write_b128 v217, v[118:121] offset:16

.Lpj_nn_a:
	s_waitcnt vmcnt(6) lgkmcnt(0)
	s_barrier
	v_add_u32_e32 v240, s61, v238
	v_add_u32_e32 v241, s61, v239
	s_add_i32 m0, s60, s62
	v_mfma_f32_16x16x32_bf16 v[2:5], v[162:165], v[130:133], 0
	global_load_lds_dwordx4 v226, s[54:55]
	v_mfma_f32_16x16x32_bf16 v[6:9], v[166:169], v[130:133], 0
	global_load_lds_dwordx4 v226, s[54:55] offset:1024
	v_mfma_f32_16x16x32_bf16 v[10:13], v[170:173], v[130:133], 0
	global_load_lds_dwordx4 v226, s[54:55] offset:2048
	v_mfma_f32_16x16x32_bf16 v[14:17], v[174:177], v[130:133], 0
	global_load_lds_dwordx4 v226, s[54:55] offset:3072
	s_add_i32 m0, s60, s63
	v_mfma_f32_16x16x32_bf16 v[18:21], v[162:165], v[134:137], 0
	global_load_lds_dwordx4 v230, s[56:57]
	v_mfma_f32_16x16x32_bf16 v[22:25], v[166:169], v[134:137], 0
	global_load_lds_dwordx4 v231, s[56:57] offset:1024
	v_mfma_f32_16x16x32_bf16 v[26:29], v[170:173], v[134:137], 0
	v_mfma_f32_16x16x32_bf16 v[30:33], v[174:177], v[134:137], 0
	v_mfma_f32_16x16x32_bf16 v[34:37], v[162:165], v[138:141], 0
	ds_read_b128 v[210:213], v241 offset:0
	v_mfma_f32_16x16x32_bf16 v[38:41], v[166:169], v[138:141], 0
	ds_read_b128 v[214:217], v241 offset:256
	v_mfma_f32_16x16x32_bf16 v[42:45], v[170:173], v[138:141], 0
	ds_read_b128 v[218:221], v241 offset:2048
	v_mfma_f32_16x16x32_bf16 v[46:49], v[174:177], v[138:141], 0
	ds_read_b128 v[222:225], v241 offset:2304
	v_mfma_f32_16x16x32_bf16 v[50:53], v[162:165], v[142:145], 0
	ds_read_b128 v[178:181], v240 offset:0
	v_mfma_f32_16x16x32_bf16 v[54:57], v[166:169], v[142:145], 0
	ds_read_b128 v[182:185], v240 offset:1024
	v_mfma_f32_16x16x32_bf16 v[58:61], v[170:173], v[142:145], 0
	ds_read_b128 v[186:189], v240 offset:2048
	v_mfma_f32_16x16x32_bf16 v[62:65], v[174:177], v[142:145], 0
	ds_read_b128 v[190:193], v240 offset:3072
	v_mfma_f32_16x16x32_bf16 v[66:69], v[162:165], v[146:149], 0
	ds_read_b128 v[194:197], v240 offset:4096
	v_mfma_f32_16x16x32_bf16 v[70:73], v[166:169], v[146:149], 0
	ds_read_b128 v[198:201], v240 offset:5120
	v_mfma_f32_16x16x32_bf16 v[74:77], v[170:173], v[146:149], 0
	ds_read_b128 v[202:205], v240 offset:6144
	v_mfma_f32_16x16x32_bf16 v[78:81], v[174:177], v[146:149], 0
	ds_read_b128 v[206:209], v240 offset:7168
	s_setprio 1
	v_mfma_f32_16x16x32_bf16 v[82:85], v[162:165], v[150:153], 0
	v_mfma_f32_16x16x32_bf16 v[86:89], v[166:169], v[150:153], 0
	v_mfma_f32_16x16x32_bf16 v[90:93], v[170:173], v[150:153], 0
	v_mfma_f32_16x16x32_bf16 v[94:97], v[174:177], v[150:153], 0
	v_mfma_f32_16x16x32_bf16 v[98:101], v[162:165], v[154:157], 0
	v_mfma_f32_16x16x32_bf16 v[102:105], v[166:169], v[154:157], 0
	v_mfma_f32_16x16x32_bf16 v[106:109], v[170:173], v[154:157], 0
	v_mfma_f32_16x16x32_bf16 v[110:113], v[174:177], v[154:157], 0
	v_mfma_f32_16x16x32_bf16 v[114:117], v[162:165], v[158:161], 0
	v_mfma_f32_16x16x32_bf16 v[118:121], v[166:169], v[158:161], 0
	v_mfma_f32_16x16x32_bf16 v[122:125], v[170:173], v[158:161], 0
	v_mfma_f32_16x16x32_bf16 v[126:129], v[174:177], v[158:161], 0
	s_setprio 0
	s_add_i32 s60, s60, 0x6000
	s_cmp_eq_u32 s60, 0x12000
	s_cselect_b32 s60, 0, s60
	s_add_u32 s54, s54, s72
	s_addc_u32 s55, s55, 0
	s_add_u32 s56, s56, s73
	s_addc_u32 s57, s57, 0
	s_add_i32 s61, s61, 0x6000
	s_cmp_eq_u32 s61, 0x12000
	s_cselect_b32 s61, 0, s61
	s_waitcnt vmcnt(6) lgkmcnt(0)
	s_barrier
	v_add_u32_e32 v240, s61, v238
	v_add_u32_e32 v241, s61, v239
	s_add_i32 m0, s60, s62
	v_mfma_f32_16x16x32_bf16 v[2:5], v[210:213], v[178:181], v[2:5]
	global_load_lds_dwordx4 v226, s[54:55]
	v_mfma_f32_16x16x32_bf16 v[6:9], v[214:217], v[178:181], v[6:9]
	global_load_lds_dwordx4 v226, s[54:55] offset:1024
	v_mfma_f32_16x16x32_bf16 v[10:13], v[218:221], v[178:181], v[10:13]
	global_load_lds_dwordx4 v226, s[54:55] offset:2048
	v_mfma_f32_16x16x32_bf16 v[14:17], v[222:225], v[178:181], v[14:17]
	global_load_lds_dwordx4 v226, s[54:55] offset:3072
	s_add_i32 m0, s60, s63
	v_mfma_f32_16x16x32_bf16 v[18:21], v[210:213], v[182:185], v[18:21]
	global_load_lds_dwordx4 v230, s[56:57]
	v_mfma_f32_16x16x32_bf16 v[22:25], v[214:217], v[182:185], v[22:25]
	global_load_lds_dwordx4 v231, s[56:57] offset:1024
	v_mfma_f32_16x16x32_bf16 v[26:29], v[218:221], v[182:185], v[26:29]
	v_mfma_f32_16x16x32_bf16 v[30:33], v[222:225], v[182:185], v[30:33]
	v_mfma_f32_16x16x32_bf16 v[34:37], v[210:213], v[186:189], v[34:37]
	ds_read_b128 v[162:165], v241 offset:0
	v_mfma_f32_16x16x32_bf16 v[38:41], v[214:217], v[186:189], v[38:41]
	ds_read_b128 v[166:169], v241 offset:256
	v_mfma_f32_16x16x32_bf16 v[42:45], v[218:221], v[186:189], v[42:45]
	ds_read_b128 v[170:173], v241 offset:2048
	v_mfma_f32_16x16x32_bf16 v[46:49], v[222:225], v[186:189], v[46:49]
	ds_read_b128 v[174:177], v241 offset:2304
	v_mfma_f32_16x16x32_bf16 v[50:53], v[210:213], v[190:193], v[50:53]
	ds_read_b128 v[130:133], v240 offset:0
	v_mfma_f32_16x16x32_bf16 v[54:57], v[214:217], v[190:193], v[54:57]
	ds_read_b128 v[134:137], v240 offset:1024
	v_mfma_f32_16x16x32_bf16 v[58:61], v[218:221], v[190:193], v[58:61]
	ds_read_b128 v[138:141], v240 offset:2048
	v_mfma_f32_16x16x32_bf16 v[62:65], v[222:225], v[190:193], v[62:65]
	ds_read_b128 v[142:145], v240 offset:3072
	v_mfma_f32_16x16x32_bf16 v[66:69], v[210:213], v[194:197], v[66:69]
	ds_read_b128 v[146:149], v240 offset:4096
	v_mfma_f32_16x16x32_bf16 v[70:73], v[214:217], v[194:197], v[70:73]
	ds_read_b128 v[150:153], v240 offset:5120
	v_mfma_f32_16x16x32_bf16 v[74:77], v[218:221], v[194:197], v[74:77]
	ds_read_b128 v[154:157], v240 offset:6144
	v_mfma_f32_16x16x32_bf16 v[78:81], v[222:225], v[194:197], v[78:81]
	ds_read_b128 v[158:161], v240 offset:7168
	s_setprio 1
	v_mfma_f32_16x16x32_bf16 v[82:85], v[210:213], v[198:201], v[82:85]
	v_mfma_f32_16x16x32_bf16 v[86:89], v[214:217], v[198:201], v[86:89]
	v_mfma_f32_16x16x32_bf16 v[90:93], v[218:221], v[198:201], v[90:93]
	v_mfma_f32_16x16x32_bf16 v[94:97], v[222:225], v[198:201], v[94:97]
	v_mfma_f32_16x16x32_bf16 v[98:101], v[210:213], v[202:205], v[98:101]
	v_mfma_f32_16x16x32_bf16 v[102:105], v[214:217], v[202:205], v[102:105]
	v_mfma_f32_16x16x32_bf16 v[106:109], v[218:221], v[202:205], v[106:109]
	v_mfma_f32_16x16x32_bf16 v[110:113], v[222:225], v[202:205], v[110:113]
	v_mfma_f32_16x16x32_bf16 v[114:117], v[210:213], v[206:209], v[114:117]
	v_mfma_f32_16x16x32_bf16 v[118:121], v[214:217], v[206:209], v[118:121]
	v_mfma_f32_16x16x32_bf16 v[122:125], v[218:221], v[206:209], v[122:125]
	v_mfma_f32_16x16x32_bf16 v[126:129], v[222:225], v[206:209], v[126:129]
	s_setprio 0
	s_add_i32 s60, s60, 0x6000
	s_cmp_eq_u32 s60, 0x12000
	s_cselect_b32 s60, 0, s60
	s_add_u32 s54, s54, s72
	s_addc_u32 s55, s55, 0
	s_add_u32 s56, s56, s73
	s_addc_u32 s57, s57, 0
	s_add_i32 s61, s61, 0x6000
	s_cmp_eq_u32 s61, 0x12000
	s_cselect_b32 s61, 0, s61
	s_branch .Lpj_main

.Lpj_nn_b:
	s_waitcnt vmcnt(63) lgkmcnt(0)
	s_barrier
	v_add_u32_e32 v240, s61, v238
	v_add_u32_e32 v241, s61, v239
	s_add_i32 m0, s60, s62
	v_mfma_f32_16x16x32_bf16 v[2:5], v[162:165], v[130:133], 0
	global_load_lds_dwordx4 v226, s[54:55]
	v_mfma_f32_16x16x32_bf16 v[6:9], v[166:169], v[130:133], 0
	global_load_lds_dwordx4 v226, s[54:55] offset:1024
	v_mfma_f32_16x16x32_bf16 v[10:13], v[170:173], v[130:133], 0
	global_load_lds_dwordx4 v226, s[54:55] offset:2048
	v_mfma_f32_16x16x32_bf16 v[14:17], v[174:177], v[130:133], 0
	global_load_lds_dwordx4 v226, s[54:55] offset:3072
	s_add_i32 m0, s60, s63
	v_mfma_f32_16x16x32_bf16 v[18:21], v[162:165], v[134:137], 0
	global_load_lds_dwordx4 v230, s[56:57]
	v_mfma_f32_16x16x32_bf16 v[22:25], v[166:169], v[134:137], 0
	global_load_lds_dwordx4 v231, s[56:57] offset:1024
	v_mfma_f32_16x16x32_bf16 v[26:29], v[170:173], v[134:137], 0
	v_mfma_f32_16x16x32_bf16 v[30:33], v[174:177], v[134:137], 0
	v_mfma_f32_16x16x32_bf16 v[34:37], v[162:165], v[138:141], 0
	ds_read_b128 v[210:213], v241 offset:0
	v_mfma_f32_16x16x32_bf16 v[38:41], v[166:169], v[138:141], 0
	ds_read_b128 v[214:217], v241 offset:256
	v_mfma_f32_16x16x32_bf16 v[42:45], v[170:173], v[138:141], 0
	ds_read_b128 v[218:221], v241 offset:2048
	v_mfma_f32_16x16x32_bf16 v[46:49], v[174:177], v[138:141], 0
	ds_read_b128 v[222:225], v241 offset:2304
	v_mfma_f32_16x16x32_bf16 v[50:53], v[162:165], v[142:145], 0
	ds_read_b128 v[178:181], v240 offset:0
	v_mfma_f32_16x16x32_bf16 v[54:57], v[166:169], v[142:145], 0
	ds_read_b128 v[182:185], v240 offset:1024
	v_mfma_f32_16x16x32_bf16 v[58:61], v[170:173], v[142:145], 0
	ds_read_b128 v[186:189], v240 offset:2048
	v_mfma_f32_16x16x32_bf16 v[62:65], v[174:177], v[142:145], 0
	ds_read_b128 v[190:193], v240 offset:3072
	v_mfma_f32_16x16x32_bf16 v[66:69], v[162:165], v[146:149], 0
	ds_read_b128 v[194:197], v240 offset:4096
	v_mfma_f32_16x16x32_bf16 v[70:73], v[166:169], v[146:149], 0
	ds_read_b128 v[198:201], v240 offset:5120
	v_mfma_f32_16x16x32_bf16 v[74:77], v[170:173], v[146:149], 0
	ds_read_b128 v[202:205], v240 offset:6144
	v_mfma_f32_16x16x32_bf16 v[78:81], v[174:177], v[146:149], 0
	ds_read_b128 v[206:209], v240 offset:7168
	s_setprio 1
	v_mfma_f32_16x16x32_bf16 v[82:85], v[162:165], v[150:153], 0
	v_mfma_f32_16x16x32_bf16 v[86:89], v[166:169], v[150:153], 0
	v_mfma_f32_16x16x32_bf16 v[90:93], v[170:173], v[150:153], 0
	v_mfma_f32_16x16x32_bf16 v[94:97], v[174:177], v[150:153], 0
	v_mfma_f32_16x16x32_bf16 v[98:101], v[162:165], v[154:157], 0
	v_mfma_f32_16x16x32_bf16 v[102:105], v[166:169], v[154:157], 0
	v_mfma_f32_16x16x32_bf16 v[106:109], v[170:173], v[154:157], 0
	v_mfma_f32_16x16x32_bf16 v[110:113], v[174:177], v[154:157], 0
	v_mfma_f32_16x16x32_bf16 v[114:117], v[162:165], v[158:161], 0
	v_mfma_f32_16x16x32_bf16 v[118:121], v[166:169], v[158:161], 0
	v_mfma_f32_16x16x32_bf16 v[122:125], v[170:173], v[158:161], 0
	v_mfma_f32_16x16x32_bf16 v[126:129], v[174:177], v[158:161], 0
	s_setprio 0
	s_add_i32 s60, s60, 0x6000
	s_cmp_eq_u32 s60, 0x12000
	s_cselect_b32 s60, 0, s60
	s_add_u32 s54, s54, s72
	s_addc_u32 s55, s55, 0
	s_add_u32 s56, s56, s73
	s_addc_u32 s57, s57, 0
	s_add_i32 s61, s61, 0x6000
	s_cmp_eq_u32 s61, 0x12000
	s_cselect_b32 s61, 0, s61
	s_waitcnt vmcnt(63) lgkmcnt(0)
	s_barrier
	v_add_u32_e32 v240, s61, v238
	v_add_u32_e32 v241, s61, v239
	s_add_i32 m0, s60, s62
	v_mfma_f32_16x16x32_bf16 v[2:5], v[210:213], v[178:181], v[2:5]
	global_load_lds_dwordx4 v226, s[54:55]
	v_mfma_f32_16x16x32_bf16 v[6:9], v[214:217], v[178:181], v[6:9]
	global_load_lds_dwordx4 v226, s[54:55] offset:1024
	v_mfma_f32_16x16x32_bf16 v[10:13], v[218:221], v[178:181], v[10:13]
	global_load_lds_dwordx4 v226, s[54:55] offset:2048
	v_mfma_f32_16x16x32_bf16 v[14:17], v[222:225], v[178:181], v[14:17]
	global_load_lds_dwordx4 v226, s[54:55] offset:3072
	s_add_i32 m0, s60, s63
	v_mfma_f32_16x16x32_bf16 v[18:21], v[210:213], v[182:185], v[18:21]
	global_load_lds_dwordx4 v230, s[56:57]
	v_mfma_f32_16x16x32_bf16 v[22:25], v[214:217], v[182:185], v[22:25]
	global_load_lds_dwordx4 v231, s[56:57] offset:1024
	v_mfma_f32_16x16x32_bf16 v[26:29], v[218:221], v[182:185], v[26:29]
	v_mfma_f32_16x16x32_bf16 v[30:33], v[222:225], v[182:185], v[30:33]
	v_mfma_f32_16x16x32_bf16 v[34:37], v[210:213], v[186:189], v[34:37]
	ds_read_b128 v[162:165], v241 offset:0
	v_mfma_f32_16x16x32_bf16 v[38:41], v[214:217], v[186:189], v[38:41]
	ds_read_b128 v[166:169], v241 offset:256
	v_mfma_f32_16x16x32_bf16 v[42:45], v[218:221], v[186:189], v[42:45]
	ds_read_b128 v[170:173], v241 offset:2048
	v_mfma_f32_16x16x32_bf16 v[46:49], v[222:225], v[186:189], v[46:49]
	ds_read_b128 v[174:177], v241 offset:2304
	v_mfma_f32_16x16x32_bf16 v[50:53], v[210:213], v[190:193], v[50:53]
	ds_read_b128 v[130:133], v240 offset:0
	v_mfma_f32_16x16x32_bf16 v[54:57], v[214:217], v[190:193], v[54:57]
	ds_read_b128 v[134:137], v240 offset:1024
	v_mfma_f32_16x16x32_bf16 v[58:61], v[218:221], v[190:193], v[58:61]
	ds_read_b128 v[138:141], v240 offset:2048
	v_mfma_f32_16x16x32_bf16 v[62:65], v[222:225], v[190:193], v[62:65]
	ds_read_b128 v[142:145], v240 offset:3072
	v_mfma_f32_16x16x32_bf16 v[66:69], v[210:213], v[194:197], v[66:69]
	ds_read_b128 v[146:149], v240 offset:4096
	v_mfma_f32_16x16x32_bf16 v[70:73], v[214:217], v[194:197], v[70:73]
	ds_read_b128 v[150:153], v240 offset:5120
	v_mfma_f32_16x16x32_bf16 v[74:77], v[218:221], v[194:197], v[74:77]
	ds_read_b128 v[154:157], v240 offset:6144
	v_mfma_f32_16x16x32_bf16 v[78:81], v[222:225], v[194:197], v[78:81]
	ds_read_b128 v[158:161], v240 offset:7168
	s_setprio 1
	v_mfma_f32_16x16x32_bf16 v[82:85], v[210:213], v[198:201], v[82:85]
	v_mfma_f32_16x16x32_bf16 v[86:89], v[214:217], v[198:201], v[86:89]
	v_mfma_f32_16x16x32_bf16 v[90:93], v[218:221], v[198:201], v[90:93]
	v_mfma_f32_16x16x32_bf16 v[94:97], v[222:225], v[198:201], v[94:97]
	v_mfma_f32_16x16x32_bf16 v[98:101], v[210:213], v[202:205], v[98:101]
	v_mfma_f32_16x16x32_bf16 v[102:105], v[214:217], v[202:205], v[102:105]
	v_mfma_f32_16x16x32_bf16 v[106:109], v[218:221], v[202:205], v[106:109]
	v_mfma_f32_16x16x32_bf16 v[110:113], v[222:225], v[202:205], v[110:113]
	v_mfma_f32_16x16x32_bf16 v[114:117], v[210:213], v[206:209], v[114:117]
	v_mfma_f32_16x16x32_bf16 v[118:121], v[214:217], v[206:209], v[118:121]
	v_mfma_f32_16x16x32_bf16 v[122:125], v[218:221], v[206:209], v[122:125]
	v_mfma_f32_16x16x32_bf16 v[126:129], v[222:225], v[206:209], v[126:129]
	s_setprio 0
	s_add_i32 s60, s60, 0x6000
	s_cmp_eq_u32 s60, 0x12000
	s_cselect_b32 s60, 0, s60
	s_add_u32 s54, s54, s72
	s_addc_u32 s55, s55, 0
	s_add_u32 s56, s56, s73
	s_addc_u32 s57, s57, 0
	s_add_i32 s61, s61, 0x6000
	s_cmp_eq_u32 s61, 0x12000
	s_cselect_b32 s61, 0, s61

.Lpj_kloop:
	s_waitcnt vmcnt(6) lgkmcnt(0)
	s_barrier
	v_add_u32_e32 v240, s61, v238
	v_add_u32_e32 v241, s61, v239
	s_add_i32 m0, s60, s62
	v_mfma_f32_16x16x32_bf16 v[2:5], v[162:165], v[130:133], v[2:5]
	global_load_lds_dwordx4 v226, s[54:55]
	v_mfma_f32_16x16x32_bf16 v[6:9], v[166:169], v[130:133], v[6:9]
	global_load_lds_dwordx4 v226, s[54:55] offset:1024
	v_mfma_f32_16x16x32_bf16 v[10:13], v[170:173], v[130:133], v[10:13]
	global_load_lds_dwordx4 v226, s[54:55] offset:2048
	v_mfma_f32_16x16x32_bf16 v[14:17], v[174:177], v[130:133], v[14:17]
	global_load_lds_dwordx4 v226, s[54:55] offset:3072
	s_add_i32 m0, s60, s63
	v_mfma_f32_16x16x32_bf16 v[18:21], v[162:165], v[134:137], v[18:21]
	global_load_lds_dwordx4 v230, s[56:57]
	v_mfma_f32_16x16x32_bf16 v[22:25], v[166:169], v[134:137], v[22:25]
	global_load_lds_dwordx4 v231, s[56:57] offset:1024
	v_mfma_f32_16x16x32_bf16 v[26:29], v[170:173], v[134:137], v[26:29]
	v_mfma_f32_16x16x32_bf16 v[30:33], v[174:177], v[134:137], v[30:33]
	v_mfma_f32_16x16x32_bf16 v[34:37], v[162:165], v[138:141], v[34:37]
	ds_read_b128 v[210:213], v241 offset:0
	v_mfma_f32_16x16x32_bf16 v[38:41], v[166:169], v[138:141], v[38:41]
	ds_read_b128 v[214:217], v241 offset:256
	v_mfma_f32_16x16x32_bf16 v[42:45], v[170:173], v[138:141], v[42:45]
	ds_read_b128 v[218:221], v241 offset:2048
	v_mfma_f32_16x16x32_bf16 v[46:49], v[174:177], v[138:141], v[46:49]
	ds_read_b128 v[222:225], v241 offset:2304
	v_mfma_f32_16x16x32_bf16 v[50:53], v[162:165], v[142:145], v[50:53]
	ds_read_b128 v[178:181], v240 offset:0
	v_mfma_f32_16x16x32_bf16 v[54:57], v[166:169], v[142:145], v[54:57]
	ds_read_b128 v[182:185], v240 offset:1024
	v_mfma_f32_16x16x32_bf16 v[58:61], v[170:173], v[142:145], v[58:61]
	ds_read_b128 v[186:189], v240 offset:2048
	v_mfma_f32_16x16x32_bf16 v[62:65], v[174:177], v[142:145], v[62:65]
	ds_read_b128 v[190:193], v240 offset:3072
	v_mfma_f32_16x16x32_bf16 v[66:69], v[162:165], v[146:149], v[66:69]
	ds_read_b128 v[194:197], v240 offset:4096
	v_mfma_f32_16x16x32_bf16 v[70:73], v[166:169], v[146:149], v[70:73]
	ds_read_b128 v[198:201], v240 offset:5120
	v_mfma_f32_16x16x32_bf16 v[74:77], v[170:173], v[146:149], v[74:77]
	ds_read_b128 v[202:205], v240 offset:6144
	v_mfma_f32_16x16x32_bf16 v[78:81], v[174:177], v[146:149], v[78:81]
	ds_read_b128 v[206:209], v240 offset:7168
	s_setprio 1
	v_mfma_f32_16x16x32_bf16 v[82:85], v[162:165], v[150:153], v[82:85]
	v_mfma_f32_16x16x32_bf16 v[86:89], v[166:169], v[150:153], v[86:89]
	v_mfma_f32_16x16x32_bf16 v[90:93], v[170:173], v[150:153], v[90:93]
	v_mfma_f32_16x16x32_bf16 v[94:97], v[174:177], v[150:153], v[94:97]
	v_mfma_f32_16x16x32_bf16 v[98:101], v[162:165], v[154:157], v[98:101]
	v_mfma_f32_16x16x32_bf16 v[102:105], v[166:169], v[154:157], v[102:105]
	v_mfma_f32_16x16x32_bf16 v[106:109], v[170:173], v[154:157], v[106:109]
	v_mfma_f32_16x16x32_bf16 v[110:113], v[174:177], v[154:157], v[110:113]
	v_mfma_f32_16x16x32_bf16 v[114:117], v[162:165], v[158:161], v[114:117]
	v_mfma_f32_16x16x32_bf16 v[118:121], v[166:169], v[158:161], v[118:121]
	v_mfma_f32_16x16x32_bf16 v[122:125], v[170:173], v[158:161], v[122:125]
	v_mfma_f32_16x16x32_bf16 v[126:129], v[174:177], v[158:161], v[126:129]
	s_setprio 0
	s_add_i32 s60, s60, 0x6000
	s_cmp_eq_u32 s60, 0x12000
	s_cselect_b32 s60, 0, s60
	s_add_u32 s54, s54, s72
	s_addc_u32 s55, s55, 0
	s_add_u32 s56, s56, s73
	s_addc_u32 s57, s57, 0
	s_add_i32 s61, s61, 0x6000
	s_cmp_eq_u32 s61, 0x12000
	s_cselect_b32 s61, 0, s61
	s_waitcnt vmcnt(6) lgkmcnt(0)
	s_barrier
	v_add_u32_e32 v240, s61, v238
	v_add_u32_e32 v241, s61, v239
	s_add_i32 m0, s60, s62
	v_mfma_f32_16x16x32_bf16 v[2:5], v[210:213], v[178:181], v[2:5]
	global_load_lds_dwordx4 v226, s[54:55]
	v_mfma_f32_16x16x32_bf16 v[6:9], v[214:217], v[178:181], v[6:9]
	global_load_lds_dwordx4 v226, s[54:55] offset:1024
	v_mfma_f32_16x16x32_bf16 v[10:13], v[218:221], v[178:181], v[10:13]
	global_load_lds_dwordx4 v226, s[54:55] offset:2048
	v_mfma_f32_16x16x32_bf16 v[14:17], v[222:225], v[178:181], v[14:17]
	global_load_lds_dwordx4 v226, s[54:55] offset:3072
	s_add_i32 m0, s60, s63
	v_mfma_f32_16x16x32_bf16 v[18:21], v[210:213], v[182:185], v[18:21]
	global_load_lds_dwordx4 v230, s[56:57]
	v_mfma_f32_16x16x32_bf16 v[22:25], v[214:217], v[182:185], v[22:25]
	global_load_lds_dwordx4 v231, s[56:57] offset:1024
	v_mfma_f32_16x16x32_bf16 v[26:29], v[218:221], v[182:185], v[26:29]
	v_mfma_f32_16x16x32_bf16 v[30:33], v[222:225], v[182:185], v[30:33]
	v_mfma_f32_16x16x32_bf16 v[34:37], v[210:213], v[186:189], v[34:37]
	ds_read_b128 v[162:165], v241 offset:0
	v_mfma_f32_16x16x32_bf16 v[38:41], v[214:217], v[186:189], v[38:41]
	ds_read_b128 v[166:169], v241 offset:256
	v_mfma_f32_16x16x32_bf16 v[42:45], v[218:221], v[186:189], v[42:45]
	ds_read_b128 v[170:173], v241 offset:2048
	v_mfma_f32_16x16x32_bf16 v[46:49], v[222:225], v[186:189], v[46:49]
	ds_read_b128 v[174:177], v241 offset:2304
	v_mfma_f32_16x16x32_bf16 v[50:53], v[210:213], v[190:193], v[50:53]
	ds_read_b128 v[130:133], v240 offset:0
	v_mfma_f32_16x16x32_bf16 v[54:57], v[214:217], v[190:193], v[54:57]
	ds_read_b128 v[134:137], v240 offset:1024
	v_mfma_f32_16x16x32_bf16 v[58:61], v[218:221], v[190:193], v[58:61]
	ds_read_b128 v[138:141], v240 offset:2048
	v_mfma_f32_16x16x32_bf16 v[62:65], v[222:225], v[190:193], v[62:65]
	ds_read_b128 v[142:145], v240 offset:3072
	v_mfma_f32_16x16x32_bf16 v[66:69], v[210:213], v[194:197], v[66:69]
	ds_read_b128 v[146:149], v240 offset:4096
	v_mfma_f32_16x16x32_bf16 v[70:73], v[214:217], v[194:197], v[70:73]
	ds_read_b128 v[150:153], v240 offset:5120
	v_mfma_f32_16x16x32_bf16 v[74:77], v[218:221], v[194:197], v[74:77]
	ds_read_b128 v[154:157], v240 offset:6144
	v_mfma_f32_16x16x32_bf16 v[78:81], v[222:225], v[194:197], v[78:81]
	ds_read_b128 v[158:161], v240 offset:7168
	s_setprio 1
	v_mfma_f32_16x16x32_bf16 v[82:85], v[210:213], v[198:201], v[82:85]
	v_mfma_f32_16x16x32_bf16 v[86:89], v[214:217], v[198:201], v[86:89]
	v_mfma_f32_16x16x32_bf16 v[90:93], v[218:221], v[198:201], v[90:93]
	v_mfma_f32_16x16x32_bf16 v[94:97], v[222:225], v[198:201], v[94:97]
	v_mfma_f32_16x16x32_bf16 v[98:101], v[210:213], v[202:205], v[98:101]
	v_mfma_f32_16x16x32_bf16 v[102:105], v[214:217], v[202:205], v[102:105]
	v_mfma_f32_16x16x32_bf16 v[106:109], v[218:221], v[202:205], v[106:109]
	v_mfma_f32_16x16x32_bf16 v[110:113], v[222:225], v[202:205], v[110:113]
	v_mfma_f32_16x16x32_bf16 v[114:117], v[210:213], v[206:209], v[114:117]
	v_mfma_f32_16x16x32_bf16 v[118:121], v[214:217], v[206:209], v[118:121]
	v_mfma_f32_16x16x32_bf16 v[122:125], v[218:221], v[206:209], v[122:125]
	v_mfma_f32_16x16x32_bf16 v[126:129], v[222:225], v[206:209], v[126:129]
	s_setprio 0
	s_add_i32 s60, s60, 0x6000
	s_cmp_eq_u32 s60, 0x12000
	s_cselect_b32 s60, 0, s60
	s_add_u32 s54, s54, s72
	s_addc_u32 s55, s55, 0
	s_add_u32 s56, s56, s73
	s_addc_u32 s57, s57, 0
	s_add_i32 s61, s61, 0x6000
	s_cmp_eq_u32 s61, 0x12000
	s_cselect_b32 s61, 0, s61
	s_add_i32 s40, s40, -1
	s_cmp_lg_u32 s40, 0
	s_cbranch_scc1 .Lpj_kloop
	s_cmp_eq_u32 s37, 0
	s_cbranch_scc1 .Lpj_tail_last
	s_waitcnt vmcnt(6) lgkmcnt(0)
	s_barrier
	v_add_u32_e32 v240, s61, v238
	v_add_u32_e32 v241, s61, v239
	s_add_i32 m0, s60, s62
	v_mfma_f32_16x16x32_bf16 v[2:5], v[162:165], v[130:133], v[2:5]
	global_load_lds_dwordx4 v226, s[54:55]
	v_mfma_f32_16x16x32_bf16 v[6:9], v[166:169], v[130:133], v[6:9]
	global_load_lds_dwordx4 v226, s[54:55] offset:1024
	v_mfma_f32_16x16x32_bf16 v[10:13], v[170:173], v[130:133], v[10:13]
	global_load_lds_dwordx4 v226, s[54:55] offset:2048
	v_mfma_f32_16x16x32_bf16 v[14:17], v[174:177], v[130:133], v[14:17]
	global_load_lds_dwordx4 v226, s[54:55] offset:3072
	s_add_i32 m0, s60, s63
	v_mfma_f32_16x16x32_bf16 v[18:21], v[162:165], v[134:137], v[18:21]
	global_load_lds_dwordx4 v230, s[56:57]
	v_mfma_f32_16x16x32_bf16 v[22:25], v[166:169], v[134:137], v[22:25]
	global_load_lds_dwordx4 v231, s[56:57] offset:1024
	v_mfma_f32_16x16x32_bf16 v[26:29], v[170:173], v[134:137], v[26:29]
	v_mfma_f32_16x16x32_bf16 v[30:33], v[174:177], v[134:137], v[30:33]
	v_mfma_f32_16x16x32_bf16 v[34:37], v[162:165], v[138:141], v[34:37]
	ds_read_b128 v[210:213], v241 offset:0
	v_mfma_f32_16x16x32_bf16 v[38:41], v[166:169], v[138:141], v[38:41]
	ds_read_b128 v[214:217], v241 offset:256
	v_mfma_f32_16x16x32_bf16 v[42:45], v[170:173], v[138:141], v[42:45]
	ds_read_b128 v[218:221], v241 offset:2048
	v_mfma_f32_16x16x32_bf16 v[46:49], v[174:177], v[138:141], v[46:49]
	ds_read_b128 v[222:225], v241 offset:2304
	v_mfma_f32_16x16x32_bf16 v[50:53], v[162:165], v[142:145], v[50:53]
	ds_read_b128 v[178:181], v240 offset:0
	v_mfma_f32_16x16x32_bf16 v[54:57], v[166:169], v[142:145], v[54:57]
	ds_read_b128 v[182:185], v240 offset:1024
	v_mfma_f32_16x16x32_bf16 v[58:61], v[170:173], v[142:145], v[58:61]
	ds_read_b128 v[186:189], v240 offset:2048
	v_mfma_f32_16x16x32_bf16 v[62:65], v[174:177], v[142:145], v[62:65]
	ds_read_b128 v[190:193], v240 offset:3072
	v_mfma_f32_16x16x32_bf16 v[66:69], v[162:165], v[146:149], v[66:69]
	ds_read_b128 v[194:197], v240 offset:4096
	v_mfma_f32_16x16x32_bf16 v[70:73], v[166:169], v[146:149], v[70:73]
	ds_read_b128 v[198:201], v240 offset:5120
	v_mfma_f32_16x16x32_bf16 v[74:77], v[170:173], v[146:149], v[74:77]
	ds_read_b128 v[202:205], v240 offset:6144
	v_mfma_f32_16x16x32_bf16 v[78:81], v[174:177], v[146:149], v[78:81]
	ds_read_b128 v[206:209], v240 offset:7168
	s_setprio 1
	v_mfma_f32_16x16x32_bf16 v[82:85], v[162:165], v[150:153], v[82:85]
	v_mfma_f32_16x16x32_bf16 v[86:89], v[166:169], v[150:153], v[86:89]
	v_mfma_f32_16x16x32_bf16 v[90:93], v[170:173], v[150:153], v[90:93]
	v_mfma_f32_16x16x32_bf16 v[94:97], v[174:177], v[150:153], v[94:97]
	v_mfma_f32_16x16x32_bf16 v[98:101], v[162:165], v[154:157], v[98:101]
	v_mfma_f32_16x16x32_bf16 v[102:105], v[166:169], v[154:157], v[102:105]
	v_mfma_f32_16x16x32_bf16 v[106:109], v[170:173], v[154:157], v[106:109]
	v_mfma_f32_16x16x32_bf16 v[110:113], v[174:177], v[154:157], v[110:113]
	v_mfma_f32_16x16x32_bf16 v[114:117], v[162:165], v[158:161], v[114:117]
	v_mfma_f32_16x16x32_bf16 v[118:121], v[166:169], v[158:161], v[118:121]
	v_mfma_f32_16x16x32_bf16 v[122:125], v[170:173], v[158:161], v[122:125]
	v_mfma_f32_16x16x32_bf16 v[126:129], v[174:177], v[158:161], v[126:129]
	s_setprio 0
	s_add_i32 s60, s60, 0x6000
	s_cmp_eq_u32 s60, 0x12000
	s_cselect_b32 s60, 0, s60
	s_add_u32 s54, s54, s72
	s_addc_u32 s55, s55, 0
	s_add_u32 s56, s56, s73
	s_addc_u32 s57, s57, 0
	s_add_i32 s61, s61, 0x6000
	s_cmp_eq_u32 s61, 0x12000
	s_cselect_b32 s61, 0, s61
	v_mov_b32_e32 v226, v232
	v_mov_b32_e32 v230, v236
	v_mov_b32_e32 v231, v237
	s_mov_b64 s[54:55], s[48:49]
	s_mov_b64 s[56:57], s[50:51]
	s_waitcnt vmcnt(6) lgkmcnt(0)
	s_barrier
	v_add_u32_e32 v240, s61, v238
	v_add_u32_e32 v241, s61, v239
	s_add_i32 m0, s60, s62
	v_mfma_f32_16x16x32_bf16 v[2:5], v[210:213], v[178:181], v[2:5]
	global_load_lds_dwordx4 v226, s[54:55]
	v_mfma_f32_16x16x32_bf16 v[6:9], v[214:217], v[178:181], v[6:9]
	global_load_lds_dwordx4 v226, s[54:55] offset:1024
	v_mfma_f32_16x16x32_bf16 v[10:13], v[218:221], v[178:181], v[10:13]
	global_load_lds_dwordx4 v226, s[54:55] offset:2048
	v_mfma_f32_16x16x32_bf16 v[14:17], v[222:225], v[178:181], v[14:17]
	global_load_lds_dwordx4 v226, s[54:55] offset:3072
	s_add_i32 m0, s60, s63
	v_mfma_f32_16x16x32_bf16 v[18:21], v[210:213], v[182:185], v[18:21]
	global_load_lds_dwordx4 v230, s[56:57]
	v_mfma_f32_16x16x32_bf16 v[22:25], v[214:217], v[182:185], v[22:25]
	global_load_lds_dwordx4 v231, s[56:57] offset:1024
	v_mfma_f32_16x16x32_bf16 v[26:29], v[218:221], v[182:185], v[26:29]
	v_mfma_f32_16x16x32_bf16 v[30:33], v[222:225], v[182:185], v[30:33]
	v_mfma_f32_16x16x32_bf16 v[34:37], v[210:213], v[186:189], v[34:37]
	ds_read_b128 v[162:165], v241 offset:0
	v_mfma_f32_16x16x32_bf16 v[38:41], v[214:217], v[186:189], v[38:41]
	ds_read_b128 v[166:169], v241 offset:256
	v_mfma_f32_16x16x32_bf16 v[42:45], v[218:221], v[186:189], v[42:45]
	ds_read_b128 v[170:173], v241 offset:2048
	v_mfma_f32_16x16x32_bf16 v[46:49], v[222:225], v[186:189], v[46:49]
	ds_read_b128 v[174:177], v241 offset:2304
	v_mfma_f32_16x16x32_bf16 v[50:53], v[210:213], v[190:193], v[50:53]
	ds_read_b128 v[130:133], v240 offset:0
	v_mfma_f32_16x16x32_bf16 v[54:57], v[214:217], v[190:193], v[54:57]
	ds_read_b128 v[134:137], v240 offset:1024
	v_mfma_f32_16x16x32_bf16 v[58:61], v[218:221], v[190:193], v[58:61]
	ds_read_b128 v[138:141], v240 offset:2048
	v_mfma_f32_16x16x32_bf16 v[62:65], v[222:225], v[190:193], v[62:65]
	ds_read_b128 v[142:145], v240 offset:3072
	v_mfma_f32_16x16x32_bf16 v[66:69], v[210:213], v[194:197], v[66:69]
	ds_read_b128 v[146:149], v240 offset:4096
	v_mfma_f32_16x16x32_bf16 v[70:73], v[214:217], v[194:197], v[70:73]
	ds_read_b128 v[150:153], v240 offset:5120
	v_mfma_f32_16x16x32_bf16 v[74:77], v[218:221], v[194:197], v[74:77]
	ds_read_b128 v[154:157], v240 offset:6144
	v_mfma_f32_16x16x32_bf16 v[78:81], v[222:225], v[194:197], v[78:81]
	ds_read_b128 v[158:161], v240 offset:7168
	s_setprio 1
	v_mfma_f32_16x16x32_bf16 v[82:85], v[210:213], v[198:201], v[82:85]
	v_mfma_f32_16x16x32_bf16 v[86:89], v[214:217], v[198:201], v[86:89]
	v_mfma_f32_16x16x32_bf16 v[90:93], v[218:221], v[198:201], v[90:93]
	v_mfma_f32_16x16x32_bf16 v[94:97], v[222:225], v[198:201], v[94:97]
	v_mfma_f32_16x16x32_bf16 v[98:101], v[210:213], v[202:205], v[98:101]
	v_mfma_f32_16x16x32_bf16 v[102:105], v[214:217], v[202:205], v[102:105]
	v_mfma_f32_16x16x32_bf16 v[106:109], v[218:221], v[202:205], v[106:109]
	v_mfma_f32_16x16x32_bf16 v[110:113], v[222:225], v[202:205], v[110:113]
	v_mfma_f32_16x16x32_bf16 v[114:117], v[210:213], v[206:209], v[114:117]
	v_mfma_f32_16x16x32_bf16 v[118:121], v[214:217], v[206:209], v[118:121]
	v_mfma_f32_16x16x32_bf16 v[122:125], v[218:221], v[206:209], v[122:125]
	v_mfma_f32_16x16x32_bf16 v[126:129], v[222:225], v[206:209], v[126:129]
	s_setprio 0
	s_add_i32 s60, s60, 0x6000
	s_cmp_eq_u32 s60, 0x12000
	s_cselect_b32 s60, 0, s60
	s_add_u32 s54, s54, s72
	s_addc_u32 s55, s55, 0
	s_add_u32 s56, s56, s73
	s_addc_u32 s57, s57, 0
	s_add_i32 s61, s61, 0x6000
	s_cmp_eq_u32 s61, 0x12000
	s_cselect_b32 s61, 0, s61
	s_waitcnt vmcnt(6) lgkmcnt(0)
	s_barrier
	v_add_u32_e32 v240, s61, v238
	v_add_u32_e32 v241, s61, v239
	s_add_i32 m0, s60, s62
	v_mfma_f32_16x16x32_bf16 v[2:5], v[162:165], v[130:133], v[2:5]
	global_load_lds_dwordx4 v226, s[54:55]
	v_mfma_f32_16x16x32_bf16 v[6:9], v[166:169], v[130:133], v[6:9]
	global_load_lds_dwordx4 v226, s[54:55] offset:1024
	v_mfma_f32_16x16x32_bf16 v[10:13], v[170:173], v[130:133], v[10:13]
	global_load_lds_dwordx4 v226, s[54:55] offset:2048
	v_mfma_f32_16x16x32_bf16 v[14:17], v[174:177], v[130:133], v[14:17]
	global_load_lds_dwordx4 v226, s[54:55] offset:3072
	s_add_i32 m0, s60, s63
	v_mfma_f32_16x16x32_bf16 v[18:21], v[162:165], v[134:137], v[18:21]
	global_load_lds_dwordx4 v230, s[56:57]
	v_mfma_f32_16x16x32_bf16 v[22:25], v[166:169], v[134:137], v[22:25]
	global_load_lds_dwordx4 v231, s[56:57] offset:1024
	v_mfma_f32_16x16x32_bf16 v[26:29], v[170:173], v[134:137], v[26:29]
	v_mfma_f32_16x16x32_bf16 v[30:33], v[174:177], v[134:137], v[30:33]
	v_mfma_f32_16x16x32_bf16 v[34:37], v[162:165], v[138:141], v[34:37]
	ds_read_b128 v[210:213], v241 offset:0
	v_mfma_f32_16x16x32_bf16 v[38:41], v[166:169], v[138:141], v[38:41]
	ds_read_b128 v[214:217], v241 offset:256
	v_mfma_f32_16x16x32_bf16 v[42:45], v[170:173], v[138:141], v[42:45]
	ds_read_b128 v[218:221], v241 offset:2048
	v_mfma_f32_16x16x32_bf16 v[46:49], v[174:177], v[138:141], v[46:49]
	ds_read_b128 v[222:225], v241 offset:2304
	v_mfma_f32_16x16x32_bf16 v[50:53], v[162:165], v[142:145], v[50:53]
	ds_read_b128 v[178:181], v240 offset:0
	v_mfma_f32_16x16x32_bf16 v[54:57], v[166:169], v[142:145], v[54:57]
	ds_read_b128 v[182:185], v240 offset:1024
	v_mfma_f32_16x16x32_bf16 v[58:61], v[170:173], v[142:145], v[58:61]
	ds_read_b128 v[186:189], v240 offset:2048
	v_mfma_f32_16x16x32_bf16 v[62:65], v[174:177], v[142:145], v[62:65]
	ds_read_b128 v[190:193], v240 offset:3072
	v_mfma_f32_16x16x32_bf16 v[66:69], v[162:165], v[146:149], v[66:69]
	ds_read_b128 v[194:197], v240 offset:4096
	v_mfma_f32_16x16x32_bf16 v[70:73], v[166:169], v[146:149], v[70:73]
	ds_read_b128 v[198:201], v240 offset:5120
	v_mfma_f32_16x16x32_bf16 v[74:77], v[170:173], v[146:149], v[74:77]
	ds_read_b128 v[202:205], v240 offset:6144
	v_mfma_f32_16x16x32_bf16 v[78:81], v[174:177], v[146:149], v[78:81]
	ds_read_b128 v[206:209], v240 offset:7168
	s_setprio 1
	v_mfma_f32_16x16x32_bf16 v[82:85], v[162:165], v[150:153], v[82:85]
	v_mfma_f32_16x16x32_bf16 v[86:89], v[166:169], v[150:153], v[86:89]
	v_mfma_f32_16x16x32_bf16 v[90:93], v[170:173], v[150:153], v[90:93]
	v_mfma_f32_16x16x32_bf16 v[94:97], v[174:177], v[150:153], v[94:97]
	v_mfma_f32_16x16x32_bf16 v[98:101], v[162:165], v[154:157], v[98:101]
	v_mfma_f32_16x16x32_bf16 v[102:105], v[166:169], v[154:157], v[102:105]
	v_mfma_f32_16x16x32_bf16 v[106:109], v[170:173], v[154:157], v[106:109]
	v_mfma_f32_16x16x32_bf16 v[110:113], v[174:177], v[154:157], v[110:113]
	v_mfma_f32_16x16x32_bf16 v[114:117], v[162:165], v[158:161], v[114:117]
	v_mfma_f32_16x16x32_bf16 v[118:121], v[166:169], v[158:161], v[118:121]
	v_mfma_f32_16x16x32_bf16 v[122:125], v[170:173], v[158:161], v[122:125]
	v_mfma_f32_16x16x32_bf16 v[126:129], v[174:177], v[158:161], v[126:129]
	s_setprio 0
	s_add_i32 s60, s60, 0x6000
	s_cmp_eq_u32 s60, 0x12000
	s_cselect_b32 s60, 0, s60
	s_add_u32 s54, s54, s72
	s_addc_u32 s55, s55, 0
	s_add_u32 s56, s56, s73
	s_addc_u32 s57, s57, 0
	s_add_i32 s61, s61, 0x6000
	s_cmp_eq_u32 s61, 0x12000
	s_cselect_b32 s61, 0, s61
	s_waitcnt vmcnt(6) lgkmcnt(0)
	s_barrier
	v_add_u32_e32 v240, s61, v238
	v_add_u32_e32 v241, s61, v239
	s_add_i32 m0, s60, s62
	v_mfma_f32_16x16x32_bf16 v[2:5], v[210:213], v[178:181], v[2:5]
	global_load_lds_dwordx4 v226, s[54:55]
	v_mfma_f32_16x16x32_bf16 v[6:9], v[214:217], v[178:181], v[6:9]
	global_load_lds_dwordx4 v226, s[54:55] offset:1024
	v_mfma_f32_16x16x32_bf16 v[10:13], v[218:221], v[178:181], v[10:13]
	global_load_lds_dwordx4 v226, s[54:55] offset:2048
	v_mfma_f32_16x16x32_bf16 v[14:17], v[222:225], v[178:181], v[14:17]
	global_load_lds_dwordx4 v226, s[54:55] offset:3072
	s_add_i32 m0, s60, s63
	v_mfma_f32_16x16x32_bf16 v[18:21], v[210:213], v[182:185], v[18:21]
	global_load_lds_dwordx4 v230, s[56:57]
	v_mfma_f32_16x16x32_bf16 v[22:25], v[214:217], v[182:185], v[22:25]
	global_load_lds_dwordx4 v231, s[56:57] offset:1024
	v_mfma_f32_16x16x32_bf16 v[26:29], v[218:221], v[182:185], v[26:29]
	v_mfma_f32_16x16x32_bf16 v[30:33], v[222:225], v[182:185], v[30:33]
	v_mfma_f32_16x16x32_bf16 v[34:37], v[210:213], v[186:189], v[34:37]
	ds_read_b128 v[162:165], v241 offset:0
	v_mfma_f32_16x16x32_bf16 v[38:41], v[214:217], v[186:189], v[38:41]
	ds_read_b128 v[166:169], v241 offset:256
	v_mfma_f32_16x16x32_bf16 v[42:45], v[218:221], v[186:189], v[42:45]
	ds_read_b128 v[170:173], v241 offset:2048
	v_mfma_f32_16x16x32_bf16 v[46:49], v[222:225], v[186:189], v[46:49]
	ds_read_b128 v[174:177], v241 offset:2304
	v_mfma_f32_16x16x32_bf16 v[50:53], v[210:213], v[190:193], v[50:53]
	ds_read_b128 v[130:133], v240 offset:0
	v_mfma_f32_16x16x32_bf16 v[54:57], v[214:217], v[190:193], v[54:57]
	ds_read_b128 v[134:137], v240 offset:1024
	v_mfma_f32_16x16x32_bf16 v[58:61], v[218:221], v[190:193], v[58:61]
	ds_read_b128 v[138:141], v240 offset:2048
	v_mfma_f32_16x16x32_bf16 v[62:65], v[222:225], v[190:193], v[62:65]
	ds_read_b128 v[142:145], v240 offset:3072
	v_mfma_f32_16x16x32_bf16 v[66:69], v[210:213], v[194:197], v[66:69]
	ds_read_b128 v[146:149], v240 offset:4096
	v_mfma_f32_16x16x32_bf16 v[70:73], v[214:217], v[194:197], v[70:73]
	ds_read_b128 v[150:153], v240 offset:5120
	v_mfma_f32_16x16x32_bf16 v[74:77], v[218:221], v[194:197], v[74:77]
	ds_read_b128 v[154:157], v240 offset:6144
	v_mfma_f32_16x16x32_bf16 v[78:81], v[222:225], v[194:197], v[78:81]
	ds_read_b128 v[158:161], v240 offset:7168
	s_setprio 1
	v_mfma_f32_16x16x32_bf16 v[82:85], v[210:213], v[198:201], v[82:85]
	v_mfma_f32_16x16x32_bf16 v[86:89], v[214:217], v[198:201], v[86:89]
	v_mfma_f32_16x16x32_bf16 v[90:93], v[218:221], v[198:201], v[90:93]
	v_mfma_f32_16x16x32_bf16 v[94:97], v[222:225], v[198:201], v[94:97]
	v_mfma_f32_16x16x32_bf16 v[98:101], v[210:213], v[202:205], v[98:101]
	v_mfma_f32_16x16x32_bf16 v[102:105], v[214:217], v[202:205], v[102:105]
	v_mfma_f32_16x16x32_bf16 v[106:109], v[218:221], v[202:205], v[106:109]
	v_mfma_f32_16x16x32_bf16 v[110:113], v[222:225], v[202:205], v[110:113]
	v_mfma_f32_16x16x32_bf16 v[114:117], v[210:213], v[206:209], v[114:117]
	v_mfma_f32_16x16x32_bf16 v[118:121], v[214:217], v[206:209], v[118:121]
	v_mfma_f32_16x16x32_bf16 v[122:125], v[218:221], v[206:209], v[122:125]
	v_mfma_f32_16x16x32_bf16 v[126:129], v[222:225], v[206:209], v[126:129]
	s_setprio 0
	s_add_i32 s60, s60, 0x6000
	s_cmp_eq_u32 s60, 0x12000
	s_cselect_b32 s60, 0, s60
	s_add_u32 s54, s54, s72
	s_addc_u32 s55, s55, 0
	s_add_u32 s56, s56, s73
	s_addc_u32 s57, s57, 0
	s_add_i32 s61, s61, 0x6000
	s_cmp_eq_u32 s61, 0x12000
	s_cselect_b32 s61, 0, s61
	s_branch .Lpj_epi

.Lpj_tail_last:
	s_waitcnt vmcnt(6) lgkmcnt(0)
	s_barrier
	v_add_u32_e32 v240, s61, v238
	v_add_u32_e32 v241, s61, v239
	s_add_i32 m0, s60, s62
	v_mfma_f32_16x16x32_bf16 v[2:5], v[162:165], v[130:133], v[2:5]
	global_load_lds_dwordx4 v226, s[54:55]
	v_mfma_f32_16x16x32_bf16 v[6:9], v[166:169], v[130:133], v[6:9]
	global_load_lds_dwordx4 v226, s[54:55] offset:1024
	v_mfma_f32_16x16x32_bf16 v[10:13], v[170:173], v[130:133], v[10:13]
	global_load_lds_dwordx4 v226, s[54:55] offset:2048
	v_mfma_f32_16x16x32_bf16 v[14:17], v[174:177], v[130:133], v[14:17]
	global_load_lds_dwordx4 v226, s[54:55] offset:3072
	s_add_i32 m0, s60, s63
	v_mfma_f32_16x16x32_bf16 v[18:21], v[162:165], v[134:137], v[18:21]
	global_load_lds_dwordx4 v230, s[56:57]
	v_mfma_f32_16x16x32_bf16 v[22:25], v[166:169], v[134:137], v[22:25]
	global_load_lds_dwordx4 v231, s[56:57] offset:1024
	v_mfma_f32_16x16x32_bf16 v[26:29], v[170:173], v[134:137], v[26:29]
	v_mfma_f32_16x16x32_bf16 v[30:33], v[174:177], v[134:137], v[30:33]
	v_mfma_f32_16x16x32_bf16 v[34:37], v[162:165], v[138:141], v[34:37]
	ds_read_b128 v[210:213], v241 offset:0
	v_mfma_f32_16x16x32_bf16 v[38:41], v[166:169], v[138:141], v[38:41]
	ds_read_b128 v[214:217], v241 offset:256
	v_mfma_f32_16x16x32_bf16 v[42:45], v[170:173], v[138:141], v[42:45]
	ds_read_b128 v[218:221], v241 offset:2048
	v_mfma_f32_16x16x32_bf16 v[46:49], v[174:177], v[138:141], v[46:49]
	ds_read_b128 v[222:225], v241 offset:2304
	v_mfma_f32_16x16x32_bf16 v[50:53], v[162:165], v[142:145], v[50:53]
	ds_read_b128 v[178:181], v240 offset:0
	v_mfma_f32_16x16x32_bf16 v[54:57], v[166:169], v[142:145], v[54:57]
	ds_read_b128 v[182:185], v240 offset:1024
	v_mfma_f32_16x16x32_bf16 v[58:61], v[170:173], v[142:145], v[58:61]
	ds_read_b128 v[186:189], v240 offset:2048
	v_mfma_f32_16x16x32_bf16 v[62:65], v[174:177], v[142:145], v[62:65]
	ds_read_b128 v[190:193], v240 offset:3072
	v_mfma_f32_16x16x32_bf16 v[66:69], v[162:165], v[146:149], v[66:69]
	ds_read_b128 v[194:197], v240 offset:4096
	v_mfma_f32_16x16x32_bf16 v[70:73], v[166:169], v[146:149], v[70:73]
	ds_read_b128 v[198:201], v240 offset:5120
	v_mfma_f32_16x16x32_bf16 v[74:77], v[170:173], v[146:149], v[74:77]
	ds_read_b128 v[202:205], v240 offset:6144
	v_mfma_f32_16x16x32_bf16 v[78:81], v[174:177], v[146:149], v[78:81]
	ds_read_b128 v[206:209], v240 offset:7168
	s_setprio 1
	v_mfma_f32_16x16x32_bf16 v[82:85], v[162:165], v[150:153], v[82:85]
	v_mfma_f32_16x16x32_bf16 v[86:89], v[166:169], v[150:153], v[86:89]
	v_mfma_f32_16x16x32_bf16 v[90:93], v[170:173], v[150:153], v[90:93]
	v_mfma_f32_16x16x32_bf16 v[94:97], v[174:177], v[150:153], v[94:97]
	v_mfma_f32_16x16x32_bf16 v[98:101], v[162:165], v[154:157], v[98:101]
	v_mfma_f32_16x16x32_bf16 v[102:105], v[166:169], v[154:157], v[102:105]
	v_mfma_f32_16x16x32_bf16 v[106:109], v[170:173], v[154:157], v[106:109]
	v_mfma_f32_16x16x32_bf16 v[110:113], v[174:177], v[154:157], v[110:113]
	v_mfma_f32_16x16x32_bf16 v[114:117], v[162:165], v[158:161], v[114:117]
	v_mfma_f32_16x16x32_bf16 v[118:121], v[166:169], v[158:161], v[118:121]
	v_mfma_f32_16x16x32_bf16 v[122:125], v[170:173], v[158:161], v[122:125]
	v_mfma_f32_16x16x32_bf16 v[126:129], v[174:177], v[158:161], v[126:129]
	s_setprio 0
	s_add_i32 s60, s60, 0x6000
	s_cmp_eq_u32 s60, 0x12000
	s_cselect_b32 s60, 0, s60
	s_add_u32 s54, s54, s72
	s_addc_u32 s55, s55, 0
	s_add_u32 s56, s56, s73
	s_addc_u32 s57, s57, 0
	s_add_i32 s61, s61, 0x6000
	s_cmp_eq_u32 s61, 0x12000
	s_cselect_b32 s61, 0, s61
	s_waitcnt vmcnt(6) lgkmcnt(0)
	s_barrier
	v_add_u32_e32 v240, s61, v238
	v_add_u32_e32 v241, s61, v239
	v_mfma_f32_16x16x32_bf16 v[2:5], v[210:213], v[178:181], v[2:5]
	v_mfma_f32_16x16x32_bf16 v[6:9], v[214:217], v[178:181], v[6:9]
	v_mfma_f32_16x16x32_bf16 v[10:13], v[218:221], v[178:181], v[10:13]
	v_mfma_f32_16x16x32_bf16 v[14:17], v[222:225], v[178:181], v[14:17]
	v_mfma_f32_16x16x32_bf16 v[18:21], v[210:213], v[182:185], v[18:21]
	v_mfma_f32_16x16x32_bf16 v[22:25], v[214:217], v[182:185], v[22:25]
	v_mfma_f32_16x16x32_bf16 v[26:29], v[218:221], v[182:185], v[26:29]
	v_mfma_f32_16x16x32_bf16 v[30:33], v[222:225], v[182:185], v[30:33]
	v_mfma_f32_16x16x32_bf16 v[34:37], v[210:213], v[186:189], v[34:37]
	ds_read_b128 v[162:165], v241 offset:0
	v_mfma_f32_16x16x32_bf16 v[38:41], v[214:217], v[186:189], v[38:41]
	ds_read_b128 v[166:169], v241 offset:256
	v_mfma_f32_16x16x32_bf16 v[42:45], v[218:221], v[186:189], v[42:45]
	ds_read_b128 v[170:173], v241 offset:2048
	v_mfma_f32_16x16x32_bf16 v[46:49], v[222:225], v[186:189], v[46:49]
	ds_read_b128 v[174:177], v241 offset:2304
	v_mfma_f32_16x16x32_bf16 v[50:53], v[210:213], v[190:193], v[50:53]
	ds_read_b128 v[130:133], v240 offset:0
	v_mfma_f32_16x16x32_bf16 v[54:57], v[214:217], v[190:193], v[54:57]
	ds_read_b128 v[134:137], v240 offset:1024
	v_mfma_f32_16x16x32_bf16 v[58:61], v[218:221], v[190:193], v[58:61]
	ds_read_b128 v[138:141], v240 offset:2048
	v_mfma_f32_16x16x32_bf16 v[62:65], v[222:225], v[190:193], v[62:65]
	ds_read_b128 v[142:145], v240 offset:3072
	v_mfma_f32_16x16x32_bf16 v[66:69], v[210:213], v[194:197], v[66:69]
	ds_read_b128 v[146:149], v240 offset:4096
	v_mfma_f32_16x16x32_bf16 v[70:73], v[214:217], v[194:197], v[70:73]
	ds_read_b128 v[150:153], v240 offset:5120
	v_mfma_f32_16x16x32_bf16 v[74:77], v[218:221], v[194:197], v[74:77]
	ds_read_b128 v[154:157], v240 offset:6144
	v_mfma_f32_16x16x32_bf16 v[78:81], v[222:225], v[194:197], v[78:81]
	ds_read_b128 v[158:161], v240 offset:7168
	s_setprio 1
	v_mfma_f32_16x16x32_bf16 v[82:85], v[210:213], v[198:201], v[82:85]
	v_mfma_f32_16x16x32_bf16 v[86:89], v[214:217], v[198:201], v[86:89]
	v_mfma_f32_16x16x32_bf16 v[90:93], v[218:221], v[198:201], v[90:93]
	v_mfma_f32_16x16x32_bf16 v[94:97], v[222:225], v[198:201], v[94:97]
	v_mfma_f32_16x16x32_bf16 v[98:101], v[210:213], v[202:205], v[98:101]
	v_mfma_f32_16x16x32_bf16 v[102:105], v[214:217], v[202:205], v[102:105]
	v_mfma_f32_16x16x32_bf16 v[106:109], v[218:221], v[202:205], v[106:109]
	v_mfma_f32_16x16x32_bf16 v[110:113], v[222:225], v[202:205], v[110:113]
	v_mfma_f32_16x16x32_bf16 v[114:117], v[210:213], v[206:209], v[114:117]
	v_mfma_f32_16x16x32_bf16 v[118:121], v[214:217], v[206:209], v[118:121]
	v_mfma_f32_16x16x32_bf16 v[122:125], v[218:221], v[206:209], v[122:125]
	v_mfma_f32_16x16x32_bf16 v[126:129], v[222:225], v[206:209], v[126:129]
	s_setprio 0
	s_add_i32 s61, s61, 0x6000
	s_cmp_eq_u32 s61, 0x12000
	s_cselect_b32 s61, 0, s61
	s_waitcnt vmcnt(0) lgkmcnt(0)
	s_barrier
	v_add_u32_e32 v240, s61, v238
	v_add_u32_e32 v241, s61, v239
	v_mfma_f32_16x16x32_bf16 v[2:5], v[162:165], v[130:133], v[2:5]
	v_mfma_f32_16x16x32_bf16 v[6:9], v[166:169], v[130:133], v[6:9]
	v_mfma_f32_16x16x32_bf16 v[10:13], v[170:173], v[130:133], v[10:13]
	v_mfma_f32_16x16x32_bf16 v[14:17], v[174:177], v[130:133], v[14:17]
	v_mfma_f32_16x16x32_bf16 v[18:21], v[162:165], v[134:137], v[18:21]
	v_mfma_f32_16x16x32_bf16 v[22:25], v[166:169], v[134:137], v[22:25]
	v_mfma_f32_16x16x32_bf16 v[26:29], v[170:173], v[134:137], v[26:29]
	v_mfma_f32_16x16x32_bf16 v[30:33], v[174:177], v[134:137], v[30:33]
	v_mfma_f32_16x16x32_bf16 v[34:37], v[162:165], v[138:141], v[34:37]
	ds_read_b128 v[210:213], v241 offset:0
	v_mfma_f32_16x16x32_bf16 v[38:41], v[166:169], v[138:141], v[38:41]
	ds_read_b128 v[214:217], v241 offset:256
	v_mfma_f32_16x16x32_bf16 v[42:45], v[170:173], v[138:141], v[42:45]
	ds_read_b128 v[218:221], v241 offset:2048
	v_mfma_f32_16x16x32_bf16 v[46:49], v[174:177], v[138:141], v[46:49]
	ds_read_b128 v[222:225], v241 offset:2304
	v_mfma_f32_16x16x32_bf16 v[50:53], v[162:165], v[142:145], v[50:53]
	ds_read_b128 v[178:181], v240 offset:0
	v_mfma_f32_16x16x32_bf16 v[54:57], v[166:169], v[142:145], v[54:57]
	ds_read_b128 v[182:185], v240 offset:1024
	v_mfma_f32_16x16x32_bf16 v[58:61], v[170:173], v[142:145], v[58:61]
	ds_read_b128 v[186:189], v240 offset:2048
	v_mfma_f32_16x16x32_bf16 v[62:65], v[174:177], v[142:145], v[62:65]
	ds_read_b128 v[190:193], v240 offset:3072
	v_mfma_f32_16x16x32_bf16 v[66:69], v[162:165], v[146:149], v[66:69]
	ds_read_b128 v[194:197], v240 offset:4096
	v_mfma_f32_16x16x32_bf16 v[70:73], v[166:169], v[146:149], v[70:73]
	ds_read_b128 v[198:201], v240 offset:5120
	v_mfma_f32_16x16x32_bf16 v[74:77], v[170:173], v[146:149], v[74:77]
	ds_read_b128 v[202:205], v240 offset:6144
	v_mfma_f32_16x16x32_bf16 v[78:81], v[174:177], v[146:149], v[78:81]
	ds_read_b128 v[206:209], v240 offset:7168
	s_setprio 1
	v_mfma_f32_16x16x32_bf16 v[82:85], v[162:165], v[150:153], v[82:85]
	v_mfma_f32_16x16x32_bf16 v[86:89], v[166:169], v[150:153], v[86:89]
	v_mfma_f32_16x16x32_bf16 v[90:93], v[170:173], v[150:153], v[90:93]
	v_mfma_f32_16x16x32_bf16 v[94:97], v[174:177], v[150:153], v[94:97]
	v_mfma_f32_16x16x32_bf16 v[98:101], v[162:165], v[154:157], v[98:101]
	v_mfma_f32_16x16x32_bf16 v[102:105], v[166:169], v[154:157], v[102:105]
	v_mfma_f32_16x16x32_bf16 v[106:109], v[170:173], v[154:157], v[106:109]
	v_mfma_f32_16x16x32_bf16 v[110:113], v[174:177], v[154:157], v[110:113]
	v_mfma_f32_16x16x32_bf16 v[114:117], v[162:165], v[158:161], v[114:117]
	v_mfma_f32_16x16x32_bf16 v[118:121], v[166:169], v[158:161], v[118:121]
	v_mfma_f32_16x16x32_bf16 v[122:125], v[170:173], v[158:161], v[122:125]
	v_mfma_f32_16x16x32_bf16 v[126:129], v[174:177], v[158:161], v[126:129]
	s_setprio 0
	s_add_i32 s61, s61, 0x6000
	s_cmp_eq_u32 s61, 0x12000
	s_cselect_b32 s61, 0, s61
	s_waitcnt lgkmcnt(0)
	s_barrier
	v_mfma_f32_16x16x32_bf16 v[2:5], v[210:213], v[178:181], v[2:5]
	v_mfma_f32_16x16x32_bf16 v[6:9], v[214:217], v[178:181], v[6:9]
	v_mfma_f32_16x16x32_bf16 v[10:13], v[218:221], v[178:181], v[10:13]
	v_mfma_f32_16x16x32_bf16 v[14:17], v[222:225], v[178:181], v[14:17]
	v_mfma_f32_16x16x32_bf16 v[18:21], v[210:213], v[182:185], v[18:21]
	v_mfma_f32_16x16x32_bf16 v[22:25], v[214:217], v[182:185], v[22:25]
	v_mfma_f32_16x16x32_bf16 v[26:29], v[218:221], v[182:185], v[26:29]
	v_mfma_f32_16x16x32_bf16 v[30:33], v[222:225], v[182:185], v[30:33]
	v_mfma_f32_16x16x32_bf16 v[34:37], v[210:213], v[186:189], v[34:37]
	v_mfma_f32_16x16x32_bf16 v[38:41], v[214:217], v[186:189], v[38:41]
	v_mfma_f32_16x16x32_bf16 v[42:45], v[218:221], v[186:189], v[42:45]
	v_mfma_f32_16x16x32_bf16 v[46:49], v[222:225], v[186:189], v[46:49]
	v_mfma_f32_16x16x32_bf16 v[50:53], v[210:213], v[190:193], v[50:53]
	v_mfma_f32_16x16x32_bf16 v[54:57], v[214:217], v[190:193], v[54:57]
	v_mfma_f32_16x16x32_bf16 v[58:61], v[218:221], v[190:193], v[58:61]
	v_mfma_f32_16x16x32_bf16 v[62:65], v[222:225], v[190:193], v[62:65]
	v_mfma_f32_16x16x32_bf16 v[66:69], v[210:213], v[194:197], v[66:69]
	v_mfma_f32_16x16x32_bf16 v[70:73], v[214:217], v[194:197], v[70:73]
	v_mfma_f32_16x16x32_bf16 v[74:77], v[218:221], v[194:197], v[74:77]
	v_mfma_f32_16x16x32_bf16 v[78:81], v[222:225], v[194:197], v[78:81]
	s_setprio 1
	v_mfma_f32_16x16x32_bf16 v[82:85], v[210:213], v[198:201], v[82:85]
	v_mfma_f32_16x16x32_bf16 v[86:89], v[214:217], v[198:201], v[86:89]
	v_mfma_f32_16x16x32_bf16 v[90:93], v[218:221], v[198:201], v[90:93]
	v_mfma_f32_16x16x32_bf16 v[94:97], v[222:225], v[198:201], v[94:97]
	v_mfma_f32_16x16x32_bf16 v[98:101], v[210:213], v[202:205], v[98:101]
	v_mfma_f32_16x16x32_bf16 v[102:105], v[214:217], v[202:205], v[102:105]
	v_mfma_f32_16x16x32_bf16 v[106:109], v[218:221], v[202:205], v[106:109]
	v_mfma_f32_16x16x32_bf16 v[110:113], v[222:225], v[202:205], v[110:113]
	v_mfma_f32_16x16x32_bf16 v[114:117], v[210:213], v[206:209], v[114:117]
	v_mfma_f32_16x16x32_bf16 v[118:121], v[214:217], v[206:209], v[118:121]
	v_mfma_f32_16x16x32_bf16 v[122:125], v[218:221], v[206:209], v[122:125]
	v_mfma_f32_16x16x32_bf16 v[126:129], v[222:225], v[206:209], v[126:129]
	s_setprio 0
